# on top of v27: in every GEMM load interval all ds_reads are issued first and the DMA-address SALU follows them
# speedup vs baseline: 1.0063x; 1.0063x over previous
; #define PG8_STAGE(bufoff, gbase) do { _Pragma("unroll") for (int _i = 0; _i < 2; ++_i) \
;         __builtin_amdgcn_global_load_lds((const unsigned*)((const char*)(gbase) + voff[_i]), (LAS unsigned*)(lds + (bufoff) + ldsw + _i * 8192), 16, 0, 0); } while (0)
; #define PG8_LDA(dst, b, h) do { _Pragma("unroll") for (int m = 0; m < 4; ++m) _Pragma("unroll") for (int k = 0; k < 2; ++k) dst[m][k] = *(const LAS bf16x8*)(lds + PG8_SA(b, h) + aoff + m * 2048 + k * 1024); } while (0)
; #define PG8_LDB(dst, b, h) do { _Pragma("unroll") for (int n = 0; n < 2; ++n) _Pragma("unroll") for (int k = 0; k < 2; ++k) dst[n][k] = *(const LAS bf16x8*)(lds + PG8_SB(b, h) + boff + n * 2048 + k * 1024); } while (0)
; #define PG8_MMA(ai, bj, At, Bt) do { __builtin_amdgcn_s_setprio(1); _Pragma("unroll") for (int m = 0; m < 4; ++m) _Pragma("unroll") for (int n = 0; n < 2; ++n) _Pragma("unroll") for (int k = 0; k < 2; ++k) \
;         acc[ai][bj][m][n] = __builtin_amdgcn_mfma_f32_16x16x32_bf16(Bt[n][k], At[m][k], acc[ai][bj][m][n], 0, 0, 0); __builtin_amdgcn_s_setprio(0); } while (0)
; #define PG8_WAIT_V(n) asm volatile("s_waitcnt vmcnt(" #n ")" ::: "memory")
; #define PG8_WAIT_L(n) asm volatile("s_waitcnt lgkmcnt(" #n ")" ::: "memory")
; #define PG8_BAR __builtin_amdgcn_s_barrier()
; #define PG8_SCHED __builtin_amdgcn_sched_barrier(0)
; template <class Epi>
; DI void gemm_phase(LAS unsigned char* lds, const Gemm g, const StaticOrder& S, const Epi& E) {
;     ...
;         for (int t = 0; t < nt; t += 2) {
;             const bool last = (t == nt - 2);
;             const char* a1 = cA + (size_t)(t + 1) * kstep;
;             const char* a2 = last ? nA : cA + (size_t)(t + 2) * kstep; const char* b2 = last ? nB : cB + (size_t)(t + 2) * kstep;
;             const char* a3 = a2 + kstep; const char* b3 = b2 + kstep;
;             PG8_LDB(B0, 0, 0); PG8_SCHED; PG8_LDA(At, 0, 0); PG8_STAGE(PG8_SA(1, 1), a1 + hstep);
;             PG8_WAIT_L(8); PG8_BAR; PG8_WAIT_L(0); PG8_MMA(0, 0, At, B0); PG8_BAR; PG8_SCHED;
;             PG8_LDB(B1, 0, 1); PG8_STAGE(PG8_SB(0, 0), b2);
;             PG8_BAR; PG8_WAIT_L(0); PG8_MMA(0, 1, At, B1); PG8_BAR;
;             PG8_LDA(At, 0, 1); PG8_STAGE(PG8_SA(0, 0), a2);
;             PG8_BAR; PG8_WAIT_L(0); PG8_MMA(1, 0, At, B0); PG8_BAR; PG8_SCHED;
;             PG8_STAGE(PG8_SB(0, 1), b2 + hstep);
;             PG8_WAIT_V(6); PG8_BAR; PG8_MMA(1, 1, At, B1); PG8_BAR;
.LBB0_37:
	ds_read_b128 v[138:141], v135
	ds_read_b128 v[142:145], v135 offset:1024
	ds_read_b128 v[146:149], v135 offset:2048
	ds_read_b128 v[150:153], v135 offset:3072
	ds_read_b128 v[186:189], v137
	ds_read_b128 v[190:193], v137 offset:1024
	ds_read_b128 v[194:197], v137 offset:2048
	ds_read_b128 v[198:201], v137 offset:3072
	ds_read_b128 v[202:205], v137 offset:4096
	ds_read_b128 v[206:209], v137 offset:5120
	ds_read_b128 v[210:213], v137 offset:6144
	ds_read_b128 v[214:217], v137 offset:7168
	s_add_u32 s20, s18, 0xfff80080
	s_addc_u32 s21, s19, -1
	s_add_i32 s39, 0, 0x10000
	s_cmp_eq_u32 s38, 28
	s_cselect_b32 s23, s4, s21
	s_cselect_b32 s22, s5, s20
	s_cselect_b32 s21, s9, s37
	s_cselect_b32 s20, s11, s33
	s_add_i32 m0, s28, 0xc000
	s_nop 0
	global_load_lds_dwordx4 v130, s[18:19]
	s_add_i32 m0, s28, 0xe000
	s_nop 0
	global_load_lds_dwordx4 v132, s[18:19]
	s_waitcnt lgkmcnt(8)
	s_setprio 1
	s_barrier
	s_waitcnt lgkmcnt(0)
	v_mfma_f32_16x16x32_bf16 v[124:127], v[138:141], v[186:189], v[124:127]
	v_mfma_f32_16x16x32_bf16 v[120:123], v[146:149], v[186:189], v[120:123]
	v_mfma_f32_16x16x32_bf16 v[108:111], v[138:141], v[194:197], v[108:111]
	v_mfma_f32_16x16x32_bf16 v[104:107], v[146:149], v[194:197], v[104:107]
	v_mfma_f32_16x16x32_bf16 v[92:95], v[138:141], v[202:205], v[92:95]
	v_mfma_f32_16x16x32_bf16 v[88:91], v[146:149], v[202:205], v[88:91]
	v_mfma_f32_16x16x32_bf16 v[76:79], v[138:141], v[210:213], v[76:79]
	v_mfma_f32_16x16x32_bf16 v[72:75], v[146:149], v[210:213], v[72:75]
	v_mfma_f32_16x16x32_bf16 v[124:127], v[142:145], v[190:193], v[124:127]
	v_mfma_f32_16x16x32_bf16 v[120:123], v[150:153], v[190:193], v[120:123]
	v_mfma_f32_16x16x32_bf16 v[108:111], v[142:145], v[198:201], v[108:111]
	v_mfma_f32_16x16x32_bf16 v[104:107], v[150:153], v[198:201], v[104:107]
	v_mfma_f32_16x16x32_bf16 v[92:95], v[142:145], v[206:209], v[92:95]
	v_mfma_f32_16x16x32_bf16 v[88:91], v[150:153], v[206:209], v[88:91]
	v_mfma_f32_16x16x32_bf16 v[76:79], v[142:145], v[214:217], v[76:79]
	s_setprio 0
	v_mfma_f32_16x16x32_bf16 v[72:75], v[150:153], v[214:217], v[72:75]
	s_barrier
	ds_read_b128 v[226:229], v135 offset:16384
	ds_read_b128 v[230:233], v135 offset:17408
	ds_read_b128 v[234:237], v135 offset:18432
	ds_read_b128 v[238:241], v135 offset:19456
	s_add_i32 s42, 0, 0x14000
	s_add_i32 s39, s39, s27
	s_mov_b32 m0, s39
	s_nop 0
	global_load_lds_dwordx4 v158, s[20:21]
	s_add_i32 m0, s39, 0x2000
	s_nop 0
	global_load_lds_dwordx4 v128, s[20:21]
	s_waitcnt lgkmcnt(0)
	s_setprio 1
	s_barrier
	v_mfma_f32_16x16x32_bf16 v[116:119], v[226:229], v[186:189], v[116:119]
	v_mfma_f32_16x16x32_bf16 v[112:115], v[234:237], v[186:189], v[112:115]
	v_mfma_f32_16x16x32_bf16 v[100:103], v[226:229], v[194:197], v[100:103]
	v_mfma_f32_16x16x32_bf16 v[96:99], v[234:237], v[194:197], v[96:99]
	v_mfma_f32_16x16x32_bf16 v[84:87], v[226:229], v[202:205], v[84:87]
	v_mfma_f32_16x16x32_bf16 v[80:83], v[234:237], v[202:205], v[80:83]
	v_mfma_f32_16x16x32_bf16 v[68:71], v[226:229], v[210:213], v[68:71]
	v_mfma_f32_16x16x32_bf16 v[64:67], v[234:237], v[210:213], v[64:67]
	v_mfma_f32_16x16x32_bf16 v[116:119], v[230:233], v[190:193], v[116:119]
	s_mov_b32 m0, s28
	v_mfma_f32_16x16x32_bf16 v[112:115], v[238:241], v[190:193], v[112:115]
	s_mov_b64 s[100:101], s[22:23]
	v_mfma_f32_16x16x32_bf16 v[100:103], v[230:233], v[198:201], v[100:103]
	v_mfma_f32_16x16x32_bf16 v[96:99], v[238:241], v[198:201], v[96:99]
	v_mfma_f32_16x16x32_bf16 v[84:87], v[230:233], v[206:209], v[84:87]
	v_mfma_f32_16x16x32_bf16 v[80:83], v[238:241], v[206:209], v[80:83]
	v_mfma_f32_16x16x32_bf16 v[68:71], v[230:233], v[214:217], v[68:71]
	s_setprio 0
	v_mfma_f32_16x16x32_bf16 v[64:67], v[238:241], v[214:217], v[64:67]
	s_barrier
	ds_read_b128 v[186:189], v137 offset:16384
	ds_read_b128 v[190:193], v137 offset:17408
	ds_read_b128 v[194:197], v137 offset:18432
	ds_read_b128 v[198:201], v137 offset:19456
	ds_read_b128 v[202:205], v137 offset:20480
	ds_read_b128 v[206:209], v137 offset:21504
	ds_read_b128 v[210:213], v137 offset:22528
	ds_read_b128 v[214:217], v137 offset:23552
	global_load_lds_dwordx4 v158, s[22:23]
	s_mov_b64 s[100:101], s[22:23]
	s_mov_b32 m0, s29
	s_nop 0
	global_load_lds_dwordx4 v128, s[22:23]
	s_waitcnt lgkmcnt(0)
	s_setprio 1
	s_barrier
	v_mfma_f32_16x16x32_bf16 v[60:63], v[138:141], v[186:189], v[60:63]
	v_mfma_f32_16x16x32_bf16 v[56:59], v[146:149], v[186:189], v[56:59]
	v_mfma_f32_16x16x32_bf16 v[44:47], v[138:141], v[194:197], v[44:47]
	v_mfma_f32_16x16x32_bf16 v[40:43], v[146:149], v[194:197], v[40:43]
	v_mfma_f32_16x16x32_bf16 v[28:31], v[138:141], v[202:205], v[28:31]
	v_mfma_f32_16x16x32_bf16 v[24:27], v[146:149], v[202:205], v[24:27]
	v_mfma_f32_16x16x32_bf16 v[12:15], v[138:141], v[210:213], v[12:15]
	v_mfma_f32_16x16x32_bf16 v[8:11], v[146:149], v[210:213], v[8:11]
	v_mfma_f32_16x16x32_bf16 v[60:63], v[142:145], v[190:193], v[60:63]
	v_mfma_f32_16x16x32_bf16 v[56:59], v[150:153], v[190:193], v[56:59]
	v_mfma_f32_16x16x32_bf16 v[44:47], v[142:145], v[198:201], v[44:47]
	v_mfma_f32_16x16x32_bf16 v[40:43], v[150:153], v[198:201], v[40:43]
	v_mfma_f32_16x16x32_bf16 v[28:31], v[142:145], v[206:209], v[28:31]
	v_mfma_f32_16x16x32_bf16 v[24:27], v[150:153], v[206:209], v[24:27]
	v_mfma_f32_16x16x32_bf16 v[12:15], v[142:145], v[214:217], v[12:15]
	s_setprio 0
	v_mfma_f32_16x16x32_bf16 v[8:11], v[150:153], v[214:217], v[8:11]
	s_barrier
	s_add_u32 s40, s20, 0x80000
	s_addc_u32 s41, s21, 0
	s_add_i32 s39, s42, s27
	s_mov_b32 m0, s39
	s_nop 0
	global_load_lds_dwordx4 v158, s[40:41]
	s_add_i32 m0, s39, 0x2000
	s_nop 0
	global_load_lds_dwordx4 v128, s[40:41]
	s_waitcnt vmcnt(6)
	s_setprio 1
	s_barrier
; #define PG8_STAGE(bufoff, gbase) do { _Pragma("unroll") for (int _i = 0; _i < 2; ++_i) \
;         __builtin_amdgcn_global_load_lds((const unsigned*)((const char*)(gbase) + voff[_i]), (LAS unsigned*)(lds + (bufoff) + ldsw + _i * 8192), 16, 0, 0); } while (0)
; #define PG8_LDA(dst, b, h) do { _Pragma("unroll") for (int m = 0; m < 4; ++m) _Pragma("unroll") for (int k = 0; k < 2; ++k) dst[m][k] = *(const LAS bf16x8*)(lds + PG8_SA(b, h) + aoff + m * 2048 + k * 1024); } while (0)
; #define PG8_LDB(dst, b, h) do { _Pragma("unroll") for (int n = 0; n < 2; ++n) _Pragma("unroll") for (int k = 0; k < 2; ++k) dst[n][k] = *(const LAS bf16x8*)(lds + PG8_SB(b, h) + boff + n * 2048 + k * 1024); } while (0)
; #define PG8_MMA(ai, bj, At, Bt) do { __builtin_amdgcn_s_setprio(1); _Pragma("unroll") for (int m = 0; m < 4; ++m) _Pragma("unroll") for (int n = 0; n < 2; ++n) _Pragma("unroll") for (int k = 0; k < 2; ++k) \
;         acc[ai][bj][m][n] = __builtin_amdgcn_mfma_f32_16x16x32_bf16(Bt[n][k], At[m][k], acc[ai][bj][m][n], 0, 0, 0); __builtin_amdgcn_s_setprio(0); } while (0)
; #define PG8_WAIT_V(n) asm volatile("s_waitcnt vmcnt(" #n ")" ::: "memory")
; #define PG8_WAIT_L(n) asm volatile("s_waitcnt lgkmcnt(" #n ")" ::: "memory")
; #define PG8_BAR __builtin_amdgcn_s_barrier()
; #define PG8_SCHED __builtin_amdgcn_sched_barrier(0)
; template <class Epi>
; DI void gemm_phase(LAS unsigned char* lds, const Gemm g, const StaticOrder& S, const Epi& E) {
;     ...
;             PG8_WAIT_V(6); PG8_BAR; PG8_MMA(1, 1, At, B1); PG8_BAR;
;             PG8_LDB(B0, 1, 0); PG8_SCHED; PG8_LDA(At, 1, 0); PG8_STAGE(PG8_SA(0, 1), a2 + hstep);
;             PG8_WAIT_L(8); PG8_BAR; PG8_WAIT_L(0); PG8_MMA(0, 0, At, B0); PG8_BAR; PG8_SCHED;
;             PG8_LDB(B1, 1, 1); PG8_STAGE(PG8_SB(1, 0), b3);
;             PG8_BAR; PG8_WAIT_L(0); PG8_MMA(0, 1, At, B1); PG8_BAR;
;             PG8_LDA(At, 1, 1); PG8_STAGE(PG8_SA(1, 0), a3);
;             PG8_BAR; PG8_WAIT_L(0); PG8_MMA(1, 0, At, B0); PG8_BAR; PG8_SCHED;
	v_mfma_f32_16x16x32_bf16 v[52:55], v[226:229], v[186:189], v[52:55]
	v_mfma_f32_16x16x32_bf16 v[48:51], v[234:237], v[186:189], v[48:51]
	v_mfma_f32_16x16x32_bf16 v[36:39], v[226:229], v[194:197], v[36:39]
	v_mfma_f32_16x16x32_bf16 v[32:35], v[234:237], v[194:197], v[32:35]
	v_mfma_f32_16x16x32_bf16 v[20:23], v[226:229], v[202:205], v[20:23]
	v_mfma_f32_16x16x32_bf16 v[16:19], v[234:237], v[202:205], v[16:19]
	v_mfma_f32_16x16x32_bf16 v[4:7], v[226:229], v[210:213], v[4:7]
	v_mfma_f32_16x16x32_bf16 v[0:3], v[234:237], v[210:213], v[0:3]
	v_mfma_f32_16x16x32_bf16 v[52:55], v[230:233], v[190:193], v[52:55]
	s_add_i32 s39, 0, 0x18000
	v_mfma_f32_16x16x32_bf16 v[48:51], v[238:241], v[190:193], v[48:51]
	v_mfma_f32_16x16x32_bf16 v[36:39], v[230:233], v[198:201], v[36:39]
	v_mfma_f32_16x16x32_bf16 v[32:35], v[238:241], v[198:201], v[32:35]
	v_mfma_f32_16x16x32_bf16 v[20:23], v[230:233], v[206:209], v[20:23]
	v_mfma_f32_16x16x32_bf16 v[16:19], v[238:241], v[206:209], v[16:19]
	v_mfma_f32_16x16x32_bf16 v[4:7], v[230:233], v[214:217], v[4:7]
	s_setprio 0
	v_mfma_f32_16x16x32_bf16 v[0:3], v[238:241], v[214:217], v[0:3]
	s_barrier
	ds_read_b128 v[138:141], v135 offset:32768
	ds_read_b128 v[142:145], v135 offset:33792
	ds_read_b128 v[146:149], v135 offset:34816
	ds_read_b128 v[150:153], v135 offset:35840
	ds_read_b128 v[186:189], v137 offset:32768
	ds_read_b128 v[190:193], v137 offset:33792
	ds_read_b128 v[194:197], v137 offset:34816
	ds_read_b128 v[198:201], v137 offset:35840
	ds_read_b128 v[202:205], v137 offset:36864
	ds_read_b128 v[206:209], v137 offset:37888
	ds_read_b128 v[210:213], v137 offset:38912
	ds_read_b128 v[214:217], v137 offset:39936
	s_add_u32 s22, s22, 0x80000
	s_addc_u32 s23, s23, 0
	s_mov_b32 m0, s30
	s_nop 0
	global_load_lds_dwordx4 v158, s[22:23]
	s_mov_b32 m0, s31
	s_nop 0
	global_load_lds_dwordx4 v128, s[22:23]
	s_waitcnt lgkmcnt(8)
	s_setprio 1
	s_barrier
	s_waitcnt lgkmcnt(0)
	v_mfma_f32_16x16x32_bf16 v[124:127], v[138:141], v[186:189], v[124:127]
	v_mfma_f32_16x16x32_bf16 v[120:123], v[146:149], v[186:189], v[120:123]
	v_mfma_f32_16x16x32_bf16 v[108:111], v[138:141], v[194:197], v[108:111]
	v_mfma_f32_16x16x32_bf16 v[104:107], v[146:149], v[194:197], v[104:107]
	v_mfma_f32_16x16x32_bf16 v[92:95], v[138:141], v[202:205], v[92:95]
	v_mfma_f32_16x16x32_bf16 v[88:91], v[146:149], v[202:205], v[88:91]
	v_mfma_f32_16x16x32_bf16 v[76:79], v[138:141], v[210:213], v[76:79]
	v_mfma_f32_16x16x32_bf16 v[72:75], v[146:149], v[210:213], v[72:75]
	v_mfma_f32_16x16x32_bf16 v[124:127], v[142:145], v[190:193], v[124:127]
	v_mfma_f32_16x16x32_bf16 v[120:123], v[150:153], v[190:193], v[120:123]
	v_mfma_f32_16x16x32_bf16 v[108:111], v[142:145], v[198:201], v[108:111]
	v_mfma_f32_16x16x32_bf16 v[104:107], v[150:153], v[198:201], v[104:107]
	v_mfma_f32_16x16x32_bf16 v[92:95], v[142:145], v[206:209], v[92:95]
	v_mfma_f32_16x16x32_bf16 v[88:91], v[150:153], v[206:209], v[88:91]
	v_mfma_f32_16x16x32_bf16 v[76:79], v[142:145], v[214:217], v[76:79]
	s_setprio 0
	v_mfma_f32_16x16x32_bf16 v[72:75], v[150:153], v[214:217], v[72:75]
	s_barrier
	ds_read_b128 v[226:229], v135 offset:49152
	ds_read_b128 v[230:233], v135 offset:50176
	ds_read_b128 v[234:237], v135 offset:51200
	ds_read_b128 v[238:241], v135 offset:52224
	s_add_i32 s22, 0, 0x1c000
	s_add_i32 s23, s39, s27
	s_add_i32 m0, s23, 0xffffff80
	s_nop 0
	global_load_lds_dwordx4 v158, s[20:21] offset:128
	s_add_i32 m0, s23, 0x1f80
	s_nop 0
	global_load_lds_dwordx4 v128, s[20:21] offset:128
	s_waitcnt lgkmcnt(0)
	s_setprio 1
	s_barrier
	v_mfma_f32_16x16x32_bf16 v[116:119], v[226:229], v[186:189], v[116:119]
	v_mfma_f32_16x16x32_bf16 v[112:115], v[234:237], v[186:189], v[112:115]
	v_mfma_f32_16x16x32_bf16 v[100:103], v[226:229], v[194:197], v[100:103]
	v_mfma_f32_16x16x32_bf16 v[96:99], v[234:237], v[194:197], v[96:99]
	v_mfma_f32_16x16x32_bf16 v[84:87], v[226:229], v[202:205], v[84:87]
	v_mfma_f32_16x16x32_bf16 v[80:83], v[234:237], v[202:205], v[80:83]
	v_mfma_f32_16x16x32_bf16 v[68:71], v[226:229], v[210:213], v[68:71]
	v_mfma_f32_16x16x32_bf16 v[64:67], v[234:237], v[210:213], v[64:67]
	v_mfma_f32_16x16x32_bf16 v[116:119], v[230:233], v[190:193], v[116:119]
	s_add_i32 m0, s34, 0xffffff80
	v_mfma_f32_16x16x32_bf16 v[112:115], v[238:241], v[190:193], v[112:115]
	v_mfma_f32_16x16x32_bf16 v[100:103], v[230:233], v[198:201], v[100:103]
	v_mfma_f32_16x16x32_bf16 v[96:99], v[238:241], v[198:201], v[96:99]
	v_mfma_f32_16x16x32_bf16 v[84:87], v[230:233], v[206:209], v[84:87]
	v_mfma_f32_16x16x32_bf16 v[80:83], v[238:241], v[206:209], v[80:83]
	v_mfma_f32_16x16x32_bf16 v[68:71], v[230:233], v[214:217], v[68:71]
	s_setprio 0
	v_mfma_f32_16x16x32_bf16 v[64:67], v[238:241], v[214:217], v[64:67]
	s_barrier
	ds_read_b128 v[186:189], v137 offset:49152
	ds_read_b128 v[190:193], v137 offset:50176
	ds_read_b128 v[194:197], v137 offset:51200
	ds_read_b128 v[198:201], v137 offset:52224
	ds_read_b128 v[202:205], v137 offset:53248
	ds_read_b128 v[206:209], v137 offset:54272
	ds_read_b128 v[210:213], v137 offset:55296
	ds_read_b128 v[214:217], v137 offset:56320
	global_load_lds_dwordx4 v158, s[100:101] offset:128
	s_add_i32 m0, s35, 0xffffff80
	s_nop 0
	global_load_lds_dwordx4 v128, s[100:101] offset:128
	s_waitcnt lgkmcnt(0)
	s_setprio 1
	s_barrier
; #define PG8_STAGE(bufoff, gbase) do { _Pragma("unroll") for (int _i = 0; _i < 2; ++_i) \
;         __builtin_amdgcn_global_load_lds((const unsigned*)((const char*)(gbase) + voff[_i]), (LAS unsigned*)(lds + (bufoff) + ldsw + _i * 8192), 16, 0, 0); } while (0)
; #define PG8_MMA(ai, bj, At, Bt) do { __builtin_amdgcn_s_setprio(1); _Pragma("unroll") for (int m = 0; m < 4; ++m) _Pragma("unroll") for (int n = 0; n < 2; ++n) _Pragma("unroll") for (int k = 0; k < 2; ++k) \
;         acc[ai][bj][m][n] = __builtin_amdgcn_mfma_f32_16x16x32_bf16(Bt[n][k], At[m][k], acc[ai][bj][m][n], 0, 0, 0); __builtin_amdgcn_s_setprio(0); } while (0)
; #define PG8_WAIT_V(n) asm volatile("s_waitcnt vmcnt(" #n ")" ::: "memory")
; #define PG8_WAIT_L(n) asm volatile("s_waitcnt lgkmcnt(" #n ")" ::: "memory")
; #define PG8_BAR __builtin_amdgcn_s_barrier()
; #define PG8_SCHED __builtin_amdgcn_sched_barrier(0)
; template <class Epi>
; DI void gemm_phase(LAS unsigned char* lds, const Gemm g, const StaticOrder& S, const Epi& E) {
;     ...
;             PG8_BAR; PG8_WAIT_L(0); PG8_MMA(1, 0, At, B0); PG8_BAR; PG8_SCHED;
;             PG8_STAGE(PG8_SB(1, 1), b3 + hstep);
;             PG8_WAIT_V(6); PG8_BAR; PG8_MMA(1, 1, At, B1); PG8_BAR;
;     DI void operator()(const f32x4 (&acc)[2][2][4][2], const Unit& u, int wr, int wc, int fr, int fq) const {
;         const int row0 = u.pm * BM + wr * 64 + fr, col0 = u.pn * HALF + wc * 32 + 8 * fq;
; #pragma unroll
;         for (int ai = 0; ai < 2; ++ai)
; #pragma unroll
;             for (int m = 0; m < 4; ++m) { float hv[8];
; #pragma unroll
;                 for (int n = 0; n < 2; ++n)
; #pragma unroll
;                     for (int e = 0; e < 4; ++e) { const float gt = acc[ai][0][m][n][e], up = acc[ai][1][m][n][e];
;                         hv[n * 4 + e] = gt * __builtin_amdgcn_rcpf(1.f + __builtin_amdgcn_exp2f(-1.4426950408889634f * gt)) * up; }
;                 *(u32x4*)(H + (size_t)(row0 + ai * HALF + m * 16) * DFF + col0) = (u32x4){pk(hv[0], hv[1]), pk(hv[2], hv[3]), pk(hv[4], hv[5]), pk(hv[6], hv[7])}; }
	v_mfma_f32_16x16x32_bf16 v[60:63], v[138:141], v[186:189], v[60:63]
	v_mfma_f32_16x16x32_bf16 v[56:59], v[146:149], v[186:189], v[56:59]
	v_mfma_f32_16x16x32_bf16 v[44:47], v[138:141], v[194:197], v[44:47]
	v_mfma_f32_16x16x32_bf16 v[40:43], v[146:149], v[194:197], v[40:43]
	v_mfma_f32_16x16x32_bf16 v[28:31], v[138:141], v[202:205], v[28:31]
	v_mfma_f32_16x16x32_bf16 v[24:27], v[146:149], v[202:205], v[24:27]
	v_mfma_f32_16x16x32_bf16 v[12:15], v[138:141], v[210:213], v[12:15]
	v_mfma_f32_16x16x32_bf16 v[8:11], v[146:149], v[210:213], v[8:11]
	v_mfma_f32_16x16x32_bf16 v[60:63], v[142:145], v[190:193], v[60:63]
	v_mfma_f32_16x16x32_bf16 v[56:59], v[150:153], v[190:193], v[56:59]
	v_mfma_f32_16x16x32_bf16 v[44:47], v[142:145], v[198:201], v[44:47]
	v_mfma_f32_16x16x32_bf16 v[40:43], v[150:153], v[198:201], v[40:43]
	v_mfma_f32_16x16x32_bf16 v[28:31], v[142:145], v[206:209], v[28:31]
	v_mfma_f32_16x16x32_bf16 v[24:27], v[150:153], v[206:209], v[24:27]
	v_mfma_f32_16x16x32_bf16 v[12:15], v[142:145], v[214:217], v[12:15]
	s_setprio 0
	v_mfma_f32_16x16x32_bf16 v[8:11], v[150:153], v[214:217], v[8:11]
	s_barrier
	s_add_u32 s20, s20, 0x80080
	s_addc_u32 s21, s21, 0
	s_add_i32 s22, s22, s27
	s_mov_b32 m0, s22
	s_nop 0
	global_load_lds_dwordx4 v158, s[20:21]
	s_add_i32 m0, s22, 0x2000
	s_nop 0
	global_load_lds_dwordx4 v128, s[20:21]
	s_waitcnt vmcnt(6)
	s_setprio 1
	s_barrier
	v_mfma_f32_16x16x32_bf16 v[52:55], v[226:229], v[186:189], v[52:55]
	v_mfma_f32_16x16x32_bf16 v[48:51], v[234:237], v[186:189], v[48:51]
	v_mfma_f32_16x16x32_bf16 v[36:39], v[226:229], v[194:197], v[36:39]
	v_mfma_f32_16x16x32_bf16 v[32:35], v[234:237], v[194:197], v[32:35]
	v_mfma_f32_16x16x32_bf16 v[20:23], v[226:229], v[202:205], v[20:23]
	v_mfma_f32_16x16x32_bf16 v[16:19], v[234:237], v[202:205], v[16:19]
	v_mfma_f32_16x16x32_bf16 v[4:7], v[226:229], v[210:213], v[4:7]
	v_mfma_f32_16x16x32_bf16 v[0:3], v[234:237], v[210:213], v[0:3]
	v_mfma_f32_16x16x32_bf16 v[52:55], v[230:233], v[190:193], v[52:55]
	s_add_i32 s38, s38, 2
	v_mfma_f32_16x16x32_bf16 v[48:51], v[238:241], v[190:193], v[48:51]
	s_add_u32 s18, s18, 0x100
	v_mfma_f32_16x16x32_bf16 v[36:39], v[230:233], v[198:201], v[36:39]
	s_addc_u32 s19, s19, 0
	v_mfma_f32_16x16x32_bf16 v[32:35], v[238:241], v[198:201], v[32:35]
	s_add_u32 s33, s33, 0x100
	v_mfma_f32_16x16x32_bf16 v[20:23], v[230:233], v[206:209], v[20:23]
	s_addc_u32 s37, s37, 0
	v_mfma_f32_16x16x32_bf16 v[16:19], v[238:241], v[206:209], v[16:19]
	s_cmp_gt_u32 s38, 29
	v_mfma_f32_16x16x32_bf16 v[4:7], v[230:233], v[214:217], v[4:7]
	s_setprio 0
	v_mfma_f32_16x16x32_bf16 v[0:3], v[238:241], v[214:217], v[0:3]
	s_barrier
	s_cbranch_scc0 .LBB0_37
	v_mul_f32_e32 v139, 0xbfb8aa3b, v124
	v_exp_f32_e32 v139, v139
	v_lshl_or_b32 v140, s2, 7, v136
	v_lshl_add_u32 v138, s3, 8, v134
	v_ashrrev_i32_e32 v141, 31, v140
	v_add_f32_e32 v139, 1.0, v139
	v_rcp_f32_e32 v142, v139
	v_mul_f32_e32 v139, 0xbfb8aa3b, v125
	v_exp_f32_e32 v139, v139
	s_movk_i32 s4, 0x2c00
	s_and_b64 vcc, exec, s[6:7]
	s_mov_b64 s[20:21], s[16:17]
	v_add_f32_e32 v139, 1.0, v139
	v_rcp_f32_e32 v143, v139
	v_mul_f32_e32 v139, 0xbfb8aa3b, v126
	v_exp_f32_e32 v139, v139
	s_mov_b64 s[18:19], s[14:15]
	v_pk_mul_f32 v[124:125], v[124:125], v[142:143]
	v_add_f32_e32 v139, 1.0, v139
	v_rcp_f32_e32 v144, v139
	v_mul_f32_e32 v139, 0xbfb8aa3b, v127
	v_exp_f32_e32 v139, v139
	v_pk_mul_f32 v[116:117], v[124:125], v[116:117]
	v_add_f32_e32 v139, 1.0, v139
	v_rcp_f32_e32 v145, v139
	v_mul_f32_e32 v139, 0xbfb8aa3b, v120
	v_exp_f32_e32 v139, v139
	v_cvt_pk_bf16_f32 v116, v116, v117
	v_pk_mul_f32 v[124:125], v[126:127], v[144:145]
	v_add_f32_e32 v139, 1.0, v139
	v_rcp_f32_e32 v146, v139
	v_mul_f32_e32 v139, 0xbfb8aa3b, v121
	v_exp_f32_e32 v139, v139
	v_pk_mul_f32 v[118:119], v[124:125], v[118:119]
	v_add_f32_e32 v139, 1.0, v139
	v_rcp_f32_e32 v147, v139
	v_mul_f32_e32 v139, 0xbfb8aa3b, v122
	v_exp_f32_e32 v139, v139
	v_cvt_pk_bf16_f32 v117, v118, v119
	v_pk_mul_f32 v[118:119], v[120:121], v[146:147]
	v_add_f32_e32 v139, 1.0, v139
	v_rcp_f32_e32 v148, v139
	v_mul_f32_e32 v139, 0xbfb8aa3b, v123
	v_exp_f32_e32 v139, v139
	v_pk_mul_f32 v[112:113], v[118:119], v[112:113]
	v_add_f32_e32 v139, 1.0, v139
	v_rcp_f32_e32 v149, v139
	v_cvt_pk_bf16_f32 v118, v112, v113
	v_pk_mul_f32 v[112:113], v[122:123], v[148:149]
	s_nop 0
	v_pk_mul_f32 v[112:113], v[112:113], v[114:115]
	v_lshlrev_b64 v[114:115], 1, v[140:141]
	v_cvt_pk_bf16_f32 v119, v112, v113
	v_mov_b64_e32 v[112:113], s[54:55]
	v_mad_i64_i32 v[120:121], s[2:3], v138, s4, v[112:113]
	v_lshl_add_u64 v[120:121], v[120:121], 0, v[114:115]
	global_store_dwordx4 v[120:121], v[116:119], off
	v_mul_f32_e32 v120, 0xbfb8aa3b, v104
	v_mul_f32_e32 v121, 0xbfb8aa3b, v105
	v_mul_f32_e32 v116, 0xbfb8aa3b, v108
	v_mul_f32_e32 v117, 0xbfb8aa3b, v109
	v_exp_f32_e32 v116, v116
	v_exp_f32_e32 v117, v117
	v_mul_f32_e32 v118, 0xbfb8aa3b, v110
	v_mul_f32_e32 v119, 0xbfb8aa3b, v111
	v_exp_f32_e32 v118, v118
	v_exp_f32_e32 v119, v119
	v_exp_f32_e32 v120, v120
	v_exp_f32_e32 v121, v121
	v_add_f32_e32 v116, 1.0, v116
	v_add_f32_e32 v117, 1.0, v117
	v_mul_f32_e32 v122, 0xbfb8aa3b, v106
	v_mul_f32_e32 v123, 0xbfb8aa3b, v107
	v_rcp_f32_e32 v116, v116
	v_rcp_f32_e32 v117, v117
	v_add_f32_e32 v118, 1.0, v118
	v_add_f32_e32 v119, 1.0, v119
	v_exp_f32_e32 v122, v122
	v_exp_f32_e32 v123, v123
	v_rcp_f32_e32 v118, v118
	v_rcp_f32_e32 v119, v119
	v_add_f32_e32 v120, 1.0, v120
	v_add_f32_e32 v121, 1.0, v121
	v_rcp_f32_e32 v120, v120
	v_rcp_f32_e32 v121, v121
	v_add_f32_e32 v122, 1.0, v122
	v_add_f32_e32 v123, 1.0, v123
	v_pk_mul_f32 v[108:109], v[108:109], v[116:117]
	v_rcp_f32_e32 v122, v122
;     DI void operator()(const f32x4 (&acc)[2][2][4][2], const Unit& u, int wr, int wc, int fr, int fq) const {
;     ...
;             for (int m = 0; m < 4; ++m) { float hv[8];
; #pragma unroll
;                 for (int n = 0; n < 2; ++n)
; #pragma unroll
;                     for (int e = 0; e < 4; ++e) { const float gt = acc[ai][0][m][n][e], up = acc[ai][1][m][n][e];
;                         hv[n * 4 + e] = gt * __builtin_amdgcn_rcpf(1.f + __builtin_amdgcn_exp2f(-1.4426950408889634f * gt)) * up; }
;                 *(u32x4*)(H + (size_t)(row0 + ai * HALF + m * 16) * DFF + col0) = (u32x4){pk(hv[0], hv[1]), pk(hv[2], hv[3]), pk(hv[4], hv[5]), pk(hv[6], hv[7])}; }
	v_rcp_f32_e32 v123, v123
	v_pk_mul_f32 v[100:101], v[108:109], v[100:101]
	v_pk_mul_f32 v[108:109], v[110:111], v[118:119]
	v_cvt_pk_bf16_f32 v100, v100, v101
	v_pk_mul_f32 v[102:103], v[108:109], v[102:103]
	s_nop 0
	v_cvt_pk_bf16_f32 v101, v102, v103
	v_pk_mul_f32 v[102:103], v[104:105], v[120:121]
	s_nop 0
	v_pk_mul_f32 v[96:97], v[102:103], v[96:97]
	s_nop 0
	v_cvt_pk_bf16_f32 v102, v96, v97
	v_pk_mul_f32 v[96:97], v[106:107], v[122:123]
	s_nop 0
	v_pk_mul_f32 v[96:97], v[96:97], v[98:99]
	v_mul_f32_e32 v98, 0xbfb8aa3b, v94
	v_cvt_pk_bf16_f32 v103, v96, v97
	v_or_b32_e32 v96, 16, v138
	v_mad_i64_i32 v[96:97], s[2:3], v96, s4, v[112:113]
	v_lshl_add_u64 v[96:97], v[96:97], 0, v[114:115]
	global_store_dwordx4 v[96:97], v[100:103], off
	v_mul_f32_e32 v96, 0xbfb8aa3b, v92
	v_mul_f32_e32 v97, 0xbfb8aa3b, v93
	v_exp_f32_e32 v96, v96
	v_exp_f32_e32 v97, v97
	v_mul_f32_e32 v99, 0xbfb8aa3b, v95
	v_exp_f32_e32 v98, v98
	v_exp_f32_e32 v99, v99
	v_mul_f32_e32 v100, 0xbfb8aa3b, v88
	v_mul_f32_e32 v101, 0xbfb8aa3b, v89
	v_exp_f32_e32 v100, v100
	v_exp_f32_e32 v101, v101
	v_add_f32_e32 v96, 1.0, v96
	v_add_f32_e32 v97, 1.0, v97
	v_mul_f32_e32 v102, 0xbfb8aa3b, v90
	v_mul_f32_e32 v103, 0xbfb8aa3b, v91
	v_rcp_f32_e32 v96, v96
	v_rcp_f32_e32 v97, v97
	v_add_f32_e32 v98, 1.0, v98
	v_add_f32_e32 v99, 1.0, v99
	v_exp_f32_e32 v102, v102
	v_exp_f32_e32 v103, v103
	v_rcp_f32_e32 v98, v98
	v_rcp_f32_e32 v99, v99
	v_add_f32_e32 v100, 1.0, v100
	v_add_f32_e32 v101, 1.0, v101
	v_rcp_f32_e32 v100, v100
	v_rcp_f32_e32 v101, v101
	v_add_f32_e32 v102, 1.0, v102
	v_add_f32_e32 v103, 1.0, v103
	v_pk_mul_f32 v[92:93], v[92:93], v[96:97]
	v_rcp_f32_e32 v102, v102
	v_rcp_f32_e32 v103, v103
	v_pk_mul_f32 v[84:85], v[92:93], v[84:85]
	v_pk_mul_f32 v[92:93], v[94:95], v[98:99]
	v_cvt_pk_bf16_f32 v84, v84, v85
	v_pk_mul_f32 v[86:87], v[92:93], v[86:87]
	s_nop 0
	v_cvt_pk_bf16_f32 v85, v86, v87
	v_pk_mul_f32 v[86:87], v[88:89], v[100:101]
	s_nop 0
	v_pk_mul_f32 v[80:81], v[86:87], v[80:81]
	s_nop 0
	v_cvt_pk_bf16_f32 v86, v80, v81
	v_pk_mul_f32 v[80:81], v[90:91], v[102:103]
	s_nop 0
	v_pk_mul_f32 v[80:81], v[80:81], v[82:83]
	v_mul_f32_e32 v82, 0xbfb8aa3b, v78
	v_cvt_pk_bf16_f32 v87, v80, v81
	v_or_b32_e32 v80, 32, v138
	v_mad_i64_i32 v[80:81], s[2:3], v80, s4, v[112:113]
	v_lshl_add_u64 v[80:81], v[80:81], 0, v[114:115]
	global_store_dwordx4 v[80:81], v[84:87], off
	v_mul_f32_e32 v80, 0xbfb8aa3b, v76
	v_mul_f32_e32 v81, 0xbfb8aa3b, v77
	v_exp_f32_e32 v80, v80
	v_exp_f32_e32 v81, v81
	v_mul_f32_e32 v83, 0xbfb8aa3b, v79
	v_exp_f32_e32 v82, v82
	v_exp_f32_e32 v83, v83
	v_mul_f32_e32 v84, 0xbfb8aa3b, v72
	v_mul_f32_e32 v85, 0xbfb8aa3b, v73
	v_exp_f32_e32 v84, v84
	v_exp_f32_e32 v85, v85
	v_add_f32_e32 v80, 1.0, v80
	v_add_f32_e32 v81, 1.0, v81
	v_mul_f32_e32 v86, 0xbfb8aa3b, v74
	v_mul_f32_e32 v87, 0xbfb8aa3b, v75
	v_rcp_f32_e32 v80, v80
	v_rcp_f32_e32 v81, v81
	v_add_f32_e32 v82, 1.0, v82
	v_add_f32_e32 v83, 1.0, v83
	v_exp_f32_e32 v86, v86
	v_exp_f32_e32 v87, v87
	v_rcp_f32_e32 v82, v82
	v_rcp_f32_e32 v83, v83
	v_add_f32_e32 v84, 1.0, v84
	v_add_f32_e32 v85, 1.0, v85
	v_rcp_f32_e32 v84, v84
	v_rcp_f32_e32 v85, v85
	v_add_f32_e32 v86, 1.0, v86
	v_add_f32_e32 v87, 1.0, v87
	v_pk_mul_f32 v[76:77], v[76:77], v[80:81]
	v_rcp_f32_e32 v86, v86
	v_rcp_f32_e32 v87, v87
	v_pk_mul_f32 v[68:69], v[76:77], v[68:69]
	v_pk_mul_f32 v[76:77], v[78:79], v[82:83]
	v_cvt_pk_bf16_f32 v68, v68, v69
	v_pk_mul_f32 v[70:71], v[76:77], v[70:71]
	s_nop 0
	v_cvt_pk_bf16_f32 v69, v70, v71
	v_pk_mul_f32 v[70:71], v[72:73], v[84:85]
	v_add_u32_e32 v72, 0x80, v138
	v_pk_mul_f32 v[64:65], v[70:71], v[64:65]
	s_nop 0
	v_cvt_pk_bf16_f32 v70, v64, v65
	v_pk_mul_f32 v[64:65], v[74:75], v[86:87]
	s_nop 0
	v_pk_mul_f32 v[64:65], v[64:65], v[66:67]
	v_mul_f32_e32 v66, 0xbfb8aa3b, v62
	v_cvt_pk_bf16_f32 v71, v64, v65
	v_or_b32_e32 v64, 48, v138
	v_mad_i64_i32 v[64:65], s[2:3], v64, s4, v[112:113]
	v_lshl_add_u64 v[64:65], v[64:65], 0, v[114:115]
	global_store_dwordx4 v[64:65], v[68:71], off
	v_mul_f32_e32 v64, 0xbfb8aa3b, v60
	v_mul_f32_e32 v65, 0xbfb8aa3b, v61
	v_exp_f32_e32 v64, v64
	v_exp_f32_e32 v65, v65
	v_mul_f32_e32 v67, 0xbfb8aa3b, v63
	v_exp_f32_e32 v66, v66
	v_exp_f32_e32 v67, v67
	v_mul_f32_e32 v68, 0xbfb8aa3b, v56
	v_mul_f32_e32 v69, 0xbfb8aa3b, v57
	v_exp_f32_e32 v68, v68
	v_exp_f32_e32 v69, v69
	v_add_f32_e32 v64, 1.0, v64
	v_add_f32_e32 v65, 1.0, v65
	v_mul_f32_e32 v70, 0xbfb8aa3b, v58
	v_mul_f32_e32 v71, 0xbfb8aa3b, v59
	v_rcp_f32_e32 v64, v64
	v_rcp_f32_e32 v65, v65
	v_add_f32_e32 v66, 1.0, v66
	v_add_f32_e32 v67, 1.0, v67
	v_exp_f32_e32 v70, v70
	v_exp_f32_e32 v71, v71
	v_rcp_f32_e32 v66, v66
	v_rcp_f32_e32 v67, v67
	v_add_f32_e32 v68, 1.0, v68
	v_add_f32_e32 v69, 1.0, v69
	v_rcp_f32_e32 v68, v68
	v_rcp_f32_e32 v69, v69
	v_add_f32_e32 v70, 1.0, v70
	v_add_f32_e32 v71, 1.0, v71
	v_pk_mul_f32 v[60:61], v[60:61], v[64:65]
	v_rcp_f32_e32 v70, v70
	v_rcp_f32_e32 v71, v71
	v_pk_mul_f32 v[52:53], v[60:61], v[52:53]
	v_pk_mul_f32 v[60:61], v[62:63], v[66:67]
	v_cvt_pk_bf16_f32 v52, v52, v53
	v_pk_mul_f32 v[54:55], v[60:61], v[54:55]
	s_nop 0
	v_cvt_pk_bf16_f32 v53, v54, v55
	v_pk_mul_f32 v[54:55], v[56:57], v[68:69]
	s_nop 0
	v_pk_mul_f32 v[48:49], v[54:55], v[48:49]
; #define PG8_WAIT_V(n) asm volatile("s_waitcnt vmcnt(" #n ")" ::: "memory")
; #define PG8_BAR __builtin_amdgcn_s_barrier()
; template <class Epi>
; DI void gemm_phase(LAS unsigned char* lds, const Gemm g, const StaticOrder& S, const Epi& E) {
;     ...
;         E(acc, cur, wr, wc, fr, fq);
;         if (!has_next) break;
; #pragma unroll
;         for (int a = 0; a < 2; ++a)
; #pragma unroll
;             for (int b = 0; b < 2; ++b)
; #pragma unroll
;                 for (int m = 0; m < 4; ++m)
; #pragma unroll
;                     for (int n = 0; n < 2; ++n) acc[a][b][m][n] = (f32x4){0.f, 0.f, 0.f, 0.f};
;         cur = nxt; cA = nA; cB = nB; ++ui;
;     }
;     PG8_WAIT_V(0);
;     if (wr == 0) PG8_BAR;
;     DI void operator()(const f32x4 (&acc)[2][2][4][2], const Unit& u, int wr, int wc, int fr, int fq) const {
;     ...
;             for (int m = 0; m < 4; ++m) { float hv[8];
; #pragma unroll
;                 for (int n = 0; n < 2; ++n)
; #pragma unroll
;                     for (int e = 0; e < 4; ++e) { const float gt = acc[ai][0][m][n][e], up = acc[ai][1][m][n][e];
;                         hv[n * 4 + e] = gt * __builtin_amdgcn_rcpf(1.f + __builtin_amdgcn_exp2f(-1.4426950408889634f * gt)) * up; }
;                 *(u32x4*)(H + (size_t)(row0 + ai * HALF + m * 16) * DFF + col0) = (u32x4){pk(hv[0], hv[1]), pk(hv[2], hv[3]), pk(hv[4], hv[5]), pk(hv[6], hv[7])}; }
	s_nop 0
	v_cvt_pk_bf16_f32 v54, v48, v49
	v_pk_mul_f32 v[48:49], v[58:59], v[70:71]
	s_nop 0
	v_pk_mul_f32 v[48:49], v[48:49], v[50:51]
	v_mul_f32_e32 v50, 0xbfb8aa3b, v46
	v_cvt_pk_bf16_f32 v55, v48, v49
	v_mad_i64_i32 v[48:49], s[2:3], v72, s4, v[112:113]
	v_lshl_add_u64 v[48:49], v[48:49], 0, v[114:115]
	global_store_dwordx4 v[48:49], v[52:55], off
	v_mul_f32_e32 v48, 0xbfb8aa3b, v44
	v_mul_f32_e32 v49, 0xbfb8aa3b, v45
	v_exp_f32_e32 v48, v48
	v_exp_f32_e32 v49, v49
	v_mul_f32_e32 v51, 0xbfb8aa3b, v47
	v_exp_f32_e32 v50, v50
	v_exp_f32_e32 v51, v51
	v_mul_f32_e32 v52, 0xbfb8aa3b, v40
	v_mul_f32_e32 v53, 0xbfb8aa3b, v41
	v_exp_f32_e32 v52, v52
	v_exp_f32_e32 v53, v53
	v_add_f32_e32 v48, 1.0, v48
	v_add_f32_e32 v49, 1.0, v49
	v_mul_f32_e32 v54, 0xbfb8aa3b, v42
	v_mul_f32_e32 v55, 0xbfb8aa3b, v43
	v_rcp_f32_e32 v48, v48
	v_rcp_f32_e32 v49, v49
	v_add_f32_e32 v50, 1.0, v50
	v_add_f32_e32 v51, 1.0, v51
	v_exp_f32_e32 v54, v54
	v_exp_f32_e32 v55, v55
	v_rcp_f32_e32 v50, v50
	v_rcp_f32_e32 v51, v51
	v_add_f32_e32 v52, 1.0, v52
	v_add_f32_e32 v53, 1.0, v53
	v_rcp_f32_e32 v52, v52
	v_rcp_f32_e32 v53, v53
	v_add_f32_e32 v54, 1.0, v54
	v_add_f32_e32 v55, 1.0, v55
	v_pk_mul_f32 v[44:45], v[44:45], v[48:49]
	v_rcp_f32_e32 v54, v54
	v_rcp_f32_e32 v55, v55
	v_pk_mul_f32 v[36:37], v[44:45], v[36:37]
	v_pk_mul_f32 v[44:45], v[46:47], v[50:51]
	v_cvt_pk_bf16_f32 v36, v36, v37
	v_pk_mul_f32 v[38:39], v[44:45], v[38:39]
	s_nop 0
	v_cvt_pk_bf16_f32 v37, v38, v39
	v_pk_mul_f32 v[38:39], v[40:41], v[52:53]
	s_nop 0
	v_pk_mul_f32 v[32:33], v[38:39], v[32:33]
	s_nop 0
	v_cvt_pk_bf16_f32 v38, v32, v33
	v_pk_mul_f32 v[32:33], v[42:43], v[54:55]
	s_nop 0
	v_pk_mul_f32 v[32:33], v[32:33], v[34:35]
	v_mul_f32_e32 v34, 0xbfb8aa3b, v30
	v_cvt_pk_bf16_f32 v39, v32, v33
	v_add_u32_e32 v32, 0x90, v138
	v_mad_i64_i32 v[32:33], s[2:3], v32, s4, v[112:113]
	v_lshl_add_u64 v[32:33], v[32:33], 0, v[114:115]
	global_store_dwordx4 v[32:33], v[36:39], off
	v_mul_f32_e32 v32, 0xbfb8aa3b, v28
	v_mul_f32_e32 v33, 0xbfb8aa3b, v29
	v_exp_f32_e32 v32, v32
	v_exp_f32_e32 v33, v33
	v_mul_f32_e32 v35, 0xbfb8aa3b, v31
	v_exp_f32_e32 v34, v34
	v_exp_f32_e32 v35, v35
	v_mul_f32_e32 v36, 0xbfb8aa3b, v24
	v_mul_f32_e32 v37, 0xbfb8aa3b, v25
	v_exp_f32_e32 v36, v36
	v_exp_f32_e32 v37, v37
	v_add_f32_e32 v32, 1.0, v32
	v_add_f32_e32 v33, 1.0, v33
	v_mul_f32_e32 v38, 0xbfb8aa3b, v26
	v_mul_f32_e32 v39, 0xbfb8aa3b, v27
	v_rcp_f32_e32 v32, v32
	v_rcp_f32_e32 v33, v33
	v_add_f32_e32 v34, 1.0, v34
	v_add_f32_e32 v35, 1.0, v35
	v_exp_f32_e32 v38, v38
	v_exp_f32_e32 v39, v39
	v_rcp_f32_e32 v34, v34
	v_rcp_f32_e32 v35, v35
	v_add_f32_e32 v36, 1.0, v36
	v_add_f32_e32 v37, 1.0, v37
	v_rcp_f32_e32 v36, v36
	v_rcp_f32_e32 v37, v37
	v_add_f32_e32 v38, 1.0, v38
	v_add_f32_e32 v39, 1.0, v39
	v_pk_mul_f32 v[28:29], v[28:29], v[32:33]
	v_rcp_f32_e32 v38, v38
	v_rcp_f32_e32 v39, v39
	v_pk_mul_f32 v[20:21], v[28:29], v[20:21]
	v_pk_mul_f32 v[28:29], v[30:31], v[34:35]
	v_cvt_pk_bf16_f32 v20, v20, v21
	v_pk_mul_f32 v[22:23], v[28:29], v[22:23]
	s_nop 0
	v_cvt_pk_bf16_f32 v21, v22, v23
	v_pk_mul_f32 v[22:23], v[24:25], v[36:37]
	s_nop 0
	v_pk_mul_f32 v[16:17], v[22:23], v[16:17]
	s_nop 0
	v_cvt_pk_bf16_f32 v22, v16, v17
	v_pk_mul_f32 v[16:17], v[26:27], v[38:39]
	s_nop 0
	v_pk_mul_f32 v[16:17], v[16:17], v[18:19]
	v_mul_f32_e32 v18, 0xbfb8aa3b, v14
	v_cvt_pk_bf16_f32 v23, v16, v17
	v_add_u32_e32 v16, 0xa0, v138
	v_mad_i64_i32 v[16:17], s[2:3], v16, s4, v[112:113]
	v_lshl_add_u64 v[16:17], v[16:17], 0, v[114:115]
	global_store_dwordx4 v[16:17], v[20:23], off
	v_mul_f32_e32 v16, 0xbfb8aa3b, v12
	v_mul_f32_e32 v17, 0xbfb8aa3b, v13
	v_exp_f32_e32 v16, v16
	v_exp_f32_e32 v17, v17
	v_mul_f32_e32 v19, 0xbfb8aa3b, v15
	v_exp_f32_e32 v18, v18
	v_exp_f32_e32 v19, v19
	v_mul_f32_e32 v20, 0xbfb8aa3b, v8
	v_mul_f32_e32 v21, 0xbfb8aa3b, v9
	v_exp_f32_e32 v20, v20
	v_exp_f32_e32 v21, v21
	v_add_f32_e32 v16, 1.0, v16
	v_add_f32_e32 v17, 1.0, v17
	v_mul_f32_e32 v22, 0xbfb8aa3b, v10
	v_mul_f32_e32 v23, 0xbfb8aa3b, v11
	v_rcp_f32_e32 v16, v16
	v_rcp_f32_e32 v17, v17
	v_add_f32_e32 v18, 1.0, v18
	v_add_f32_e32 v19, 1.0, v19
	v_exp_f32_e32 v22, v22
	v_exp_f32_e32 v23, v23
	v_rcp_f32_e32 v18, v18
	v_rcp_f32_e32 v19, v19
	v_add_f32_e32 v20, 1.0, v20
	v_add_f32_e32 v21, 1.0, v21
	v_rcp_f32_e32 v20, v20
	v_rcp_f32_e32 v21, v21
	v_add_f32_e32 v22, 1.0, v22
	v_add_f32_e32 v23, 1.0, v23
	v_pk_mul_f32 v[12:13], v[12:13], v[16:17]
	v_rcp_f32_e32 v22, v22
	v_rcp_f32_e32 v23, v23
	v_pk_mul_f32 v[4:5], v[12:13], v[4:5]
	v_pk_mul_f32 v[12:13], v[14:15], v[18:19]
	v_cvt_pk_bf16_f32 v4, v4, v5
	v_pk_mul_f32 v[6:7], v[12:13], v[6:7]
	s_nop 0
	v_cvt_pk_bf16_f32 v5, v6, v7
	v_pk_mul_f32 v[6:7], v[8:9], v[20:21]
	s_nop 0
	v_pk_mul_f32 v[0:1], v[6:7], v[0:1]
	s_nop 0
	v_cvt_pk_bf16_f32 v6, v0, v1
	v_pk_mul_f32 v[0:1], v[10:11], v[22:23]
	s_nop 0
	v_pk_mul_f32 v[0:1], v[0:1], v[2:3]
	s_nop 0
	v_cvt_pk_bf16_f32 v7, v0, v1
	v_add_u32_e32 v0, 0xb0, v138
	v_mad_i64_i32 v[0:1], s[2:3], v0, s4, v[112:113]
	v_lshl_add_u64 v[0:1], v[0:1], 0, v[114:115]
	s_mov_b32 s2, s8
	s_mov_b32 s3, s10
	global_store_dwordx4 v[0:1], v[4:7], off
	s_cbranch_vccz .LBB0_34
	s_waitcnt vmcnt(0)
	s_cmpk_gt_u32 s24, 0xff
	s_cbranch_scc1 .LBB0_41
	s_barrier

; #define PG8_STAGE(bufoff, gbase) do { _Pragma("unroll") for (int _i = 0; _i < 2; ++_i) \
;         __builtin_amdgcn_global_load_lds((const unsigned*)((const char*)(gbase) + voff[_i]), (LAS unsigned*)(lds + (bufoff) + ldsw + _i * 8192), 16, 0, 0); } while (0)
; #define PG8_LDA(dst, b, h) do { _Pragma("unroll") for (int m = 0; m < 4; ++m) _Pragma("unroll") for (int k = 0; k < 2; ++k) dst[m][k] = *(const LAS bf16x8*)(lds + PG8_SA(b, h) + aoff + m * 2048 + k * 1024); } while (0)
; #define PG8_LDB(dst, b, h) do { _Pragma("unroll") for (int n = 0; n < 2; ++n) _Pragma("unroll") for (int k = 0; k < 2; ++k) dst[n][k] = *(const LAS bf16x8*)(lds + PG8_SB(b, h) + boff + n * 2048 + k * 1024); } while (0)
; #define PG8_MMA(ai, bj, At, Bt) do { __builtin_amdgcn_s_setprio(1); _Pragma("unroll") for (int m = 0; m < 4; ++m) _Pragma("unroll") for (int n = 0; n < 2; ++n) _Pragma("unroll") for (int k = 0; k < 2; ++k) \
;         acc[ai][bj][m][n] = __builtin_amdgcn_mfma_f32_16x16x32_bf16(Bt[n][k], At[m][k], acc[ai][bj][m][n], 0, 0, 0); __builtin_amdgcn_s_setprio(0); } while (0)
; #define PG8_WAIT_V(n) asm volatile("s_waitcnt vmcnt(" #n ")" ::: "memory")
; #define PG8_WAIT_L(n) asm volatile("s_waitcnt lgkmcnt(" #n ")" ::: "memory")
; #define PG8_BAR __builtin_amdgcn_s_barrier()
; #define PG8_SCHED __builtin_amdgcn_sched_barrier(0)
; template <class Epi>
; DI void gemm_phase(LAS unsigned char* lds, const Gemm g, const StaticOrder& S, const Epi& E) {
;     ...
;             const bool last = (t == nt - 2);
;             const char* a1 = cA + (size_t)(t + 1) * kstep;
;             const char* a2 = last ? nA : cA + (size_t)(t + 2) * kstep; const char* b2 = last ? nB : cB + (size_t)(t + 2) * kstep;
;             const char* a3 = a2 + kstep; const char* b3 = b2 + kstep;
;             PG8_LDB(B0, 0, 0); PG8_SCHED; PG8_LDA(At, 0, 0); PG8_STAGE(PG8_SA(1, 1), a1 + hstep);
;             PG8_WAIT_L(8); PG8_BAR; PG8_WAIT_L(0); PG8_MMA(0, 0, At, B0); PG8_BAR; PG8_SCHED;
;             PG8_LDB(B1, 0, 1); PG8_STAGE(PG8_SB(0, 0), b2);
;             PG8_BAR; PG8_WAIT_L(0); PG8_MMA(0, 1, At, B1); PG8_BAR;
;             PG8_LDA(At, 0, 1); PG8_STAGE(PG8_SA(0, 0), a2);
;             PG8_BAR; PG8_WAIT_L(0); PG8_MMA(1, 0, At, B0); PG8_BAR; PG8_SCHED;
;             PG8_STAGE(PG8_SB(0, 1), b2 + hstep);
;             PG8_WAIT_V(6); PG8_BAR; PG8_MMA(1, 1, At, B1); PG8_BAR;
.LBB0_77:
	ds_read_b128 v[128:131], v226
	ds_read_b128 v[132:135], v226 offset:1024
	ds_read_b128 v[136:139], v226 offset:2048
	ds_read_b128 v[140:143], v226 offset:3072
	ds_read_b128 v[144:147], v228
	ds_read_b128 v[148:151], v228 offset:1024
	ds_read_b128 v[152:155], v228 offset:2048
	ds_read_b128 v[194:197], v228 offset:3072
	ds_read_b128 v[198:201], v228 offset:4096
	ds_read_b128 v[202:205], v228 offset:5120
	ds_read_b128 v[206:209], v228 offset:6144
	ds_read_b128 v[210:213], v228 offset:7168
	s_add_u32 s22, s20, 0x100
	s_addc_u32 s23, s21, 0
	s_add_i32 s43, 0, 0x10000
	s_cmp_eq_u32 s33, 32
	s_cselect_b32 s27, s9, s23
	s_cselect_b32 s26, s8, s22
	s_cselect_b32 s25, s11, s5
	s_cselect_b32 s24, s10, s4
	s_add_i32 m0, s34, 0xc000
	s_nop 0
	global_load_lds_dwordx4 v190, s[20:21]
	s_add_i32 m0, s34, 0xe000
	s_nop 0
	global_load_lds_dwordx4 v192, s[20:21]
	s_waitcnt lgkmcnt(8)
	s_setprio 1
	s_barrier
	s_waitcnt lgkmcnt(0)
	v_mfma_f32_16x16x32_bf16 v[124:127], v[128:131], v[144:147], v[124:127]
	v_mfma_f32_16x16x32_bf16 v[120:123], v[136:139], v[144:147], v[120:123]
	v_mfma_f32_16x16x32_bf16 v[116:119], v[128:131], v[152:155], v[116:119]
	v_mfma_f32_16x16x32_bf16 v[112:115], v[136:139], v[152:155], v[112:115]
	v_mfma_f32_16x16x32_bf16 v[108:111], v[128:131], v[198:201], v[108:111]
	v_mfma_f32_16x16x32_bf16 v[104:107], v[136:139], v[198:201], v[104:107]
	v_mfma_f32_16x16x32_bf16 v[100:103], v[128:131], v[206:209], v[100:103]
	v_mfma_f32_16x16x32_bf16 v[96:99], v[136:139], v[206:209], v[96:99]
	v_mfma_f32_16x16x32_bf16 v[124:127], v[132:135], v[148:151], v[124:127]
	v_mfma_f32_16x16x32_bf16 v[120:123], v[140:143], v[148:151], v[120:123]
	v_mfma_f32_16x16x32_bf16 v[116:119], v[132:135], v[194:197], v[116:119]
	v_mfma_f32_16x16x32_bf16 v[112:115], v[140:143], v[194:197], v[112:115]
	v_mfma_f32_16x16x32_bf16 v[108:111], v[132:135], v[202:205], v[108:111]
	v_mfma_f32_16x16x32_bf16 v[104:107], v[140:143], v[202:205], v[104:107]
	v_mfma_f32_16x16x32_bf16 v[100:103], v[132:135], v[210:213], v[100:103]
	s_setprio 0
	v_mfma_f32_16x16x32_bf16 v[96:99], v[140:143], v[210:213], v[96:99]
	s_barrier
	ds_read_b128 v[214:217], v226 offset:16384
	ds_read_b128 v[230:233], v226 offset:17408
	ds_read_b128 v[234:237], v226 offset:18432
	ds_read_b128 v[238:241], v226 offset:19456
	s_add_i32 s44, 0, 0x14000
	s_add_i32 s20, s43, s31
	s_mov_b32 m0, s20
	s_nop 0
	global_load_lds_dwordx4 v188, s[24:25]
	s_add_i32 m0, s20, 0x2000
	s_nop 0
	global_load_lds_dwordx4 v186, s[24:25]
	s_waitcnt lgkmcnt(0)
	s_setprio 1
	s_barrier
	v_mfma_f32_16x16x32_bf16 v[60:63], v[214:217], v[144:147], v[60:63]
	v_mfma_f32_16x16x32_bf16 v[56:59], v[234:237], v[144:147], v[56:59]
	v_mfma_f32_16x16x32_bf16 v[52:55], v[214:217], v[152:155], v[52:55]
	v_mfma_f32_16x16x32_bf16 v[48:51], v[234:237], v[152:155], v[48:51]
	v_mfma_f32_16x16x32_bf16 v[44:47], v[214:217], v[198:201], v[44:47]
	v_mfma_f32_16x16x32_bf16 v[40:43], v[234:237], v[198:201], v[40:43]
	v_mfma_f32_16x16x32_bf16 v[36:39], v[214:217], v[206:209], v[36:39]
	v_mfma_f32_16x16x32_bf16 v[32:35], v[234:237], v[206:209], v[32:35]
	v_mfma_f32_16x16x32_bf16 v[60:63], v[230:233], v[148:151], v[60:63]
	s_mov_b32 m0, s34
	v_mfma_f32_16x16x32_bf16 v[56:59], v[238:241], v[148:151], v[56:59]
	s_mov_b64 s[100:101], s[26:27]
	v_mfma_f32_16x16x32_bf16 v[52:55], v[230:233], v[194:197], v[52:55]
	v_mfma_f32_16x16x32_bf16 v[48:51], v[238:241], v[194:197], v[48:51]
	v_mfma_f32_16x16x32_bf16 v[44:47], v[230:233], v[202:205], v[44:47]
	v_mfma_f32_16x16x32_bf16 v[40:43], v[238:241], v[202:205], v[40:43]
	v_mfma_f32_16x16x32_bf16 v[36:39], v[230:233], v[210:213], v[36:39]
	s_setprio 0
	v_mfma_f32_16x16x32_bf16 v[32:35], v[238:241], v[210:213], v[32:35]
	s_barrier
	ds_read_b128 v[144:147], v228 offset:16384
	ds_read_b128 v[148:151], v228 offset:17408
	ds_read_b128 v[152:155], v228 offset:18432
	ds_read_b128 v[194:197], v228 offset:19456
	ds_read_b128 v[198:201], v228 offset:20480
	ds_read_b128 v[202:205], v228 offset:21504
	ds_read_b128 v[206:209], v228 offset:22528
	ds_read_b128 v[210:213], v228 offset:23552
	global_load_lds_dwordx4 v188, s[26:27]
	s_mov_b64 s[100:101], s[26:27]
	s_mov_b32 m0, s35
	s_nop 0
	global_load_lds_dwordx4 v186, s[26:27]
	s_waitcnt lgkmcnt(0)
	s_setprio 1
	s_barrier
	v_mfma_f32_16x16x32_bf16 v[92:95], v[128:131], v[144:147], v[92:95]
	v_mfma_f32_16x16x32_bf16 v[88:91], v[136:139], v[144:147], v[88:91]
	v_mfma_f32_16x16x32_bf16 v[84:87], v[128:131], v[152:155], v[84:87]
	v_mfma_f32_16x16x32_bf16 v[80:83], v[136:139], v[152:155], v[80:83]
	v_mfma_f32_16x16x32_bf16 v[76:79], v[128:131], v[198:201], v[76:79]
	v_mfma_f32_16x16x32_bf16 v[72:75], v[136:139], v[198:201], v[72:75]
	v_mfma_f32_16x16x32_bf16 v[68:71], v[128:131], v[206:209], v[68:71]
	v_mfma_f32_16x16x32_bf16 v[64:67], v[136:139], v[206:209], v[64:67]
	v_mfma_f32_16x16x32_bf16 v[92:95], v[132:135], v[148:151], v[92:95]
	v_mfma_f32_16x16x32_bf16 v[88:91], v[140:143], v[148:151], v[88:91]
	v_mfma_f32_16x16x32_bf16 v[84:87], v[132:135], v[194:197], v[84:87]
	v_mfma_f32_16x16x32_bf16 v[80:83], v[140:143], v[194:197], v[80:83]
	v_mfma_f32_16x16x32_bf16 v[76:79], v[132:135], v[202:205], v[76:79]
	v_mfma_f32_16x16x32_bf16 v[72:75], v[140:143], v[202:205], v[72:75]
	v_mfma_f32_16x16x32_bf16 v[68:71], v[132:135], v[210:213], v[68:71]
	s_setprio 0
	v_mfma_f32_16x16x32_bf16 v[64:67], v[140:143], v[210:213], v[64:67]
	s_barrier
	s_add_u32 s20, s24, 0x90000
	s_addc_u32 s21, s25, 0
	s_add_i32 s43, s44, s31
	s_mov_b32 m0, s43
	s_nop 0
	global_load_lds_dwordx4 v188, s[20:21]
	s_add_i32 m0, s43, 0x2000
	s_nop 0
	global_load_lds_dwordx4 v186, s[20:21]
	s_waitcnt vmcnt(6)
	s_setprio 1
	s_barrier
; #define PG8_STAGE(bufoff, gbase) do { _Pragma("unroll") for (int _i = 0; _i < 2; ++_i) \
;         __builtin_amdgcn_global_load_lds((const unsigned*)((const char*)(gbase) + voff[_i]), (LAS unsigned*)(lds + (bufoff) + ldsw + _i * 8192), 16, 0, 0); } while (0)
; #define PG8_LDA(dst, b, h) do { _Pragma("unroll") for (int m = 0; m < 4; ++m) _Pragma("unroll") for (int k = 0; k < 2; ++k) dst[m][k] = *(const LAS bf16x8*)(lds + PG8_SA(b, h) + aoff + m * 2048 + k * 1024); } while (0)
; #define PG8_LDB(dst, b, h) do { _Pragma("unroll") for (int n = 0; n < 2; ++n) _Pragma("unroll") for (int k = 0; k < 2; ++k) dst[n][k] = *(const LAS bf16x8*)(lds + PG8_SB(b, h) + boff + n * 2048 + k * 1024); } while (0)
; #define PG8_MMA(ai, bj, At, Bt) do { __builtin_amdgcn_s_setprio(1); _Pragma("unroll") for (int m = 0; m < 4; ++m) _Pragma("unroll") for (int n = 0; n < 2; ++n) _Pragma("unroll") for (int k = 0; k < 2; ++k) \
;         acc[ai][bj][m][n] = __builtin_amdgcn_mfma_f32_16x16x32_bf16(Bt[n][k], At[m][k], acc[ai][bj][m][n], 0, 0, 0); __builtin_amdgcn_s_setprio(0); } while (0)
; #define PG8_WAIT_V(n) asm volatile("s_waitcnt vmcnt(" #n ")" ::: "memory")
; #define PG8_WAIT_L(n) asm volatile("s_waitcnt lgkmcnt(" #n ")" ::: "memory")
; #define PG8_BAR __builtin_amdgcn_s_barrier()
; #define PG8_SCHED __builtin_amdgcn_sched_barrier(0)
; template <class Epi>
; DI void gemm_phase(LAS unsigned char* lds, const Gemm g, const StaticOrder& S, const Epi& E) {
;     ...
;             PG8_WAIT_V(6); PG8_BAR; PG8_MMA(1, 1, At, B1); PG8_BAR;
;             PG8_LDB(B0, 1, 0); PG8_SCHED; PG8_LDA(At, 1, 0); PG8_STAGE(PG8_SA(0, 1), a2 + hstep);
;             PG8_WAIT_L(8); PG8_BAR; PG8_WAIT_L(0); PG8_MMA(0, 0, At, B0); PG8_BAR; PG8_SCHED;
;             PG8_LDB(B1, 1, 1); PG8_STAGE(PG8_SB(1, 0), b3);
;             PG8_BAR; PG8_WAIT_L(0); PG8_MMA(0, 1, At, B1); PG8_BAR;
;             PG8_LDA(At, 1, 1); PG8_STAGE(PG8_SA(1, 0), a3);
;             PG8_BAR; PG8_WAIT_L(0); PG8_MMA(1, 0, At, B0); PG8_BAR; PG8_SCHED;
	v_mfma_f32_16x16x32_bf16 v[28:31], v[214:217], v[144:147], v[28:31]
	v_mfma_f32_16x16x32_bf16 v[24:27], v[234:237], v[144:147], v[24:27]
	v_mfma_f32_16x16x32_bf16 v[20:23], v[214:217], v[152:155], v[20:23]
	v_mfma_f32_16x16x32_bf16 v[16:19], v[234:237], v[152:155], v[16:19]
	v_mfma_f32_16x16x32_bf16 v[12:15], v[214:217], v[198:201], v[12:15]
	v_mfma_f32_16x16x32_bf16 v[8:11], v[234:237], v[198:201], v[8:11]
	v_mfma_f32_16x16x32_bf16 v[4:7], v[214:217], v[206:209], v[4:7]
	v_mfma_f32_16x16x32_bf16 v[0:3], v[234:237], v[206:209], v[0:3]
	v_mfma_f32_16x16x32_bf16 v[28:31], v[230:233], v[148:151], v[28:31]
	s_add_i32 s43, 0, 0x18000
	v_mfma_f32_16x16x32_bf16 v[24:27], v[238:241], v[148:151], v[24:27]
	v_mfma_f32_16x16x32_bf16 v[20:23], v[230:233], v[194:197], v[20:23]
	v_mfma_f32_16x16x32_bf16 v[16:19], v[238:241], v[194:197], v[16:19]
	v_mfma_f32_16x16x32_bf16 v[12:15], v[230:233], v[202:205], v[12:15]
	v_mfma_f32_16x16x32_bf16 v[8:11], v[238:241], v[202:205], v[8:11]
	v_mfma_f32_16x16x32_bf16 v[4:7], v[230:233], v[210:213], v[4:7]
	s_setprio 0
	v_mfma_f32_16x16x32_bf16 v[0:3], v[238:241], v[210:213], v[0:3]
	s_barrier
	ds_read_b128 v[128:131], v226 offset:32768
	ds_read_b128 v[132:135], v226 offset:33792
	ds_read_b128 v[136:139], v226 offset:34816
	ds_read_b128 v[140:143], v226 offset:35840
	ds_read_b128 v[144:147], v228 offset:32768
	ds_read_b128 v[148:151], v228 offset:33792
	ds_read_b128 v[152:155], v228 offset:34816
	ds_read_b128 v[194:197], v228 offset:35840
	ds_read_b128 v[198:201], v228 offset:36864
	ds_read_b128 v[202:205], v228 offset:37888
	ds_read_b128 v[206:209], v228 offset:38912
	ds_read_b128 v[210:213], v228 offset:39936
	s_add_u32 s20, s26, 0x90000
	s_addc_u32 s21, s27, 0
	s_mov_b32 m0, s36
	s_nop 0
	global_load_lds_dwordx4 v188, s[20:21]
	s_mov_b32 m0, s37
	s_nop 0
	global_load_lds_dwordx4 v186, s[20:21]
	s_waitcnt lgkmcnt(8)
	s_setprio 1
	s_barrier
	s_waitcnt lgkmcnt(0)
	v_mfma_f32_16x16x32_bf16 v[124:127], v[128:131], v[144:147], v[124:127]
	v_mfma_f32_16x16x32_bf16 v[120:123], v[136:139], v[144:147], v[120:123]
	v_mfma_f32_16x16x32_bf16 v[116:119], v[128:131], v[152:155], v[116:119]
	v_mfma_f32_16x16x32_bf16 v[112:115], v[136:139], v[152:155], v[112:115]
	v_mfma_f32_16x16x32_bf16 v[108:111], v[128:131], v[198:201], v[108:111]
	v_mfma_f32_16x16x32_bf16 v[104:107], v[136:139], v[198:201], v[104:107]
	v_mfma_f32_16x16x32_bf16 v[100:103], v[128:131], v[206:209], v[100:103]
	v_mfma_f32_16x16x32_bf16 v[96:99], v[136:139], v[206:209], v[96:99]
	v_mfma_f32_16x16x32_bf16 v[124:127], v[132:135], v[148:151], v[124:127]
	v_mfma_f32_16x16x32_bf16 v[120:123], v[140:143], v[148:151], v[120:123]
	v_mfma_f32_16x16x32_bf16 v[116:119], v[132:135], v[194:197], v[116:119]
	v_mfma_f32_16x16x32_bf16 v[112:115], v[140:143], v[194:197], v[112:115]
	v_mfma_f32_16x16x32_bf16 v[108:111], v[132:135], v[202:205], v[108:111]
	v_mfma_f32_16x16x32_bf16 v[104:107], v[140:143], v[202:205], v[104:107]
	v_mfma_f32_16x16x32_bf16 v[100:103], v[132:135], v[210:213], v[100:103]
	s_setprio 0
	v_mfma_f32_16x16x32_bf16 v[96:99], v[140:143], v[210:213], v[96:99]
	s_barrier
	ds_read_b128 v[214:217], v226 offset:49152
	ds_read_b128 v[230:233], v226 offset:50176
	ds_read_b128 v[234:237], v226 offset:51200
	ds_read_b128 v[238:241], v226 offset:52224
	s_add_i32 s26, 0, 0x1c000
	s_add_i32 s20, s43, s31
	s_add_i32 m0, s20, 0xffffff80
	s_nop 0
	global_load_lds_dwordx4 v188, s[24:25] offset:128
	s_add_i32 m0, s20, 0x1f80
	s_nop 0
	global_load_lds_dwordx4 v186, s[24:25] offset:128
	s_waitcnt lgkmcnt(0)
	s_setprio 1
	s_barrier
	v_mfma_f32_16x16x32_bf16 v[60:63], v[214:217], v[144:147], v[60:63]
	v_mfma_f32_16x16x32_bf16 v[56:59], v[234:237], v[144:147], v[56:59]
	v_mfma_f32_16x16x32_bf16 v[52:55], v[214:217], v[152:155], v[52:55]
	v_mfma_f32_16x16x32_bf16 v[48:51], v[234:237], v[152:155], v[48:51]
	v_mfma_f32_16x16x32_bf16 v[44:47], v[214:217], v[198:201], v[44:47]
	v_mfma_f32_16x16x32_bf16 v[40:43], v[234:237], v[198:201], v[40:43]
	v_mfma_f32_16x16x32_bf16 v[36:39], v[214:217], v[206:209], v[36:39]
	v_mfma_f32_16x16x32_bf16 v[32:35], v[234:237], v[206:209], v[32:35]
	v_mfma_f32_16x16x32_bf16 v[60:63], v[230:233], v[148:151], v[60:63]
	s_add_i32 m0, s38, 0xffffff80
	v_mfma_f32_16x16x32_bf16 v[56:59], v[238:241], v[148:151], v[56:59]
	v_mfma_f32_16x16x32_bf16 v[52:55], v[230:233], v[194:197], v[52:55]
	v_mfma_f32_16x16x32_bf16 v[48:51], v[238:241], v[194:197], v[48:51]
	v_mfma_f32_16x16x32_bf16 v[44:47], v[230:233], v[202:205], v[44:47]
	v_mfma_f32_16x16x32_bf16 v[40:43], v[238:241], v[202:205], v[40:43]
	v_mfma_f32_16x16x32_bf16 v[36:39], v[230:233], v[210:213], v[36:39]
	s_setprio 0
	v_mfma_f32_16x16x32_bf16 v[32:35], v[238:241], v[210:213], v[32:35]
	s_barrier
	ds_read_b128 v[144:147], v228 offset:49152
	ds_read_b128 v[148:151], v228 offset:50176
	ds_read_b128 v[152:155], v228 offset:51200
	ds_read_b128 v[194:197], v228 offset:52224
	ds_read_b128 v[198:201], v228 offset:53248
	ds_read_b128 v[202:205], v228 offset:54272
	ds_read_b128 v[206:209], v228 offset:55296
	ds_read_b128 v[210:213], v228 offset:56320
	global_load_lds_dwordx4 v188, s[100:101] offset:128
	s_add_i32 m0, s39, 0xffffff80
	s_nop 0
	global_load_lds_dwordx4 v186, s[100:101] offset:128
	s_waitcnt lgkmcnt(0)
	s_setprio 1
	s_barrier
; #define PG8_BAR __builtin_amdgcn_s_barrier()
; template <class Epi>
; DI void gemm_phase(LAS unsigned char* lds, const Gemm g, const StaticOrder& S, const Epi& E) {
;     ...
;             PG8_BAR; PG8_WAIT_L(0); PG8_MMA(1, 0, At, B0); PG8_BAR; PG8_SCHED;
;             PG8_STAGE(PG8_SB(1, 1), b3 + hstep);
;             PG8_WAIT_V(6); PG8_BAR; PG8_MMA(1, 1, At, B1); PG8_BAR;
;     template <bool LN, int BJ, int LO, int HI> DI void batch(const f32x4 (&acc)[2][2][4][2], unsigned row0, unsigned col0, const f32x4 (&gv)[2], const f32x4 (&bv)[2]) const {
;         f32x4 r[HI - LO]; float mean[(HI - LO) / 2], rstd[(HI - LO) / 2];
; #pragma unroll
;         for (int i = LO; i < HI; ++i) { const int ai = i >> 3, m = (i >> 1) & 3, n = i & 1; const unsigned row = row0 + ai * HALF + m * 16;
;             if (n == 0) { mean[(i - LO) >> 1] = 0.f; rstd[(i - LO) >> 1] = 1.f;
;                 if (LN) { const float2 st = *(const float2*)(stats + row * 2u); mean[(i - LO) >> 1] = st.x; rstd[(i - LO) >> 1] = st.y; } }
;             r[i - LO] = *(const f32x4*)(src + (row * (unsigned)DM + col0 + BJ * HALF + n * 16)); }
; #pragma unroll
;         for (int i = LO; i < HI; ++i) { const int ai = i >> 3, m = (i >> 1) & 3, n = i & 1; const unsigned row = row0 + ai * HALF + m * 16;
;             *(f32x4*)(Y + (row * (unsigned)DM + col0 + BJ * HALF + n * 16)) = acc[ai][BJ][m][n] + ((r[i - LO] - mean[(i - LO) >> 1]) * rstd[(i - LO) >> 1]) * gv[n] + bv[n]; }
;         __builtin_amdgcn_sched_barrier(0);
;     }
;     template <bool LN, int BJ> DI void load_gb(unsigned col0, f32x4 (&gv)[2], f32x4 (&bv)[2]) const {
; #pragma unroll
;         for (int n = 0; n < 2; ++n) {
;             if (LN) { gv[n] = *(const f32x4*)(gam + col0 + BJ * HALF + n * 16) * ALPHA; bv[n] = *(const f32x4*)(bet + col0 + BJ * HALF + n * 16) * ALPHA; }
;             else { gv[n] = (f32x4){ALPHA, ALPHA, ALPHA, ALPHA}; bv[n] = (f32x4){0.f, 0.f, 0.f, 0.f}; }
;         }
;     }
;     template <bool LN> DI void run(const f32x4 (&acc)[2][2][4][2], const Unit& u, int wr, int wc, int fr, int fq) const {
;         const unsigned row0 = u.pm * BM + wr * 64 + fr, col0 = u.pn * BM + wc * 32 + 4 * fq;
;         f32x4 gv[2], bv[2];
;         load_gb<LN, 0>(col0, gv, bv);
;         batch<LN, 0, 0, 4>(acc, row0, col0, gv, bv);
;         batch<LN, 0, 4, 8>(acc, row0, col0, gv, bv);
;         batch<LN, 0, 8, 12>(acc, row0, col0, gv, bv);
	v_mfma_f32_16x16x32_bf16 v[92:95], v[128:131], v[144:147], v[92:95]
	v_mfma_f32_16x16x32_bf16 v[88:91], v[136:139], v[144:147], v[88:91]
	v_mfma_f32_16x16x32_bf16 v[84:87], v[128:131], v[152:155], v[84:87]
	v_mfma_f32_16x16x32_bf16 v[80:83], v[136:139], v[152:155], v[80:83]
	v_mfma_f32_16x16x32_bf16 v[76:79], v[128:131], v[198:201], v[76:79]
	v_mfma_f32_16x16x32_bf16 v[72:75], v[136:139], v[198:201], v[72:75]
	v_mfma_f32_16x16x32_bf16 v[68:71], v[128:131], v[206:209], v[68:71]
	v_mfma_f32_16x16x32_bf16 v[64:67], v[136:139], v[206:209], v[64:67]
	v_mfma_f32_16x16x32_bf16 v[92:95], v[132:135], v[148:151], v[92:95]
	v_mfma_f32_16x16x32_bf16 v[88:91], v[140:143], v[148:151], v[88:91]
	v_mfma_f32_16x16x32_bf16 v[84:87], v[132:135], v[194:197], v[84:87]
	v_mfma_f32_16x16x32_bf16 v[80:83], v[140:143], v[194:197], v[80:83]
	v_mfma_f32_16x16x32_bf16 v[76:79], v[132:135], v[202:205], v[76:79]
	v_mfma_f32_16x16x32_bf16 v[72:75], v[140:143], v[202:205], v[72:75]
	v_mfma_f32_16x16x32_bf16 v[68:71], v[132:135], v[210:213], v[68:71]
	s_setprio 0
	v_mfma_f32_16x16x32_bf16 v[64:67], v[140:143], v[210:213], v[64:67]
	s_barrier
	s_add_u32 s20, s24, 0x90080
	s_addc_u32 s21, s25, 0
	s_add_i32 s24, s26, s31
	s_mov_b32 m0, s24
	s_nop 0
	global_load_lds_dwordx4 v188, s[20:21]
	s_add_i32 m0, s24, 0x2000
	s_nop 0
	global_load_lds_dwordx4 v186, s[20:21]
	s_waitcnt vmcnt(6)
	s_setprio 1
	s_barrier
	v_mfma_f32_16x16x32_bf16 v[28:31], v[214:217], v[144:147], v[28:31]
	v_mfma_f32_16x16x32_bf16 v[24:27], v[234:237], v[144:147], v[24:27]
	v_mfma_f32_16x16x32_bf16 v[20:23], v[214:217], v[152:155], v[20:23]
	v_mfma_f32_16x16x32_bf16 v[16:19], v[234:237], v[152:155], v[16:19]
	v_mfma_f32_16x16x32_bf16 v[12:15], v[214:217], v[198:201], v[12:15]
	v_mfma_f32_16x16x32_bf16 v[8:11], v[234:237], v[198:201], v[8:11]
	v_mfma_f32_16x16x32_bf16 v[4:7], v[214:217], v[206:209], v[4:7]
	v_mfma_f32_16x16x32_bf16 v[0:3], v[234:237], v[206:209], v[0:3]
	v_mfma_f32_16x16x32_bf16 v[28:31], v[230:233], v[148:151], v[28:31]
	s_add_i32 s33, s33, 2
	v_mfma_f32_16x16x32_bf16 v[24:27], v[238:241], v[148:151], v[24:27]
	s_add_u32 s4, s4, 0x100
	v_mfma_f32_16x16x32_bf16 v[20:23], v[230:233], v[194:197], v[20:23]
	s_addc_u32 s5, s5, 0
	v_mfma_f32_16x16x32_bf16 v[16:19], v[238:241], v[194:197], v[16:19]
	s_cmp_gt_u32 s33, 33
	v_mfma_f32_16x16x32_bf16 v[12:15], v[230:233], v[202:205], v[12:15]
	s_mov_b64 s[20:21], s[22:23]
	v_mfma_f32_16x16x32_bf16 v[8:11], v[238:241], v[202:205], v[8:11]
	v_mfma_f32_16x16x32_bf16 v[4:7], v[230:233], v[210:213], v[4:7]
	s_setprio 0
	v_mfma_f32_16x16x32_bf16 v[0:3], v[238:241], v[210:213], v[0:3]
	s_barrier
	s_cbranch_scc0 .LBB0_77
	v_lshl_add_u32 v206, s3, 8, v225
	v_lshl_or_b32 v158, s2, 8, v227
	v_lshlrev_b32_e32 v232, 11, v206
	s_andn2_b64 vcc, exec, s[14:15]
	v_or_b32_e32 v231, 16, v158
	v_add_u32_e32 v194, v232, v158
	v_or_b32_e32 v230, 0x80, v158
	v_or_b32_e32 v229, 0x90, v158
	s_cbranch_vccnz .LBB0_80
	v_lshlrev_b64 v[132:133], 2, v[158:159]
	v_lshl_add_u64 v[140:141], s[16:17], 0, v[132:133]
	global_load_dwordx4 v[128:131], v[140:141], off
	v_lshl_add_u64 v[142:143], s[18:19], 0, v[132:133]
	v_readlane_b32 s2, v253, 8
	v_mov_b32_e32 v195, v159
	v_lshlrev_b32_e32 v136, 1, v206
	v_mov_b32_e32 v137, v159
	v_readlane_b32 s3, v253, 9
	v_lshlrev_b64 v[212:213], 2, v[194:195]
	v_add_u32_e32 v146, v232, v231
	v_lshl_add_u64 v[144:145], v[136:137], 2, s[2:3]
	v_lshl_add_u64 v[136:137], s[88:89], 0, v[212:213]
	v_mov_b32_e32 v147, v159
	v_lshl_add_u64 v[146:147], v[146:147], 2, s[88:89]
	v_or_b32_e32 v195, 16, v206
	v_mov_b32_e32 v201, v159
	v_mov_b32_e32 v209, v159
	v_lshl_add_u64 v[212:213], s[90:91], 0, v[212:213]
	s_waitcnt vmcnt(0)
	v_pk_mul_f32 v[152:153], v[130:131], s[78:79] op_sel_hi:[1,0]
	v_pk_mul_f32 v[154:155], v[128:129], s[78:79] op_sel_hi:[1,0]
	global_load_dwordx4 v[132:135], v[142:143], off
	global_load_dwordx4 v[128:131], v[140:141], off offset:64
	global_load_dwordx2 v[204:205], v[144:145], off
	global_load_dwordx4 v[196:199], v[146:147], off
	v_lshlrev_b32_e32 v146, 1, v195
	global_load_dwordx4 v[136:139], v[136:137], off
	v_lshlrev_b32_e32 v195, 11, v195
	v_mov_b32_e32 v147, v159
	v_add_u32_e32 v200, v195, v158
	v_lshl_add_u64 v[146:147], v[146:147], 2, s[2:3]
	v_lshl_add_u64 v[200:201], v[200:201], 2, s[88:89]
	global_load_dwordx2 v[214:215], v[146:147], off
	v_add_u32_e32 v208, v195, v231
	global_load_dwordx4 v[200:203], v[200:201], off
	v_lshl_add_u64 v[208:209], v[208:209], 2, s[88:89]
	global_load_dwordx4 v[208:211], v[208:209], off
	s_waitcnt vmcnt(0)
	v_pk_mul_f32 v[148:149], v[130:131], s[78:79] op_sel_hi:[1,0]
	v_pk_mul_f32 v[150:151], v[128:129], s[78:79] op_sel_hi:[1,0]
	global_load_dwordx4 v[128:131], v[142:143], off offset:64
	v_sub_f32_e32 v137, v137, v204
	v_sub_f32_e32 v136, v136, v204
	v_sub_f32_e32 v139, v139, v204
	v_sub_f32_e32 v138, v138, v204
	v_pk_mul_f32 v[138:139], v[204:205], v[138:139] op_sel:[1,0]
	v_pk_mul_f32 v[136:137], v[204:205], v[136:137] op_sel:[1,0]
	v_pk_fma_f32 v[138:139], v[152:153], v[138:139], v[126:127]
	v_pk_fma_f32 v[136:137], v[154:155], v[136:137], v[124:125]
	v_pk_fma_f32 v[138:139], v[134:135], s[78:79], v[138:139] op_sel_hi:[1,0,1]
	v_pk_fma_f32 v[136:137], v[132:133], s[78:79], v[136:137] op_sel_hi:[1,0,1]
	global_store_dwordx4 v[212:213], v[136:139], off
	s_nop 1
	v_sub_f32_e32 v137, v197, v204
	v_sub_f32_e32 v136, v196, v204
	v_sub_f32_e32 v139, v199, v204
	v_sub_f32_e32 v138, v198, v204
	v_pk_mul_f32 v[138:139], v[204:205], v[138:139] op_sel:[1,0]
	v_pk_mul_f32 v[136:137], v[204:205], v[136:137] op_sel:[1,0]
	v_pk_fma_f32 v[138:139], v[148:149], v[138:139], v[122:123]
	v_pk_fma_f32 v[136:137], v[150:151], v[136:137], v[120:121]
	v_or_b32_e32 v196, 16, v194
	v_mov_b32_e32 v197, v159
	v_lshl_add_u64 v[196:197], v[196:197], 2, s[90:91]
	s_waitcnt vmcnt(0)
;     template <bool LN, int BJ, int LO, int HI> DI void batch(const f32x4 (&acc)[2][2][4][2], unsigned row0, unsigned col0, const f32x4 (&gv)[2], const f32x4 (&bv)[2]) const {
;         f32x4 r[HI - LO]; float mean[(HI - LO) / 2], rstd[(HI - LO) / 2];
; #pragma unroll
;         for (int i = LO; i < HI; ++i) { const int ai = i >> 3, m = (i >> 1) & 3, n = i & 1; const unsigned row = row0 + ai * HALF + m * 16;
;             if (n == 0) { mean[(i - LO) >> 1] = 0.f; rstd[(i - LO) >> 1] = 1.f;
;                 if (LN) { const float2 st = *(const float2*)(stats + row * 2u); mean[(i - LO) >> 1] = st.x; rstd[(i - LO) >> 1] = st.y; } }
;             r[i - LO] = *(const f32x4*)(src + (row * (unsigned)DM + col0 + BJ * HALF + n * 16)); }
; #pragma unroll
;         for (int i = LO; i < HI; ++i) { const int ai = i >> 3, m = (i >> 1) & 3, n = i & 1; const unsigned row = row0 + ai * HALF + m * 16;
;             *(f32x4*)(Y + (row * (unsigned)DM + col0 + BJ * HALF + n * 16)) = acc[ai][BJ][m][n] + ((r[i - LO] - mean[(i - LO) >> 1]) * rstd[(i - LO) >> 1]) * gv[n] + bv[n]; }
	v_pk_fma_f32 v[138:139], v[130:131], s[78:79], v[138:139] op_sel_hi:[1,0,1]
	v_pk_fma_f32 v[136:137], v[128:129], s[78:79], v[136:137] op_sel_hi:[1,0,1]
	global_store_dwordx4 v[196:197], v[136:139], off
	v_add_u32_e32 v196, 0x8000, v194
	v_mov_b32_e32 v197, v159
	v_sub_f32_e32 v137, v201, v214
	v_sub_f32_e32 v136, v200, v214
	v_sub_f32_e32 v139, v203, v214
	v_sub_f32_e32 v138, v202, v214
	v_pk_mul_f32 v[138:139], v[214:215], v[138:139] op_sel:[1,0]
	v_pk_mul_f32 v[136:137], v[214:215], v[136:137] op_sel:[1,0]
	v_pk_fma_f32 v[138:139], v[152:153], v[138:139], v[118:119]
	v_pk_fma_f32 v[136:137], v[154:155], v[136:137], v[116:117]
	v_pk_fma_f32 v[138:139], v[134:135], s[78:79], v[138:139] op_sel_hi:[1,0,1]
	v_pk_fma_f32 v[136:137], v[132:133], s[78:79], v[136:137] op_sel_hi:[1,0,1]
	v_lshl_add_u64 v[196:197], v[196:197], 2, s[90:91]
	global_store_dwordx4 v[196:197], v[136:139], off
	v_add_u32_e32 v196, 0x8010, v194
	v_mov_b32_e32 v197, v159
	v_sub_f32_e32 v137, v209, v214
	v_sub_f32_e32 v136, v208, v214
	v_sub_f32_e32 v139, v211, v214
	v_sub_f32_e32 v138, v210, v214
	v_pk_mul_f32 v[138:139], v[214:215], v[138:139] op_sel:[1,0]
	v_pk_mul_f32 v[136:137], v[214:215], v[136:137] op_sel:[1,0]
	v_pk_fma_f32 v[138:139], v[148:149], v[138:139], v[114:115]
	v_pk_fma_f32 v[136:137], v[150:151], v[136:137], v[112:113]
	v_pk_fma_f32 v[138:139], v[130:131], s[78:79], v[138:139] op_sel_hi:[1,0,1]
	v_pk_fma_f32 v[136:137], v[128:129], s[78:79], v[136:137] op_sel_hi:[1,0,1]
	v_lshl_add_u64 v[196:197], v[196:197], 2, s[90:91]
	global_store_dwordx4 v[196:197], v[136:139], off
	s_nop 1
	v_or_b32_e32 v138, 32, v206
	v_lshlrev_b32_e32 v136, 1, v138
	v_mov_b32_e32 v137, v159
	v_lshlrev_b32_e32 v236, 11, v138
	v_lshl_add_u64 v[200:201], v[136:137], 2, s[2:3]
	v_add_u32_e32 v136, v236, v158
	v_lshl_add_u64 v[136:137], v[136:137], 2, s[88:89]
	global_load_dwordx2 v[204:205], v[200:201], off
	v_add_u32_e32 v196, v236, v231
	global_load_dwordx4 v[136:139], v[136:137], off
	v_mov_b32_e32 v197, v159
	v_lshl_add_u64 v[196:197], v[196:197], 2, s[88:89]
	global_load_dwordx4 v[196:199], v[196:197], off
	v_or_b32_e32 v207, 48, v206
	v_lshlrev_b32_e32 v235, 11, v207
	v_lshlrev_b32_e32 v202, 1, v207
	v_mov_b32_e32 v203, v159
	v_add_u32_e32 v208, v235, v158
	v_mov_b32_e32 v209, v159
	v_lshl_add_u64 v[202:203], v[202:203], 2, s[2:3]
	v_lshl_add_u64 v[208:209], v[208:209], 2, s[88:89]
	global_load_dwordx2 v[216:217], v[202:203], off
	v_add_u32_e32 v212, v235, v231
	global_load_dwordx4 v[208:211], v[208:209], off
	v_mov_b32_e32 v213, v159
	v_lshl_add_u64 v[212:213], v[212:213], 2, s[88:89]
	global_load_dwordx4 v[212:215], v[212:213], off
	v_add_u32_e32 v218, 0x10000, v194
	v_mov_b32_e32 v219, v159
	v_lshl_add_u64 v[218:219], v[218:219], 2, s[90:91]
	s_waitcnt vmcnt(0)
	v_sub_f32_e32 v137, v137, v204
	v_sub_f32_e32 v136, v136, v204
	v_sub_f32_e32 v139, v139, v204
	v_sub_f32_e32 v138, v138, v204
	v_pk_mul_f32 v[138:139], v[204:205], v[138:139] op_sel:[1,0]
	v_pk_mul_f32 v[136:137], v[204:205], v[136:137] op_sel:[1,0]
	v_pk_fma_f32 v[138:139], v[152:153], v[138:139], v[110:111]
	v_pk_fma_f32 v[136:137], v[154:155], v[136:137], v[108:109]
	v_pk_fma_f32 v[138:139], v[134:135], s[78:79], v[138:139] op_sel_hi:[1,0,1]
	v_pk_fma_f32 v[136:137], v[132:133], s[78:79], v[136:137] op_sel_hi:[1,0,1]
	global_store_dwordx4 v[218:219], v[136:139], off
	s_nop 1
	v_sub_f32_e32 v137, v197, v204
	v_sub_f32_e32 v136, v196, v204
	v_sub_f32_e32 v139, v199, v204
	v_sub_f32_e32 v138, v198, v204
	v_pk_mul_f32 v[138:139], v[204:205], v[138:139] op_sel:[1,0]
	v_pk_mul_f32 v[136:137], v[204:205], v[136:137] op_sel:[1,0]
	v_pk_fma_f32 v[138:139], v[148:149], v[138:139], v[106:107]
	v_pk_fma_f32 v[136:137], v[150:151], v[136:137], v[104:105]
	v_add_u32_e32 v196, 0x10010, v194
	v_mov_b32_e32 v197, v159
	v_pk_fma_f32 v[138:139], v[130:131], s[78:79], v[138:139] op_sel_hi:[1,0,1]
	v_pk_fma_f32 v[136:137], v[128:129], s[78:79], v[136:137] op_sel_hi:[1,0,1]
	v_lshl_add_u64 v[196:197], v[196:197], 2, s[90:91]
	global_store_dwordx4 v[196:197], v[136:139], off
	v_add_u32_e32 v196, 0x18000, v194
	v_mov_b32_e32 v197, v159
	v_sub_f32_e32 v137, v209, v216
	v_sub_f32_e32 v136, v208, v216
	v_sub_f32_e32 v139, v211, v216
	v_sub_f32_e32 v138, v210, v216
	v_pk_mul_f32 v[138:139], v[216:217], v[138:139] op_sel:[1,0]
	v_pk_mul_f32 v[136:137], v[216:217], v[136:137] op_sel:[1,0]
	v_pk_fma_f32 v[138:139], v[152:153], v[138:139], v[102:103]
	v_pk_fma_f32 v[136:137], v[154:155], v[136:137], v[100:101]
	v_pk_fma_f32 v[138:139], v[134:135], s[78:79], v[138:139] op_sel_hi:[1,0,1]
	v_pk_fma_f32 v[136:137], v[132:133], s[78:79], v[136:137] op_sel_hi:[1,0,1]
	v_lshl_add_u64 v[196:197], v[196:197], 2, s[90:91]
	global_store_dwordx4 v[196:197], v[136:139], off
	v_add_u32_e32 v196, 0x18010, v194
	v_mov_b32_e32 v197, v159
	v_sub_f32_e32 v137, v213, v216
	v_sub_f32_e32 v136, v212, v216
	v_sub_f32_e32 v139, v215, v216
	v_sub_f32_e32 v138, v214, v216
	v_pk_mul_f32 v[138:139], v[216:217], v[138:139] op_sel:[1,0]
	v_pk_mul_f32 v[136:137], v[216:217], v[136:137] op_sel:[1,0]
	v_pk_fma_f32 v[138:139], v[148:149], v[138:139], v[98:99]
	v_pk_fma_f32 v[136:137], v[150:151], v[136:137], v[96:97]
	v_pk_fma_f32 v[138:139], v[130:131], s[78:79], v[138:139] op_sel_hi:[1,0,1]
	v_pk_fma_f32 v[136:137], v[128:129], s[78:79], v[136:137] op_sel_hi:[1,0,1]
	v_lshl_add_u64 v[196:197], v[196:197], 2, s[90:91]
	global_store_dwordx4 v[196:197], v[136:139], off
	s_nop 1
	v_add_u32_e32 v138, 0x80, v206
	v_lshlrev_b32_e32 v136, 1, v138
	v_mov_b32_e32 v137, v159
	v_lshlrev_b32_e32 v233, 11, v138
	v_lshl_add_u64 v[196:197], v[136:137], 2, s[2:3]
	v_add_u32_e32 v136, v233, v158
	v_lshl_add_u64 v[136:137], v[136:137], 2, s[88:89]
	global_load_dwordx2 v[204:205], v[196:197], off
	v_add_u32_e32 v198, v233, v231
	global_load_dwordx4 v[136:139], v[136:137], off
	v_mov_b32_e32 v199, v159
	v_add_u32_e32 v207, 0x90, v206
	v_lshl_add_u64 v[198:199], v[198:199], 2, s[88:89]
	v_lshlrev_b32_e32 v234, 11, v207
	global_load_dwordx4 v[208:211], v[198:199], off
	v_add_u32_e32 v212, v234, v158
	v_mov_b32_e32 v213, v159
	v_lshl_add_u64 v[212:213], v[212:213], 2, s[88:89]
	global_load_dwordx4 v[212:215], v[212:213], off
	v_lshlrev_b32_e32 v198, 1, v207
	v_mov_b32_e32 v199, v159
	v_lshl_add_u64 v[198:199], v[198:199], 2, s[2:3]
	global_load_dwordx2 v[220:221], v[198:199], off
	v_add_u32_e32 v216, v234, v231
	v_mov_b32_e32 v217, v159
	v_lshl_add_u64 v[216:217], v[216:217], 2, s[88:89]
	global_load_dwordx4 v[216:219], v[216:217], off
	v_add_u32_e32 v238, 0x40000, v194
	v_mov_b32_e32 v239, v159
	v_lshl_add_u64 v[238:239], v[238:239], 2, s[90:91]
	s_waitcnt vmcnt(0)
;     template <bool LN, int BJ, int LO, int HI> DI void batch(const f32x4 (&acc)[2][2][4][2], unsigned row0, unsigned col0, const f32x4 (&gv)[2], const f32x4 (&bv)[2]) const {
;         f32x4 r[HI - LO]; float mean[(HI - LO) / 2], rstd[(HI - LO) / 2];
; #pragma unroll
;         for (int i = LO; i < HI; ++i) { const int ai = i >> 3, m = (i >> 1) & 3, n = i & 1; const unsigned row = row0 + ai * HALF + m * 16;
;             if (n == 0) { mean[(i - LO) >> 1] = 0.f; rstd[(i - LO) >> 1] = 1.f;
;                 if (LN) { const float2 st = *(const float2*)(stats + row * 2u); mean[(i - LO) >> 1] = st.x; rstd[(i - LO) >> 1] = st.y; } }
;             r[i - LO] = *(const f32x4*)(src + (row * (unsigned)DM + col0 + BJ * HALF + n * 16)); }
; #pragma unroll
;         for (int i = LO; i < HI; ++i) { const int ai = i >> 3, m = (i >> 1) & 3, n = i & 1; const unsigned row = row0 + ai * HALF + m * 16;
;             *(f32x4*)(Y + (row * (unsigned)DM + col0 + BJ * HALF + n * 16)) = acc[ai][BJ][m][n] + ((r[i - LO] - mean[(i - LO) >> 1]) * rstd[(i - LO) >> 1]) * gv[n] + bv[n]; }
;     template <bool LN, int BJ> DI void load_gb(unsigned col0, f32x4 (&gv)[2], f32x4 (&bv)[2]) const {
; #pragma unroll
;         for (int n = 0; n < 2; ++n) {
;             if (LN) { gv[n] = *(const f32x4*)(gam + col0 + BJ * HALF + n * 16) * ALPHA; bv[n] = *(const f32x4*)(bet + col0 + BJ * HALF + n * 16) * ALPHA; }
;             else { gv[n] = (f32x4){ALPHA, ALPHA, ALPHA, ALPHA}; bv[n] = (f32x4){0.f, 0.f, 0.f, 0.f}; }
;         }
	v_sub_f32_e32 v137, v137, v204
	v_sub_f32_e32 v136, v136, v204
	v_sub_f32_e32 v139, v139, v204
	v_sub_f32_e32 v138, v138, v204
	v_pk_mul_f32 v[138:139], v[204:205], v[138:139] op_sel:[1,0]
	v_pk_mul_f32 v[136:137], v[204:205], v[136:137] op_sel:[1,0]
	v_pk_fma_f32 v[138:139], v[152:153], v[138:139], v[94:95]
	v_pk_fma_f32 v[136:137], v[154:155], v[136:137], v[92:93]
	v_pk_fma_f32 v[138:139], v[134:135], s[78:79], v[138:139] op_sel_hi:[1,0,1]
	v_pk_fma_f32 v[136:137], v[132:133], s[78:79], v[136:137] op_sel_hi:[1,0,1]
	global_store_dwordx4 v[238:239], v[136:139], off
	s_nop 1
	v_sub_f32_e32 v137, v209, v204
	v_sub_f32_e32 v136, v208, v204
	v_sub_f32_e32 v139, v211, v204
	v_sub_f32_e32 v138, v210, v204
	v_pk_mul_f32 v[138:139], v[204:205], v[138:139] op_sel:[1,0]
	v_pk_mul_f32 v[136:137], v[204:205], v[136:137] op_sel:[1,0]
	v_pk_fma_f32 v[138:139], v[148:149], v[138:139], v[90:91]
	v_pk_fma_f32 v[136:137], v[150:151], v[136:137], v[88:89]
	v_add_u32_e32 v204, 0x40010, v194
	v_mov_b32_e32 v205, v159
	v_pk_fma_f32 v[138:139], v[130:131], s[78:79], v[138:139] op_sel_hi:[1,0,1]
	v_pk_fma_f32 v[136:137], v[128:129], s[78:79], v[136:137] op_sel_hi:[1,0,1]
	v_lshl_add_u64 v[204:205], v[204:205], 2, s[90:91]
	global_store_dwordx4 v[204:205], v[136:139], off
	v_add_u32_e32 v204, 0x48000, v194
	v_mov_b32_e32 v205, v159
	v_sub_f32_e32 v137, v213, v220
	v_sub_f32_e32 v136, v212, v220
	v_sub_f32_e32 v139, v215, v220
	v_sub_f32_e32 v138, v214, v220
	v_pk_mul_f32 v[138:139], v[220:221], v[138:139] op_sel:[1,0]
	v_pk_mul_f32 v[136:137], v[220:221], v[136:137] op_sel:[1,0]
	v_pk_fma_f32 v[138:139], v[152:153], v[138:139], v[86:87]
	v_pk_fma_f32 v[136:137], v[154:155], v[136:137], v[84:85]
	v_pk_fma_f32 v[138:139], v[134:135], s[78:79], v[138:139] op_sel_hi:[1,0,1]
	v_pk_fma_f32 v[136:137], v[132:133], s[78:79], v[136:137] op_sel_hi:[1,0,1]
	v_lshl_add_u64 v[204:205], v[204:205], 2, s[90:91]
	global_store_dwordx4 v[204:205], v[136:139], off
	v_add_u32_e32 v204, 0x48010, v194
	v_mov_b32_e32 v205, v159
	v_sub_f32_e32 v137, v217, v220
	v_sub_f32_e32 v136, v216, v220
	v_sub_f32_e32 v139, v219, v220
	v_sub_f32_e32 v138, v218, v220
	v_pk_mul_f32 v[138:139], v[220:221], v[138:139] op_sel:[1,0]
	v_pk_mul_f32 v[136:137], v[220:221], v[136:137] op_sel:[1,0]
	v_pk_fma_f32 v[138:139], v[148:149], v[138:139], v[82:83]
	v_pk_fma_f32 v[136:137], v[150:151], v[136:137], v[80:81]
	v_pk_fma_f32 v[138:139], v[130:131], s[78:79], v[138:139] op_sel_hi:[1,0,1]
	v_pk_fma_f32 v[136:137], v[128:129], s[78:79], v[136:137] op_sel_hi:[1,0,1]
	v_lshl_add_u64 v[204:205], v[204:205], 2, s[90:91]
	global_store_dwordx4 v[204:205], v[136:139], off
	s_nop 1
	v_add_u32_e32 v138, 0xa0, v206
	v_lshlrev_b32_e32 v136, 1, v138
	v_mov_b32_e32 v137, v159
	v_lshlrev_b32_e32 v237, 11, v138
	v_lshl_add_u64 v[204:205], v[136:137], 2, s[2:3]
	v_add_u32_e32 v136, v237, v158
	v_lshl_add_u64 v[136:137], v[136:137], 2, s[88:89]
	global_load_dwordx2 v[220:221], v[204:205], off
	v_add_u32_e32 v208, v237, v231
	global_load_dwordx4 v[136:139], v[136:137], off
	v_mov_b32_e32 v209, v159
	v_lshl_add_u64 v[208:209], v[208:209], 2, s[88:89]
	global_load_dwordx4 v[212:215], v[208:209], off
	v_add_u32_e32 v208, 0xb0, v206
	v_lshlrev_b32_e32 v206, 1, v208
	v_mov_b32_e32 v207, v159
	v_lshlrev_b32_e32 v238, 11, v208
	v_lshl_add_u64 v[210:211], v[206:207], 2, s[2:3]
	v_add_u32_e32 v206, v238, v158
	v_lshl_add_u64 v[206:207], v[206:207], 2, s[88:89]
	global_load_dwordx2 v[240:241], v[210:211], off
	v_add_u32_e32 v216, v238, v231
	global_load_dwordx4 v[206:209], v[206:207], off
	v_mov_b32_e32 v217, v159
	v_lshl_add_u64 v[216:217], v[216:217], 2, s[88:89]
	global_load_dwordx4 v[216:219], v[216:217], off
	v_add_u32_e32 v242, 0x50000, v194
	v_mov_b32_e32 v243, v159
	v_lshl_add_u64 v[242:243], v[242:243], 2, s[90:91]
	s_waitcnt vmcnt(0)
	v_sub_f32_e32 v137, v137, v220
	v_sub_f32_e32 v136, v136, v220
	v_sub_f32_e32 v139, v139, v220
	v_sub_f32_e32 v138, v138, v220
	v_pk_mul_f32 v[138:139], v[220:221], v[138:139] op_sel:[1,0]
	v_pk_mul_f32 v[136:137], v[220:221], v[136:137] op_sel:[1,0]
	v_pk_fma_f32 v[138:139], v[152:153], v[138:139], v[78:79]
	v_pk_fma_f32 v[136:137], v[154:155], v[136:137], v[76:77]
	v_pk_fma_f32 v[138:139], v[134:135], s[78:79], v[138:139] op_sel_hi:[1,0,1]
	v_pk_fma_f32 v[136:137], v[132:133], s[78:79], v[136:137] op_sel_hi:[1,0,1]
	global_store_dwordx4 v[242:243], v[136:139], off
	s_nop 1
	v_sub_f32_e32 v137, v213, v220
	v_sub_f32_e32 v136, v212, v220
	v_sub_f32_e32 v139, v215, v220
	v_sub_f32_e32 v138, v214, v220
	v_pk_mul_f32 v[138:139], v[220:221], v[138:139] op_sel:[1,0]
	v_pk_mul_f32 v[136:137], v[220:221], v[136:137] op_sel:[1,0]
	v_pk_fma_f32 v[138:139], v[148:149], v[138:139], v[74:75]
	v_pk_fma_f32 v[136:137], v[150:151], v[136:137], v[72:73]
	v_add_u32_e32 v212, 0x50010, v194
	v_mov_b32_e32 v213, v159
	v_pk_fma_f32 v[138:139], v[130:131], s[78:79], v[138:139] op_sel_hi:[1,0,1]
	v_pk_fma_f32 v[136:137], v[128:129], s[78:79], v[136:137] op_sel_hi:[1,0,1]
	v_lshl_add_u64 v[212:213], v[212:213], 2, s[90:91]
	global_store_dwordx4 v[212:213], v[136:139], off
	s_nop 1
	v_sub_f32_e32 v137, v207, v240
	v_sub_f32_e32 v136, v206, v240
	v_sub_f32_e32 v139, v209, v240
	v_sub_f32_e32 v138, v208, v240
	v_pk_mul_f32 v[136:137], v[240:241], v[136:137] op_sel:[1,0]
	v_pk_mul_f32 v[138:139], v[240:241], v[138:139] op_sel:[1,0]
	v_pk_fma_f32 v[136:137], v[154:155], v[136:137], v[68:69]
	v_pk_fma_f32 v[138:139], v[152:153], v[138:139], v[70:71]
	v_pk_fma_f32 v[132:133], v[132:133], s[78:79], v[136:137] op_sel_hi:[1,0,1]
	v_add_u32_e32 v136, 0x58000, v194
	v_mov_b32_e32 v137, v159
	v_pk_fma_f32 v[134:135], v[134:135], s[78:79], v[138:139] op_sel_hi:[1,0,1]
	v_lshl_add_u64 v[136:137], v[136:137], 2, s[90:91]
	global_store_dwordx4 v[136:137], v[132:135], off
	s_nop 1
	v_sub_f32_e32 v133, v217, v240
	v_sub_f32_e32 v132, v216, v240
	v_sub_f32_e32 v135, v219, v240
	v_sub_f32_e32 v134, v218, v240
	v_pk_mul_f32 v[132:133], v[240:241], v[132:133] op_sel:[1,0]
	v_pk_mul_f32 v[134:135], v[240:241], v[134:135] op_sel:[1,0]
	v_pk_fma_f32 v[132:133], v[150:151], v[132:133], v[64:65]
	v_pk_fma_f32 v[134:135], v[148:149], v[134:135], v[66:67]
	v_pk_fma_f32 v[128:129], v[128:129], s[78:79], v[132:133] op_sel_hi:[1,0,1]
	v_add_u32_e32 v132, 0x58010, v194
	v_mov_b32_e32 v133, v159
	v_pk_fma_f32 v[130:131], v[130:131], s[78:79], v[134:135] op_sel_hi:[1,0,1]
	v_lshl_add_u64 v[132:133], v[132:133], 2, s[90:91]
	global_store_dwordx4 v[132:133], v[128:131], off
	global_load_dwordx4 v[128:131], v[140:141], off offset:512
	v_add_u32_e32 v136, v232, v230
	v_mov_b32_e32 v137, v159
	v_lshl_add_u64 v[136:137], v[136:137], 2, s[88:89]
	s_waitcnt vmcnt(0)
;     template <bool LN, int BJ, int LO, int HI> DI void batch(const f32x4 (&acc)[2][2][4][2], unsigned row0, unsigned col0, const f32x4 (&gv)[2], const f32x4 (&bv)[2]) const {
;         f32x4 r[HI - LO]; float mean[(HI - LO) / 2], rstd[(HI - LO) / 2];
; #pragma unroll
;         for (int i = LO; i < HI; ++i) { const int ai = i >> 3, m = (i >> 1) & 3, n = i & 1; const unsigned row = row0 + ai * HALF + m * 16;
;             if (n == 0) { mean[(i - LO) >> 1] = 0.f; rstd[(i - LO) >> 1] = 1.f;
;                 if (LN) { const float2 st = *(const float2*)(stats + row * 2u); mean[(i - LO) >> 1] = st.x; rstd[(i - LO) >> 1] = st.y; } }
;             r[i - LO] = *(const f32x4*)(src + (row * (unsigned)DM + col0 + BJ * HALF + n * 16)); }
; #pragma unroll
;         for (int i = LO; i < HI; ++i) { const int ai = i >> 3, m = (i >> 1) & 3, n = i & 1; const unsigned row = row0 + ai * HALF + m * 16;
;             *(f32x4*)(Y + (row * (unsigned)DM + col0 + BJ * HALF + n * 16)) = acc[ai][BJ][m][n] + ((r[i - LO] - mean[(i - LO) >> 1]) * rstd[(i - LO) >> 1]) * gv[n] + bv[n]; }
;     template <bool LN, int BJ> DI void load_gb(unsigned col0, f32x4 (&gv)[2], f32x4 (&bv)[2]) const {
; #pragma unroll
;         for (int n = 0; n < 2; ++n) {
;             if (LN) { gv[n] = *(const f32x4*)(gam + col0 + BJ * HALF + n * 16) * ALPHA; bv[n] = *(const f32x4*)(bet + col0 + BJ * HALF + n * 16) * ALPHA; }
;             else { gv[n] = (f32x4){ALPHA, ALPHA, ALPHA, ALPHA}; bv[n] = (f32x4){0.f, 0.f, 0.f, 0.f}; }
;         }
	v_pk_mul_f32 v[212:213], v[130:131], s[78:79] op_sel_hi:[1,0]
	v_pk_mul_f32 v[214:215], v[128:129], s[78:79] op_sel_hi:[1,0]
	global_load_dwordx4 v[132:135], v[142:143], off offset:512
	global_load_dwordx4 v[128:131], v[140:141], off offset:576
	s_waitcnt vmcnt(0)
	v_pk_mul_f32 v[206:207], v[130:131], s[78:79] op_sel_hi:[1,0]
	v_pk_mul_f32 v[208:209], v[128:129], s[78:79] op_sel_hi:[1,0]
	global_load_dwordx4 v[128:131], v[142:143], off offset:576
	global_load_dwordx2 v[220:221], v[144:145], off
	global_load_dwordx4 v[240:243], v[136:137], off
	v_add_u32_e32 v136, v232, v229
	v_mov_b32_e32 v137, v159
	v_lshl_add_u64 v[136:137], v[136:137], 2, s[88:89]
	global_load_dwordx4 v[244:247], v[136:137], off
	global_load_dwordx2 v[218:219], v[146:147], off
	v_add_u32_e32 v136, v195, v230
	v_mov_b32_e32 v137, v159
	v_lshl_add_u64 v[136:137], v[136:137], 2, s[88:89]
	global_load_dwordx4 v[248:251], v[136:137], off
	v_add_u32_e32 v136, v195, v229
	v_mov_b32_e32 v137, v159
	v_lshl_add_u64 v[136:137], v[136:137], 2, s[88:89]
	global_load_dwordx4 v[152:155], v[136:137], off
	global_load_dwordx2 v[216:217], v[200:201], off
	v_add_u32_e32 v136, v236, v230
	v_mov_b32_e32 v137, v159
	v_lshl_add_u64 v[136:137], v[136:137], 2, s[88:89]
	global_load_dwordx4 v[148:151], v[136:137], off
	v_add_u32_e32 v136, v236, v229
	v_mov_b32_e32 v137, v159
	v_lshl_add_u64 v[136:137], v[136:137], 2, s[88:89]
	global_load_dwordx4 v[144:147], v[136:137], off
	global_load_dwordx2 v[200:201], v[202:203], off
	v_add_u32_e32 v136, v235, v230
	v_mov_b32_e32 v137, v159
	v_lshl_add_u64 v[136:137], v[136:137], 2, s[88:89]
	global_load_dwordx4 v[140:143], v[136:137], off
	v_add_u32_e32 v136, v235, v229
	v_mov_b32_e32 v137, v159
	v_lshl_add_u64 v[136:137], v[136:137], 2, s[88:89]
	global_load_dwordx4 v[136:139], v[136:137], off
	v_add_u32_e32 v202, 0x80, v194
	v_mov_b32_e32 v203, v159
	v_lshl_add_u64 v[202:203], v[202:203], 2, s[90:91]
	s_waitcnt vmcnt(0)
	v_sub_f32_e32 v241, v241, v220
	v_sub_f32_e32 v240, v240, v220
	v_sub_f32_e32 v243, v243, v220
	v_sub_f32_e32 v242, v242, v220
	v_pk_mul_f32 v[242:243], v[220:221], v[242:243] op_sel:[1,0]
	v_pk_mul_f32 v[240:241], v[220:221], v[240:241] op_sel:[1,0]
	v_pk_fma_f32 v[242:243], v[212:213], v[242:243], v[62:63]
	v_pk_fma_f32 v[240:241], v[214:215], v[240:241], v[60:61]
	v_pk_fma_f32 v[242:243], v[134:135], s[78:79], v[242:243] op_sel_hi:[1,0,1]
	v_pk_fma_f32 v[240:241], v[132:133], s[78:79], v[240:241] op_sel_hi:[1,0,1]
	global_store_dwordx4 v[202:203], v[240:243], off
	v_sub_f32_e32 v203, v245, v220
	v_sub_f32_e32 v202, v244, v220
	v_sub_f32_e32 v241, v247, v220
	v_sub_f32_e32 v240, v246, v220
	v_pk_mul_f32 v[202:203], v[220:221], v[202:203] op_sel:[1,0]
	v_pk_mul_f32 v[240:241], v[220:221], v[240:241] op_sel:[1,0]
	v_pk_fma_f32 v[202:203], v[208:209], v[202:203], v[56:57]
	v_pk_fma_f32 v[220:221], v[206:207], v[240:241], v[58:59]
	v_pk_fma_f32 v[240:241], v[128:129], s[78:79], v[202:203] op_sel_hi:[1,0,1]
	v_add_u32_e32 v202, 0x90, v194
	v_mov_b32_e32 v203, v159
	v_pk_fma_f32 v[242:243], v[130:131], s[78:79], v[220:221] op_sel_hi:[1,0,1]
	v_lshl_add_u64 v[202:203], v[202:203], 2, s[90:91]
	global_store_dwordx4 v[202:203], v[240:243], off
	v_sub_f32_e32 v203, v249, v218
	v_sub_f32_e32 v202, v248, v218
	v_sub_f32_e32 v221, v251, v218
	v_sub_f32_e32 v220, v250, v218
	v_pk_mul_f32 v[202:203], v[218:219], v[202:203] op_sel:[1,0]
	v_pk_mul_f32 v[220:221], v[218:219], v[220:221] op_sel:[1,0]
	v_pk_fma_f32 v[202:203], v[214:215], v[202:203], v[52:53]
	v_pk_fma_f32 v[220:221], v[212:213], v[220:221], v[54:55]
	v_pk_fma_f32 v[240:241], v[132:133], s[78:79], v[202:203] op_sel_hi:[1,0,1]
	v_add_u32_e32 v202, 0x8080, v194
	v_mov_b32_e32 v203, v159
	v_sub_f32_e32 v153, v153, v218
	v_sub_f32_e32 v152, v152, v218
	v_sub_f32_e32 v155, v155, v218
	v_sub_f32_e32 v154, v154, v218
	v_pk_fma_f32 v[242:243], v[134:135], s[78:79], v[220:221] op_sel_hi:[1,0,1]
	v_lshl_add_u64 v[202:203], v[202:203], 2, s[90:91]
	v_pk_mul_f32 v[154:155], v[218:219], v[154:155] op_sel:[1,0]
	v_pk_mul_f32 v[152:153], v[218:219], v[152:153] op_sel:[1,0]
	global_store_dwordx4 v[202:203], v[240:243], off
	v_pk_fma_f32 v[152:153], v[208:209], v[152:153], v[48:49]
	v_pk_fma_f32 v[154:155], v[206:207], v[154:155], v[50:51]
	v_add_u32_e32 v202, 0x8090, v194
	v_mov_b32_e32 v203, v159
	v_sub_f32_e32 v149, v149, v216
	v_sub_f32_e32 v148, v148, v216
	v_sub_f32_e32 v151, v151, v216
	v_sub_f32_e32 v150, v150, v216
	v_pk_fma_f32 v[154:155], v[130:131], s[78:79], v[154:155] op_sel_hi:[1,0,1]
	v_pk_fma_f32 v[152:153], v[128:129], s[78:79], v[152:153] op_sel_hi:[1,0,1]
	v_lshl_add_u64 v[202:203], v[202:203], 2, s[90:91]
	v_pk_mul_f32 v[150:151], v[216:217], v[150:151] op_sel:[1,0]
	v_pk_mul_f32 v[148:149], v[216:217], v[148:149] op_sel:[1,0]
	global_store_dwordx4 v[202:203], v[152:155], off
	v_pk_fma_f32 v[148:149], v[214:215], v[148:149], v[44:45]
	v_pk_fma_f32 v[150:151], v[212:213], v[150:151], v[46:47]
	v_add_u32_e32 v152, 0x10080, v194
	v_mov_b32_e32 v153, v159
	v_sub_f32_e32 v145, v145, v216
	v_sub_f32_e32 v144, v144, v216
	v_sub_f32_e32 v147, v147, v216
	v_sub_f32_e32 v146, v146, v216
	v_pk_fma_f32 v[150:151], v[134:135], s[78:79], v[150:151] op_sel_hi:[1,0,1]
	v_pk_fma_f32 v[148:149], v[132:133], s[78:79], v[148:149] op_sel_hi:[1,0,1]
	v_lshl_add_u64 v[152:153], v[152:153], 2, s[90:91]
	v_pk_mul_f32 v[146:147], v[216:217], v[146:147] op_sel:[1,0]
	v_pk_mul_f32 v[144:145], v[216:217], v[144:145] op_sel:[1,0]
	global_store_dwordx4 v[152:153], v[148:151], off
	v_pk_fma_f32 v[144:145], v[208:209], v[144:145], v[40:41]
	v_pk_fma_f32 v[146:147], v[206:207], v[146:147], v[42:43]
;     template <bool LN, int BJ, int LO, int HI> DI void batch(const f32x4 (&acc)[2][2][4][2], unsigned row0, unsigned col0, const f32x4 (&gv)[2], const f32x4 (&bv)[2]) const {
;         f32x4 r[HI - LO]; float mean[(HI - LO) / 2], rstd[(HI - LO) / 2];
; #pragma unroll
;         for (int i = LO; i < HI; ++i) { const int ai = i >> 3, m = (i >> 1) & 3, n = i & 1; const unsigned row = row0 + ai * HALF + m * 16;
;             if (n == 0) { mean[(i - LO) >> 1] = 0.f; rstd[(i - LO) >> 1] = 1.f;
;                 if (LN) { const float2 st = *(const float2*)(stats + row * 2u); mean[(i - LO) >> 1] = st.x; rstd[(i - LO) >> 1] = st.y; } }
;             r[i - LO] = *(const f32x4*)(src + (row * (unsigned)DM + col0 + BJ * HALF + n * 16)); }
; #pragma unroll
;         for (int i = LO; i < HI; ++i) { const int ai = i >> 3, m = (i >> 1) & 3, n = i & 1; const unsigned row = row0 + ai * HALF + m * 16;
;             *(f32x4*)(Y + (row * (unsigned)DM + col0 + BJ * HALF + n * 16)) = acc[ai][BJ][m][n] + ((r[i - LO] - mean[(i - LO) >> 1]) * rstd[(i - LO) >> 1]) * gv[n] + bv[n]; }
	v_add_u32_e32 v148, 0x10090, v194
	v_mov_b32_e32 v149, v159
	v_sub_f32_e32 v141, v141, v200
	v_sub_f32_e32 v140, v140, v200
	v_sub_f32_e32 v143, v143, v200
	v_sub_f32_e32 v142, v142, v200
	v_pk_fma_f32 v[146:147], v[130:131], s[78:79], v[146:147] op_sel_hi:[1,0,1]
	v_pk_fma_f32 v[144:145], v[128:129], s[78:79], v[144:145] op_sel_hi:[1,0,1]
	v_lshl_add_u64 v[148:149], v[148:149], 2, s[90:91]
	v_pk_mul_f32 v[142:143], v[200:201], v[142:143] op_sel:[1,0]
	v_pk_mul_f32 v[140:141], v[200:201], v[140:141] op_sel:[1,0]
	global_store_dwordx4 v[148:149], v[144:147], off
	v_pk_fma_f32 v[140:141], v[214:215], v[140:141], v[36:37]
	v_pk_fma_f32 v[142:143], v[212:213], v[142:143], v[38:39]
	v_add_u32_e32 v144, 0x18080, v194
	v_mov_b32_e32 v145, v159
	v_sub_f32_e32 v137, v137, v200
	v_sub_f32_e32 v136, v136, v200
	v_sub_f32_e32 v139, v139, v200
	v_sub_f32_e32 v138, v138, v200
	v_pk_fma_f32 v[142:143], v[134:135], s[78:79], v[142:143] op_sel_hi:[1,0,1]
	v_pk_fma_f32 v[140:141], v[132:133], s[78:79], v[140:141] op_sel_hi:[1,0,1]
	v_lshl_add_u64 v[144:145], v[144:145], 2, s[90:91]
	v_pk_mul_f32 v[138:139], v[200:201], v[138:139] op_sel:[1,0]
	v_pk_mul_f32 v[136:137], v[200:201], v[136:137] op_sel:[1,0]
	global_store_dwordx4 v[144:145], v[140:143], off
	v_pk_fma_f32 v[136:137], v[208:209], v[136:137], v[32:33]
	v_pk_fma_f32 v[138:139], v[206:207], v[138:139], v[34:35]
	v_add_u32_e32 v140, 0x18090, v194
	v_mov_b32_e32 v141, v159
	v_pk_fma_f32 v[138:139], v[130:131], s[78:79], v[138:139] op_sel_hi:[1,0,1]
	v_pk_fma_f32 v[136:137], v[128:129], s[78:79], v[136:137] op_sel_hi:[1,0,1]
	v_lshl_add_u64 v[140:141], v[140:141], 2, s[90:91]
	global_store_dwordx4 v[140:141], v[136:139], off
	s_nop 1
	v_add_u32_e32 v136, v233, v230
	v_mov_b32_e32 v137, v159
	v_lshl_add_u64 v[136:137], v[136:137], 2, s[88:89]
	global_load_dwordx2 v[220:221], v[196:197], off
	global_load_dwordx4 v[216:219], v[136:137], off
	v_add_u32_e32 v136, v233, v229
	v_mov_b32_e32 v137, v159
	v_lshl_add_u64 v[136:137], v[136:137], 2, s[88:89]
	global_load_dwordx4 v[240:243], v[136:137], off
	global_load_dwordx2 v[200:201], v[198:199], off
	v_add_u32_e32 v136, v234, v230
	v_mov_b32_e32 v137, v159
	v_lshl_add_u64 v[136:137], v[136:137], 2, s[88:89]
	global_load_dwordx4 v[244:247], v[136:137], off
	v_add_u32_e32 v136, v234, v229
	v_mov_b32_e32 v137, v159
	v_lshl_add_u64 v[136:137], v[136:137], 2, s[88:89]
	global_load_dwordx4 v[152:155], v[136:137], off
	global_load_dwordx2 v[198:199], v[204:205], off
	v_add_u32_e32 v136, v237, v230
	v_mov_b32_e32 v137, v159
	v_lshl_add_u64 v[136:137], v[136:137], 2, s[88:89]
	global_load_dwordx4 v[148:151], v[136:137], off
	v_add_u32_e32 v136, v237, v229
	v_mov_b32_e32 v137, v159
	v_lshl_add_u64 v[136:137], v[136:137], 2, s[88:89]
	global_load_dwordx4 v[144:147], v[136:137], off
	global_load_dwordx2 v[196:197], v[210:211], off
	v_add_u32_e32 v136, v238, v230
	v_mov_b32_e32 v137, v159
	v_lshl_add_u64 v[136:137], v[136:137], 2, s[88:89]
	global_load_dwordx4 v[140:143], v[136:137], off
	v_add_u32_e32 v136, v238, v229
	v_mov_b32_e32 v137, v159
	v_lshl_add_u64 v[136:137], v[136:137], 2, s[88:89]
	global_load_dwordx4 v[136:139], v[136:137], off
	v_add_u32_e32 v210, 0x40080, v194
	v_mov_b32_e32 v211, v159
	v_lshl_add_u64 v[210:211], v[210:211], 2, s[90:91]
	s_waitcnt vmcnt(0)
;     template <bool LN, int BJ, int LO, int HI> DI void batch(const f32x4 (&acc)[2][2][4][2], unsigned row0, unsigned col0, const f32x4 (&gv)[2], const f32x4 (&bv)[2]) const {
;         f32x4 r[HI - LO]; float mean[(HI - LO) / 2], rstd[(HI - LO) / 2];
; #pragma unroll
;         for (int i = LO; i < HI; ++i) { const int ai = i >> 3, m = (i >> 1) & 3, n = i & 1; const unsigned row = row0 + ai * HALF + m * 16;
;             if (n == 0) { mean[(i - LO) >> 1] = 0.f; rstd[(i - LO) >> 1] = 1.f;
;                 if (LN) { const float2 st = *(const float2*)(stats + row * 2u); mean[(i - LO) >> 1] = st.x; rstd[(i - LO) >> 1] = st.y; } }
;             r[i - LO] = *(const f32x4*)(src + (row * (unsigned)DM + col0 + BJ * HALF + n * 16)); }
; #pragma unroll
;         for (int i = LO; i < HI; ++i) { const int ai = i >> 3, m = (i >> 1) & 3, n = i & 1; const unsigned row = row0 + ai * HALF + m * 16;
;             *(f32x4*)(Y + (row * (unsigned)DM + col0 + BJ * HALF + n * 16)) = acc[ai][BJ][m][n] + ((r[i - LO] - mean[(i - LO) >> 1]) * rstd[(i - LO) >> 1]) * gv[n] + bv[n]; }
	v_sub_f32_e32 v203, v217, v220
	v_sub_f32_e32 v202, v216, v220
	v_sub_f32_e32 v205, v219, v220
	v_sub_f32_e32 v204, v218, v220
	v_pk_mul_f32 v[204:205], v[220:221], v[204:205] op_sel:[1,0]
	v_pk_mul_f32 v[202:203], v[220:221], v[202:203] op_sel:[1,0]
	v_pk_fma_f32 v[204:205], v[212:213], v[204:205], v[30:31]
	v_pk_fma_f32 v[202:203], v[214:215], v[202:203], v[28:29]
	v_pk_fma_f32 v[204:205], v[134:135], s[78:79], v[204:205] op_sel_hi:[1,0,1]
	v_pk_fma_f32 v[202:203], v[132:133], s[78:79], v[202:203] op_sel_hi:[1,0,1]
	global_store_dwordx4 v[210:211], v[202:205], off
	v_add_u32_e32 v210, 0x40090, v194
	v_mov_b32_e32 v211, v159
	v_sub_f32_e32 v203, v241, v220
	v_sub_f32_e32 v202, v240, v220
	v_sub_f32_e32 v205, v243, v220
	v_sub_f32_e32 v204, v242, v220
	v_pk_mul_f32 v[204:205], v[220:221], v[204:205] op_sel:[1,0]
	v_pk_mul_f32 v[202:203], v[220:221], v[202:203] op_sel:[1,0]
	v_pk_fma_f32 v[204:205], v[206:207], v[204:205], v[26:27]
	v_pk_fma_f32 v[202:203], v[208:209], v[202:203], v[24:25]
	v_pk_fma_f32 v[204:205], v[130:131], s[78:79], v[204:205] op_sel_hi:[1,0,1]
	v_pk_fma_f32 v[202:203], v[128:129], s[78:79], v[202:203] op_sel_hi:[1,0,1]
	v_lshl_add_u64 v[210:211], v[210:211], 2, s[90:91]
	global_store_dwordx4 v[210:211], v[202:205], off
	v_sub_f32_e32 v149, v149, v198
	v_sub_f32_e32 v148, v148, v198
	v_sub_f32_e32 v203, v245, v200
	v_sub_f32_e32 v202, v244, v200
	v_sub_f32_e32 v141, v141, v196
	v_sub_f32_e32 v140, v140, v196
	v_sub_f32_e32 v205, v247, v200
	v_sub_f32_e32 v204, v246, v200
	v_pk_mul_f32 v[202:203], v[200:201], v[202:203] op_sel:[1,0]
	v_sub_f32_e32 v151, v151, v198
	v_sub_f32_e32 v150, v150, v198
	v_pk_mul_f32 v[148:149], v[198:199], v[148:149] op_sel:[1,0]
	v_sub_f32_e32 v143, v143, v196
	v_sub_f32_e32 v142, v142, v196
	v_pk_mul_f32 v[140:141], v[196:197], v[140:141] op_sel:[1,0]
	v_pk_mul_f32 v[204:205], v[200:201], v[204:205] op_sel:[1,0]
	v_pk_fma_f32 v[202:203], v[214:215], v[202:203], v[20:21]
	v_sub_f32_e32 v153, v153, v200
	v_sub_f32_e32 v152, v152, v200
	v_sub_f32_e32 v155, v155, v200
	v_sub_f32_e32 v154, v154, v200
	v_pk_mul_f32 v[150:151], v[198:199], v[150:151] op_sel:[1,0]
	v_pk_fma_f32 v[148:149], v[214:215], v[148:149], v[12:13]
	v_pk_mul_f32 v[142:143], v[196:197], v[142:143] op_sel:[1,0]
	v_pk_fma_f32 v[140:141], v[214:215], v[140:141], v[4:5]
	v_pk_fma_f32 v[204:205], v[212:213], v[204:205], v[22:23]
	v_pk_fma_f32 v[202:203], v[132:133], s[78:79], v[202:203] op_sel_hi:[1,0,1]
	v_pk_mul_f32 v[154:155], v[200:201], v[154:155] op_sel:[1,0]
	v_pk_mul_f32 v[152:153], v[200:201], v[152:153] op_sel:[1,0]
	v_pk_fma_f32 v[150:151], v[212:213], v[150:151], v[14:15]
	v_pk_fma_f32 v[148:149], v[132:133], s[78:79], v[148:149] op_sel_hi:[1,0,1]
	v_pk_fma_f32 v[142:143], v[212:213], v[142:143], v[6:7]
	v_pk_fma_f32 v[132:133], v[132:133], s[78:79], v[140:141] op_sel_hi:[1,0,1]
	v_add_u32_e32 v140, 0x58080, v194
	v_mov_b32_e32 v141, v159
	v_pk_fma_f32 v[204:205], v[134:135], s[78:79], v[204:205] op_sel_hi:[1,0,1]
	v_pk_fma_f32 v[152:153], v[208:209], v[152:153], v[16:17]
	v_pk_fma_f32 v[154:155], v[206:207], v[154:155], v[18:19]
	v_add_u32_e32 v200, 0x48090, v194
	v_mov_b32_e32 v201, v159
	v_pk_fma_f32 v[150:151], v[134:135], s[78:79], v[150:151] op_sel_hi:[1,0,1]
	v_pk_fma_f32 v[134:135], v[134:135], s[78:79], v[142:143] op_sel_hi:[1,0,1]
	v_lshl_add_u64 v[140:141], v[140:141], 2, s[90:91]
	v_pk_fma_f32 v[154:155], v[130:131], s[78:79], v[154:155] op_sel_hi:[1,0,1]
	v_pk_fma_f32 v[152:153], v[128:129], s[78:79], v[152:153] op_sel_hi:[1,0,1]
	v_lshl_add_u64 v[200:201], v[200:201], 2, s[90:91]
	v_sub_f32_e32 v145, v145, v198
	v_sub_f32_e32 v144, v144, v198
	global_store_dwordx4 v[140:141], v[132:135], off
	global_store_dwordx4 v[200:201], v[152:155], off
	v_sub_f32_e32 v147, v147, v198
	v_sub_f32_e32 v133, v137, v196
	v_sub_f32_e32 v132, v136, v196
	v_add_u32_e32 v152, 0x50080, v194
	v_mov_b32_e32 v153, v159
	v_sub_f32_e32 v146, v146, v198
	v_pk_mul_f32 v[144:145], v[198:199], v[144:145] op_sel:[1,0]
	v_sub_f32_e32 v135, v139, v196
	v_sub_f32_e32 v134, v138, v196
	v_pk_mul_f32 v[132:133], v[196:197], v[132:133] op_sel:[1,0]
	v_lshl_add_u64 v[152:153], v[152:153], 2, s[90:91]
	v_pk_mul_f32 v[146:147], v[198:199], v[146:147] op_sel:[1,0]
	v_pk_fma_f32 v[144:145], v[208:209], v[144:145], v[8:9]
	v_pk_mul_f32 v[134:135], v[196:197], v[134:135] op_sel:[1,0]
	v_pk_fma_f32 v[132:133], v[208:209], v[132:133], v[0:1]
	v_add_u32_e32 v210, 0x48080, v194
	v_mov_b32_e32 v211, v159
	global_store_dwordx4 v[152:153], v[148:151], off
	v_pk_fma_f32 v[146:147], v[206:207], v[146:147], v[10:11]
	v_pk_fma_f32 v[144:145], v[128:129], s[78:79], v[144:145] op_sel_hi:[1,0,1]
	v_add_u32_e32 v148, 0x50090, v194
	v_mov_b32_e32 v149, v159
	v_pk_fma_f32 v[134:135], v[206:207], v[134:135], v[2:3]
	v_pk_fma_f32 v[128:129], v[128:129], s[78:79], v[132:133] op_sel_hi:[1,0,1]
	v_add_u32_e32 v132, 0x58090, v194
	v_mov_b32_e32 v133, v159
	v_lshl_add_u64 v[210:211], v[210:211], 2, s[90:91]
	v_pk_fma_f32 v[146:147], v[130:131], s[78:79], v[146:147] op_sel_hi:[1,0,1]
	v_lshl_add_u64 v[148:149], v[148:149], 2, s[90:91]
	v_pk_fma_f32 v[130:131], v[130:131], s[78:79], v[134:135] op_sel_hi:[1,0,1]
	v_lshl_add_u64 v[132:133], v[132:133], 2, s[90:91]
	global_store_dwordx4 v[210:211], v[202:205], off
	global_store_dwordx4 v[148:149], v[144:147], off
	global_store_dwordx4 v[132:133], v[128:131], off
	s_mov_b64 s[20:21], 0
	s_branch .LBB0_81

; #define PG8_STAGE(bufoff, gbase) do { _Pragma("unroll") for (int _i = 0; _i < 2; ++_i) \
;         __builtin_amdgcn_global_load_lds((const unsigned*)((const char*)(gbase) + voff[_i]), (LAS unsigned*)(lds + (bufoff) + ldsw + _i * 8192), 16, 0, 0); } while (0)
; #define PG8_LDA(dst, b, h) do { _Pragma("unroll") for (int m = 0; m < 4; ++m) _Pragma("unroll") for (int k = 0; k < 2; ++k) dst[m][k] = *(const LAS bf16x8*)(lds + PG8_SA(b, h) + aoff + m * 2048 + k * 1024); } while (0)
; #define PG8_LDB(dst, b, h) do { _Pragma("unroll") for (int n = 0; n < 2; ++n) _Pragma("unroll") for (int k = 0; k < 2; ++k) dst[n][k] = *(const LAS bf16x8*)(lds + PG8_SB(b, h) + boff + n * 2048 + k * 1024); } while (0)
; #define PG8_MMA(ai, bj, At, Bt) do { __builtin_amdgcn_s_setprio(1); _Pragma("unroll") for (int m = 0; m < 4; ++m) _Pragma("unroll") for (int n = 0; n < 2; ++n) _Pragma("unroll") for (int k = 0; k < 2; ++k) \
;         acc[ai][bj][m][n] = __builtin_amdgcn_mfma_f32_16x16x32_bf16(Bt[n][k], At[m][k], acc[ai][bj][m][n], 0, 0, 0); __builtin_amdgcn_s_setprio(0); } while (0)
; #define PG8_WAIT_V(n) asm volatile("s_waitcnt vmcnt(" #n ")" ::: "memory")
; #define PG8_WAIT_L(n) asm volatile("s_waitcnt lgkmcnt(" #n ")" ::: "memory")
; #define PG8_BAR __builtin_amdgcn_s_barrier()
; #define PG8_SCHED __builtin_amdgcn_sched_barrier(0)
; template <class Epi>
; DI void gemm_phase(LAS unsigned char* lds, const Gemm g, const StaticOrder& S, const Epi& E) {
;     ...
;             const bool last = (t == nt - 2);
;             const char* a1 = cA + (size_t)(t + 1) * kstep;
;             const char* a2 = last ? nA : cA + (size_t)(t + 2) * kstep; const char* b2 = last ? nB : cB + (size_t)(t + 2) * kstep;
;             const char* a3 = a2 + kstep; const char* b3 = b2 + kstep;
;             PG8_LDB(B0, 0, 0); PG8_SCHED; PG8_LDA(At, 0, 0); PG8_STAGE(PG8_SA(1, 1), a1 + hstep);
;             PG8_WAIT_L(8); PG8_BAR; PG8_WAIT_L(0); PG8_MMA(0, 0, At, B0); PG8_BAR; PG8_SCHED;
;             PG8_LDB(B1, 0, 1); PG8_STAGE(PG8_SB(0, 0), b2);
;             PG8_BAR; PG8_WAIT_L(0); PG8_MMA(0, 1, At, B1); PG8_BAR;
;             PG8_LDA(At, 0, 1); PG8_STAGE(PG8_SA(0, 0), a2);
;             PG8_BAR; PG8_WAIT_L(0); PG8_MMA(1, 0, At, B0); PG8_BAR; PG8_SCHED;
;             PG8_STAGE(PG8_SB(0, 1), b2 + hstep);
;             PG8_WAIT_V(6); PG8_BAR; PG8_MMA(1, 1, At, B1); PG8_BAR;
.LBB0_134:
	ds_read_b128 v[96:99], v199
	ds_read_b128 v[100:103], v199 offset:1024
	ds_read_b128 v[136:139], v199 offset:2048
	ds_read_b128 v[148:151], v199 offset:3072
	ds_read_b128 v[152:155], v201
	ds_read_b128 v[186:189], v201 offset:1024
	ds_read_b128 v[190:193], v201 offset:2048
	ds_read_b128 v[194:197], v201 offset:3072
	ds_read_b128 v[202:205], v201 offset:4096
	ds_read_b128 v[206:209], v201 offset:5120
	ds_read_b128 v[210:213], v201 offset:6144
	ds_read_b128 v[214:217], v201 offset:7168
	s_add_u32 s18, s16, 0x100
	s_addc_u32 s19, s17, 0
	s_add_i32 s39, 0, 0x10000
	s_cmpk_eq_i32 s33, 0x54
	s_cselect_b32 s23, s9, s19
	s_cselect_b32 s22, s8, s18
	s_cselect_b32 s21, s11, s5
	s_cselect_b32 s20, s10, s4
	s_add_i32 m0, s28, 0xc000
	s_nop 0
	global_load_lds_dwordx4 v144, s[16:17]
	s_add_i32 m0, s28, 0xe000
	s_nop 0
	global_load_lds_dwordx4 v146, s[16:17]
	s_waitcnt lgkmcnt(8)
	s_setprio 1
	s_barrier
	s_waitcnt lgkmcnt(0)
	v_mfma_f32_16x16x32_bf16 v[132:135], v[96:99], v[152:155], v[132:135]
	v_mfma_f32_16x16x32_bf16 v[128:131], v[136:139], v[152:155], v[128:131]
	v_mfma_f32_16x16x32_bf16 v[124:127], v[96:99], v[190:193], v[124:127]
	v_mfma_f32_16x16x32_bf16 v[120:123], v[136:139], v[190:193], v[120:123]
	v_mfma_f32_16x16x32_bf16 v[116:119], v[96:99], v[202:205], v[116:119]
	v_mfma_f32_16x16x32_bf16 v[112:115], v[136:139], v[202:205], v[112:115]
	v_mfma_f32_16x16x32_bf16 v[108:111], v[96:99], v[210:213], v[108:111]
	v_mfma_f32_16x16x32_bf16 v[104:107], v[136:139], v[210:213], v[104:107]
	v_mfma_f32_16x16x32_bf16 v[132:135], v[100:103], v[186:189], v[132:135]
	v_mfma_f32_16x16x32_bf16 v[128:131], v[148:151], v[186:189], v[128:131]
	v_mfma_f32_16x16x32_bf16 v[124:127], v[100:103], v[194:197], v[124:127]
	v_mfma_f32_16x16x32_bf16 v[120:123], v[148:151], v[194:197], v[120:123]
	v_mfma_f32_16x16x32_bf16 v[116:119], v[100:103], v[206:209], v[116:119]
	v_mfma_f32_16x16x32_bf16 v[112:115], v[148:151], v[206:209], v[112:115]
	v_mfma_f32_16x16x32_bf16 v[108:111], v[100:103], v[214:217], v[108:111]
	s_setprio 0
	v_mfma_f32_16x16x32_bf16 v[104:107], v[148:151], v[214:217], v[104:107]
	s_barrier
	ds_read_b128 v[226:229], v199 offset:16384
	ds_read_b128 v[230:233], v199 offset:17408
	ds_read_b128 v[234:237], v199 offset:18432
	ds_read_b128 v[238:241], v199 offset:19456
	s_add_i32 s40, 0, 0x14000
	s_add_i32 s16, s39, s27
	s_mov_b32 m0, s16
	s_nop 0
	global_load_lds_dwordx4 v142, s[20:21]
	s_add_i32 m0, s16, 0x2000
	s_nop 0
	global_load_lds_dwordx4 v140, s[20:21]
	s_waitcnt lgkmcnt(0)
	s_setprio 1
	s_barrier
	v_mfma_f32_16x16x32_bf16 v[60:63], v[226:229], v[152:155], v[60:63]
	v_mfma_f32_16x16x32_bf16 v[56:59], v[234:237], v[152:155], v[56:59]
	v_mfma_f32_16x16x32_bf16 v[52:55], v[226:229], v[190:193], v[52:55]
	v_mfma_f32_16x16x32_bf16 v[48:51], v[234:237], v[190:193], v[48:51]
	v_mfma_f32_16x16x32_bf16 v[44:47], v[226:229], v[202:205], v[44:47]
	v_mfma_f32_16x16x32_bf16 v[40:43], v[234:237], v[202:205], v[40:43]
	v_mfma_f32_16x16x32_bf16 v[36:39], v[226:229], v[210:213], v[36:39]
	v_mfma_f32_16x16x32_bf16 v[32:35], v[234:237], v[210:213], v[32:35]
	v_mfma_f32_16x16x32_bf16 v[60:63], v[230:233], v[186:189], v[60:63]
	s_mov_b32 m0, s28
	v_mfma_f32_16x16x32_bf16 v[56:59], v[238:241], v[186:189], v[56:59]
	s_mov_b64 s[100:101], s[22:23]
	v_mfma_f32_16x16x32_bf16 v[52:55], v[230:233], v[194:197], v[52:55]
	v_mfma_f32_16x16x32_bf16 v[48:51], v[238:241], v[194:197], v[48:51]
	v_mfma_f32_16x16x32_bf16 v[44:47], v[230:233], v[206:209], v[44:47]
	v_mfma_f32_16x16x32_bf16 v[40:43], v[238:241], v[206:209], v[40:43]
	v_mfma_f32_16x16x32_bf16 v[36:39], v[230:233], v[214:217], v[36:39]
	s_setprio 0
	v_mfma_f32_16x16x32_bf16 v[32:35], v[238:241], v[214:217], v[32:35]
	s_barrier
	ds_read_b128 v[152:155], v201 offset:16384
	ds_read_b128 v[186:189], v201 offset:17408
	ds_read_b128 v[190:193], v201 offset:18432
	ds_read_b128 v[194:197], v201 offset:19456
	ds_read_b128 v[202:205], v201 offset:20480
	ds_read_b128 v[206:209], v201 offset:21504
	ds_read_b128 v[210:213], v201 offset:22528
	ds_read_b128 v[214:217], v201 offset:23552
	global_load_lds_dwordx4 v142, s[22:23]
	s_mov_b64 s[100:101], s[22:23]
	s_mov_b32 m0, s29
	s_nop 0
	global_load_lds_dwordx4 v140, s[22:23]
	s_waitcnt lgkmcnt(0)
	s_setprio 1
	s_barrier
	v_mfma_f32_16x16x32_bf16 v[92:95], v[96:99], v[152:155], v[92:95]
	v_mfma_f32_16x16x32_bf16 v[88:91], v[136:139], v[152:155], v[88:91]
	v_mfma_f32_16x16x32_bf16 v[84:87], v[96:99], v[190:193], v[84:87]
	v_mfma_f32_16x16x32_bf16 v[80:83], v[136:139], v[190:193], v[80:83]
	v_mfma_f32_16x16x32_bf16 v[76:79], v[96:99], v[202:205], v[76:79]
	v_mfma_f32_16x16x32_bf16 v[72:75], v[136:139], v[202:205], v[72:75]
	v_mfma_f32_16x16x32_bf16 v[68:71], v[96:99], v[210:213], v[68:71]
	v_mfma_f32_16x16x32_bf16 v[64:67], v[136:139], v[210:213], v[64:67]
	v_mfma_f32_16x16x32_bf16 v[92:95], v[100:103], v[186:189], v[92:95]
	v_mfma_f32_16x16x32_bf16 v[88:91], v[148:151], v[186:189], v[88:91]
	v_mfma_f32_16x16x32_bf16 v[84:87], v[100:103], v[194:197], v[84:87]
	v_mfma_f32_16x16x32_bf16 v[80:83], v[148:151], v[194:197], v[80:83]
	v_mfma_f32_16x16x32_bf16 v[76:79], v[100:103], v[206:209], v[76:79]
	v_mfma_f32_16x16x32_bf16 v[72:75], v[148:151], v[206:209], v[72:75]
	v_mfma_f32_16x16x32_bf16 v[68:71], v[100:103], v[214:217], v[68:71]
	s_setprio 0
	v_mfma_f32_16x16x32_bf16 v[64:67], v[148:151], v[214:217], v[64:67]
	s_barrier
	s_add_u32 s16, s20, 0x160000
	s_addc_u32 s17, s21, 0
	s_add_i32 s39, s40, s27
	s_mov_b32 m0, s39
	s_nop 0
	global_load_lds_dwordx4 v142, s[16:17]
	s_add_i32 m0, s39, 0x2000
	s_nop 0
	global_load_lds_dwordx4 v140, s[16:17]
	s_waitcnt vmcnt(6)
	s_setprio 1
	s_barrier
; #define PG8_STAGE(bufoff, gbase) do { _Pragma("unroll") for (int _i = 0; _i < 2; ++_i) \
;         __builtin_amdgcn_global_load_lds((const unsigned*)((const char*)(gbase) + voff[_i]), (LAS unsigned*)(lds + (bufoff) + ldsw + _i * 8192), 16, 0, 0); } while (0)
; #define PG8_LDA(dst, b, h) do { _Pragma("unroll") for (int m = 0; m < 4; ++m) _Pragma("unroll") for (int k = 0; k < 2; ++k) dst[m][k] = *(const LAS bf16x8*)(lds + PG8_SA(b, h) + aoff + m * 2048 + k * 1024); } while (0)
; #define PG8_LDB(dst, b, h) do { _Pragma("unroll") for (int n = 0; n < 2; ++n) _Pragma("unroll") for (int k = 0; k < 2; ++k) dst[n][k] = *(const LAS bf16x8*)(lds + PG8_SB(b, h) + boff + n * 2048 + k * 1024); } while (0)
; #define PG8_MMA(ai, bj, At, Bt) do { __builtin_amdgcn_s_setprio(1); _Pragma("unroll") for (int m = 0; m < 4; ++m) _Pragma("unroll") for (int n = 0; n < 2; ++n) _Pragma("unroll") for (int k = 0; k < 2; ++k) \
;         acc[ai][bj][m][n] = __builtin_amdgcn_mfma_f32_16x16x32_bf16(Bt[n][k], At[m][k], acc[ai][bj][m][n], 0, 0, 0); __builtin_amdgcn_s_setprio(0); } while (0)
; #define PG8_WAIT_V(n) asm volatile("s_waitcnt vmcnt(" #n ")" ::: "memory")
; #define PG8_WAIT_L(n) asm volatile("s_waitcnt lgkmcnt(" #n ")" ::: "memory")
; #define PG8_BAR __builtin_amdgcn_s_barrier()
; #define PG8_SCHED __builtin_amdgcn_sched_barrier(0)
; template <class Epi>
; DI void gemm_phase(LAS unsigned char* lds, const Gemm g, const StaticOrder& S, const Epi& E) {
;     ...
;             PG8_WAIT_V(6); PG8_BAR; PG8_MMA(1, 1, At, B1); PG8_BAR;
;             PG8_LDB(B0, 1, 0); PG8_SCHED; PG8_LDA(At, 1, 0); PG8_STAGE(PG8_SA(0, 1), a2 + hstep);
;             PG8_WAIT_L(8); PG8_BAR; PG8_WAIT_L(0); PG8_MMA(0, 0, At, B0); PG8_BAR; PG8_SCHED;
;             PG8_LDB(B1, 1, 1); PG8_STAGE(PG8_SB(1, 0), b3);
;             PG8_BAR; PG8_WAIT_L(0); PG8_MMA(0, 1, At, B1); PG8_BAR;
;             PG8_LDA(At, 1, 1); PG8_STAGE(PG8_SA(1, 0), a3);
;             PG8_BAR; PG8_WAIT_L(0); PG8_MMA(1, 0, At, B0); PG8_BAR; PG8_SCHED;
	v_mfma_f32_16x16x32_bf16 v[28:31], v[226:229], v[152:155], v[28:31]
	v_mfma_f32_16x16x32_bf16 v[24:27], v[234:237], v[152:155], v[24:27]
	v_mfma_f32_16x16x32_bf16 v[20:23], v[226:229], v[190:193], v[20:23]
	v_mfma_f32_16x16x32_bf16 v[16:19], v[234:237], v[190:193], v[16:19]
	v_mfma_f32_16x16x32_bf16 v[12:15], v[226:229], v[202:205], v[12:15]
	v_mfma_f32_16x16x32_bf16 v[8:11], v[234:237], v[202:205], v[8:11]
	v_mfma_f32_16x16x32_bf16 v[4:7], v[226:229], v[210:213], v[4:7]
	v_mfma_f32_16x16x32_bf16 v[0:3], v[234:237], v[210:213], v[0:3]
	v_mfma_f32_16x16x32_bf16 v[28:31], v[230:233], v[186:189], v[28:31]
	s_add_i32 s39, 0, 0x18000
	v_mfma_f32_16x16x32_bf16 v[24:27], v[238:241], v[186:189], v[24:27]
	v_mfma_f32_16x16x32_bf16 v[20:23], v[230:233], v[194:197], v[20:23]
	v_mfma_f32_16x16x32_bf16 v[16:19], v[238:241], v[194:197], v[16:19]
	v_mfma_f32_16x16x32_bf16 v[12:15], v[230:233], v[206:209], v[12:15]
	v_mfma_f32_16x16x32_bf16 v[8:11], v[238:241], v[206:209], v[8:11]
	v_mfma_f32_16x16x32_bf16 v[4:7], v[230:233], v[214:217], v[4:7]
	s_setprio 0
	v_mfma_f32_16x16x32_bf16 v[0:3], v[238:241], v[214:217], v[0:3]
	s_barrier
	ds_read_b128 v[96:99], v199 offset:32768
	ds_read_b128 v[100:103], v199 offset:33792
	ds_read_b128 v[136:139], v199 offset:34816
	ds_read_b128 v[148:151], v199 offset:35840
	ds_read_b128 v[152:155], v201 offset:32768
	ds_read_b128 v[186:189], v201 offset:33792
	ds_read_b128 v[190:193], v201 offset:34816
	ds_read_b128 v[194:197], v201 offset:35840
	ds_read_b128 v[202:205], v201 offset:36864
	ds_read_b128 v[206:209], v201 offset:37888
	ds_read_b128 v[210:213], v201 offset:38912
	ds_read_b128 v[214:217], v201 offset:39936
	s_add_u32 s16, s22, 0x160000
	s_addc_u32 s17, s23, 0
	s_mov_b32 m0, s30
	s_nop 0
	global_load_lds_dwordx4 v142, s[16:17]
	s_mov_b32 m0, s31
	s_nop 0
	global_load_lds_dwordx4 v140, s[16:17]
	s_waitcnt lgkmcnt(8)
	s_setprio 1
	s_barrier
	s_waitcnt lgkmcnt(0)
	v_mfma_f32_16x16x32_bf16 v[132:135], v[96:99], v[152:155], v[132:135]
	v_mfma_f32_16x16x32_bf16 v[128:131], v[136:139], v[152:155], v[128:131]
	v_mfma_f32_16x16x32_bf16 v[124:127], v[96:99], v[190:193], v[124:127]
	v_mfma_f32_16x16x32_bf16 v[120:123], v[136:139], v[190:193], v[120:123]
	v_mfma_f32_16x16x32_bf16 v[116:119], v[96:99], v[202:205], v[116:119]
	v_mfma_f32_16x16x32_bf16 v[112:115], v[136:139], v[202:205], v[112:115]
	v_mfma_f32_16x16x32_bf16 v[108:111], v[96:99], v[210:213], v[108:111]
	v_mfma_f32_16x16x32_bf16 v[104:107], v[136:139], v[210:213], v[104:107]
	v_mfma_f32_16x16x32_bf16 v[132:135], v[100:103], v[186:189], v[132:135]
	v_mfma_f32_16x16x32_bf16 v[128:131], v[148:151], v[186:189], v[128:131]
	v_mfma_f32_16x16x32_bf16 v[124:127], v[100:103], v[194:197], v[124:127]
	v_mfma_f32_16x16x32_bf16 v[120:123], v[148:151], v[194:197], v[120:123]
	v_mfma_f32_16x16x32_bf16 v[116:119], v[100:103], v[206:209], v[116:119]
	v_mfma_f32_16x16x32_bf16 v[112:115], v[148:151], v[206:209], v[112:115]
	v_mfma_f32_16x16x32_bf16 v[108:111], v[100:103], v[214:217], v[108:111]
	s_setprio 0
	v_mfma_f32_16x16x32_bf16 v[104:107], v[148:151], v[214:217], v[104:107]
	s_barrier
	ds_read_b128 v[226:229], v199 offset:49152
	ds_read_b128 v[230:233], v199 offset:50176
	ds_read_b128 v[234:237], v199 offset:51200
	ds_read_b128 v[238:241], v199 offset:52224
	s_add_i32 s22, 0, 0x1c000
	s_add_i32 s16, s39, s27
	s_add_i32 m0, s16, 0xffffff80
	s_nop 0
	global_load_lds_dwordx4 v142, s[20:21] offset:128
	s_add_i32 m0, s16, 0x1f80
	s_nop 0
	global_load_lds_dwordx4 v140, s[20:21] offset:128
	s_waitcnt lgkmcnt(0)
	s_setprio 1
	s_barrier
	v_mfma_f32_16x16x32_bf16 v[60:63], v[226:229], v[152:155], v[60:63]
	v_mfma_f32_16x16x32_bf16 v[56:59], v[234:237], v[152:155], v[56:59]
	v_mfma_f32_16x16x32_bf16 v[52:55], v[226:229], v[190:193], v[52:55]
	v_mfma_f32_16x16x32_bf16 v[48:51], v[234:237], v[190:193], v[48:51]
	v_mfma_f32_16x16x32_bf16 v[44:47], v[226:229], v[202:205], v[44:47]
	v_mfma_f32_16x16x32_bf16 v[40:43], v[234:237], v[202:205], v[40:43]
	v_mfma_f32_16x16x32_bf16 v[36:39], v[226:229], v[210:213], v[36:39]
	v_mfma_f32_16x16x32_bf16 v[32:35], v[234:237], v[210:213], v[32:35]
	v_mfma_f32_16x16x32_bf16 v[60:63], v[230:233], v[186:189], v[60:63]
	s_add_i32 m0, s34, 0xffffff80
	v_mfma_f32_16x16x32_bf16 v[56:59], v[238:241], v[186:189], v[56:59]
	v_mfma_f32_16x16x32_bf16 v[52:55], v[230:233], v[194:197], v[52:55]
	v_mfma_f32_16x16x32_bf16 v[48:51], v[238:241], v[194:197], v[48:51]
	v_mfma_f32_16x16x32_bf16 v[44:47], v[230:233], v[206:209], v[44:47]
	v_mfma_f32_16x16x32_bf16 v[40:43], v[238:241], v[206:209], v[40:43]
	v_mfma_f32_16x16x32_bf16 v[36:39], v[230:233], v[214:217], v[36:39]
	s_setprio 0
	v_mfma_f32_16x16x32_bf16 v[32:35], v[238:241], v[214:217], v[32:35]
	s_barrier
	ds_read_b128 v[152:155], v201 offset:49152
	ds_read_b128 v[186:189], v201 offset:50176
	ds_read_b128 v[190:193], v201 offset:51200
	ds_read_b128 v[194:197], v201 offset:52224
	ds_read_b128 v[202:205], v201 offset:53248
	ds_read_b128 v[206:209], v201 offset:54272
	ds_read_b128 v[210:213], v201 offset:55296
	ds_read_b128 v[214:217], v201 offset:56320
	global_load_lds_dwordx4 v142, s[100:101] offset:128
	s_add_i32 m0, s35, 0xffffff80
	s_nop 0
	global_load_lds_dwordx4 v140, s[100:101] offset:128
	s_waitcnt lgkmcnt(0)
	s_setprio 1
	s_barrier
; #define PG8_BAR __builtin_amdgcn_s_barrier()
; template <class Epi>
; DI void gemm_phase(LAS unsigned char* lds, const Gemm g, const StaticOrder& S, const Epi& E) {
;     ...
;             PG8_BAR; PG8_WAIT_L(0); PG8_MMA(1, 0, At, B0); PG8_BAR; PG8_SCHED;
;             PG8_STAGE(PG8_SB(1, 1), b3 + hstep);
;             PG8_WAIT_V(6); PG8_BAR; PG8_MMA(1, 1, At, B1); PG8_BAR;
;     template <bool LN, int BJ, int LO, int HI> DI void batch(const f32x4 (&acc)[2][2][4][2], unsigned row0, unsigned col0, const f32x4 (&gv)[2], const f32x4 (&bv)[2]) const {
;         f32x4 r[HI - LO]; float mean[(HI - LO) / 2], rstd[(HI - LO) / 2];
; #pragma unroll
;         for (int i = LO; i < HI; ++i) { const int ai = i >> 3, m = (i >> 1) & 3, n = i & 1; const unsigned row = row0 + ai * HALF + m * 16;
;             if (n == 0) { mean[(i - LO) >> 1] = 0.f; rstd[(i - LO) >> 1] = 1.f;
;                 if (LN) { const float2 st = *(const float2*)(stats + row * 2u); mean[(i - LO) >> 1] = st.x; rstd[(i - LO) >> 1] = st.y; } }
;             r[i - LO] = *(const f32x4*)(src + (row * (unsigned)DM + col0 + BJ * HALF + n * 16)); }
; #pragma unroll
;         for (int i = LO; i < HI; ++i) { const int ai = i >> 3, m = (i >> 1) & 3, n = i & 1; const unsigned row = row0 + ai * HALF + m * 16;
;             *(f32x4*)(Y + (row * (unsigned)DM + col0 + BJ * HALF + n * 16)) = acc[ai][BJ][m][n] + ((r[i - LO] - mean[(i - LO) >> 1]) * rstd[(i - LO) >> 1]) * gv[n] + bv[n]; }
;         __builtin_amdgcn_sched_barrier(0);
;     }
;     template <bool LN, int BJ> DI void load_gb(unsigned col0, f32x4 (&gv)[2], f32x4 (&bv)[2]) const {
; #pragma unroll
;         for (int n = 0; n < 2; ++n) {
;             if (LN) { gv[n] = *(const f32x4*)(gam + col0 + BJ * HALF + n * 16) * ALPHA; bv[n] = *(const f32x4*)(bet + col0 + BJ * HALF + n * 16) * ALPHA; }
;             else { gv[n] = (f32x4){ALPHA, ALPHA, ALPHA, ALPHA}; bv[n] = (f32x4){0.f, 0.f, 0.f, 0.f}; }
;         }
;     }
;     template <bool LN> DI void run(const f32x4 (&acc)[2][2][4][2], const Unit& u, int wr, int wc, int fr, int fq) const {
;         const unsigned row0 = u.pm * BM + wr * 64 + fr, col0 = u.pn * BM + wc * 32 + 4 * fq;
;         f32x4 gv[2], bv[2];
;         load_gb<LN, 0>(col0, gv, bv);
;         batch<LN, 0, 0, 4>(acc, row0, col0, gv, bv);
;         batch<LN, 0, 4, 8>(acc, row0, col0, gv, bv);
;         batch<LN, 0, 8, 12>(acc, row0, col0, gv, bv);
	v_mfma_f32_16x16x32_bf16 v[92:95], v[96:99], v[152:155], v[92:95]
	v_mfma_f32_16x16x32_bf16 v[88:91], v[136:139], v[152:155], v[88:91]
	v_mfma_f32_16x16x32_bf16 v[84:87], v[96:99], v[190:193], v[84:87]
	v_mfma_f32_16x16x32_bf16 v[80:83], v[136:139], v[190:193], v[80:83]
	v_mfma_f32_16x16x32_bf16 v[76:79], v[96:99], v[202:205], v[76:79]
	v_mfma_f32_16x16x32_bf16 v[72:75], v[136:139], v[202:205], v[72:75]
	v_mfma_f32_16x16x32_bf16 v[68:71], v[96:99], v[210:213], v[68:71]
	v_mfma_f32_16x16x32_bf16 v[64:67], v[136:139], v[210:213], v[64:67]
	v_mfma_f32_16x16x32_bf16 v[92:95], v[100:103], v[186:189], v[92:95]
	v_mfma_f32_16x16x32_bf16 v[88:91], v[148:151], v[186:189], v[88:91]
	v_mfma_f32_16x16x32_bf16 v[84:87], v[100:103], v[194:197], v[84:87]
	v_mfma_f32_16x16x32_bf16 v[80:83], v[148:151], v[194:197], v[80:83]
	v_mfma_f32_16x16x32_bf16 v[76:79], v[100:103], v[206:209], v[76:79]
	v_mfma_f32_16x16x32_bf16 v[72:75], v[148:151], v[206:209], v[72:75]
	v_mfma_f32_16x16x32_bf16 v[68:71], v[100:103], v[214:217], v[68:71]
	s_setprio 0
	v_mfma_f32_16x16x32_bf16 v[64:67], v[148:151], v[214:217], v[64:67]
	s_barrier
	s_add_u32 s16, s20, 0x160080
	s_addc_u32 s17, s21, 0
	s_add_i32 s20, s22, s27
	s_mov_b32 m0, s20
	s_nop 0
	global_load_lds_dwordx4 v142, s[16:17]
	s_add_i32 m0, s20, 0x2000
	s_nop 0
	global_load_lds_dwordx4 v140, s[16:17]
	s_waitcnt vmcnt(6)
	s_setprio 1
	s_barrier
	v_mfma_f32_16x16x32_bf16 v[28:31], v[226:229], v[152:155], v[28:31]
	v_mfma_f32_16x16x32_bf16 v[24:27], v[234:237], v[152:155], v[24:27]
	v_mfma_f32_16x16x32_bf16 v[20:23], v[226:229], v[190:193], v[20:23]
	v_mfma_f32_16x16x32_bf16 v[16:19], v[234:237], v[190:193], v[16:19]
	v_mfma_f32_16x16x32_bf16 v[12:15], v[226:229], v[202:205], v[12:15]
	v_mfma_f32_16x16x32_bf16 v[8:11], v[234:237], v[202:205], v[8:11]
	v_mfma_f32_16x16x32_bf16 v[4:7], v[226:229], v[210:213], v[4:7]
	v_mfma_f32_16x16x32_bf16 v[0:3], v[234:237], v[210:213], v[0:3]
	v_mfma_f32_16x16x32_bf16 v[28:31], v[230:233], v[186:189], v[28:31]
	s_add_i32 s33, s33, 2
	v_mfma_f32_16x16x32_bf16 v[24:27], v[238:241], v[186:189], v[24:27]
	s_add_u32 s4, s4, 0x100
	v_mfma_f32_16x16x32_bf16 v[20:23], v[230:233], v[194:197], v[20:23]
	s_addc_u32 s5, s5, 0
	v_mfma_f32_16x16x32_bf16 v[16:19], v[238:241], v[194:197], v[16:19]
	s_cmpk_gt_u32 s33, 0x55
	v_mfma_f32_16x16x32_bf16 v[12:15], v[230:233], v[206:209], v[12:15]
	s_mov_b64 s[16:17], s[18:19]
	v_mfma_f32_16x16x32_bf16 v[8:11], v[238:241], v[206:209], v[8:11]
	v_mfma_f32_16x16x32_bf16 v[4:7], v[230:233], v[214:217], v[4:7]
	s_setprio 0
	v_mfma_f32_16x16x32_bf16 v[0:3], v[238:241], v[214:217], v[0:3]
	s_barrier
	s_cbranch_scc0 .LBB0_134
	v_lshl_or_b32 v158, s2, 8, v200
	v_lshlrev_b64 v[100:101], 2, v[158:159]
	v_lshl_add_u64 v[150:151], s[12:13], 0, v[100:101]
	global_load_dwordx4 v[96:99], v[150:151], off
	v_lshl_add_u64 v[152:153], s[14:15], 0, v[100:101]
	v_lshl_add_u32 v203, s3, 8, v198
	v_lshlrev_b32_e32 v202, 11, v203
	v_add_u32_e32 v148, v202, v158
	v_mov_b32_e32 v149, v159
	v_lshlrev_b32_e32 v136, 1, v203
	v_mov_b32_e32 v137, v159
	v_lshlrev_b64 v[220:221], 2, v[148:149]
	v_lshl_add_u64 v[154:155], v[136:137], 2, s[96:97]
	v_lshl_add_u64 v[136:137], s[90:91], 0, v[220:221]
	v_or_b32_e32 v204, 16, v158
	v_or_b32_e32 v138, 16, v203
	v_lshlrev_b32_e32 v149, 11, v138
	s_waitcnt vmcnt(0)
	v_pk_mul_f32 v[192:193], v[98:99], s[78:79] op_sel_hi:[1,0]
	v_pk_mul_f32 v[194:195], v[96:97], s[78:79] op_sel_hi:[1,0]
	global_load_dwordx4 v[100:103], v[152:153], off
	global_load_dwordx4 v[96:99], v[150:151], off offset:64
	global_load_dwordx2 v[218:219], v[154:155], off
	global_load_dwordx4 v[206:209], v[136:137], off
	v_add_u32_e32 v136, v202, v204
	v_mov_b32_e32 v137, v159
	v_lshl_add_u64 v[136:137], v[136:137], 2, s[90:91]
	global_load_dwordx4 v[210:213], v[136:137], off
	v_lshlrev_b32_e32 v136, 1, v138
	v_mov_b32_e32 v137, v159
	v_lshl_add_u64 v[186:187], v[136:137], 2, s[96:97]
	v_add_u32_e32 v136, v149, v158
	v_lshl_add_u64 v[136:137], v[136:137], 2, s[90:91]
	global_load_dwordx2 v[196:197], v[186:187], off
	global_load_dwordx4 v[214:217], v[136:137], off
	v_add_u32_e32 v136, v149, v204
	v_mov_b32_e32 v137, v159
	v_lshl_add_u64 v[136:137], v[136:137], 2, s[90:91]
	global_load_dwordx4 v[136:139], v[136:137], off
	s_waitcnt vmcnt(0)
	v_pk_mul_f32 v[188:189], v[98:99], s[78:79] op_sel_hi:[1,0]
	v_pk_mul_f32 v[190:191], v[96:97], s[78:79] op_sel_hi:[1,0]
	global_load_dwordx4 v[96:99], v[152:153], off offset:64
	v_sub_f32_e32 v207, v207, v218
	v_sub_f32_e32 v206, v206, v218
	v_sub_f32_e32 v209, v209, v218
	v_sub_f32_e32 v208, v208, v218
	v_pk_mul_f32 v[208:209], v[218:219], v[208:209] op_sel:[1,0]
	v_pk_mul_f32 v[206:207], v[218:219], v[206:207] op_sel:[1,0]
	v_pk_fma_f32 v[134:135], v[192:193], v[208:209], v[134:135]
	v_pk_fma_f32 v[132:133], v[194:195], v[206:207], v[132:133]
	v_pk_fma_f32 v[134:135], v[102:103], s[78:79], v[134:135] op_sel_hi:[1,0,1]
	v_pk_fma_f32 v[132:133], v[100:101], s[78:79], v[132:133] op_sel_hi:[1,0,1]
	v_lshl_add_u64 v[206:207], s[88:89], 0, v[220:221]
	global_store_dwordx4 v[206:207], v[132:135], off
	s_nop 1
	v_sub_f32_e32 v133, v211, v218
	v_sub_f32_e32 v132, v210, v218
	v_sub_f32_e32 v135, v213, v218
	v_sub_f32_e32 v134, v212, v218
	v_pk_mul_f32 v[134:135], v[218:219], v[134:135] op_sel:[1,0]
	v_pk_mul_f32 v[132:133], v[218:219], v[132:133] op_sel:[1,0]
	v_pk_fma_f32 v[130:131], v[188:189], v[134:135], v[130:131]
	v_pk_fma_f32 v[128:129], v[190:191], v[132:133], v[128:129]
	v_or_b32_e32 v132, 16, v148
	v_mov_b32_e32 v133, v159
	v_lshl_add_u64 v[132:133], v[132:133], 2, s[88:89]
	s_waitcnt vmcnt(0)
;     template <bool LN, int BJ, int LO, int HI> DI void batch(const f32x4 (&acc)[2][2][4][2], unsigned row0, unsigned col0, const f32x4 (&gv)[2], const f32x4 (&bv)[2]) const {
;         f32x4 r[HI - LO]; float mean[(HI - LO) / 2], rstd[(HI - LO) / 2];
; #pragma unroll
;         for (int i = LO; i < HI; ++i) { const int ai = i >> 3, m = (i >> 1) & 3, n = i & 1; const unsigned row = row0 + ai * HALF + m * 16;
;             if (n == 0) { mean[(i - LO) >> 1] = 0.f; rstd[(i - LO) >> 1] = 1.f;
;                 if (LN) { const float2 st = *(const float2*)(stats + row * 2u); mean[(i - LO) >> 1] = st.x; rstd[(i - LO) >> 1] = st.y; } }
;             r[i - LO] = *(const f32x4*)(src + (row * (unsigned)DM + col0 + BJ * HALF + n * 16)); }
; #pragma unroll
;         for (int i = LO; i < HI; ++i) { const int ai = i >> 3, m = (i >> 1) & 3, n = i & 1; const unsigned row = row0 + ai * HALF + m * 16;
;             *(f32x4*)(Y + (row * (unsigned)DM + col0 + BJ * HALF + n * 16)) = acc[ai][BJ][m][n] + ((r[i - LO] - mean[(i - LO) >> 1]) * rstd[(i - LO) >> 1]) * gv[n] + bv[n]; }
	v_pk_fma_f32 v[130:131], v[98:99], s[78:79], v[130:131] op_sel_hi:[1,0,1]
	v_pk_fma_f32 v[128:129], v[96:97], s[78:79], v[128:129] op_sel_hi:[1,0,1]
	global_store_dwordx4 v[132:133], v[128:131], off
	s_nop 1
	v_sub_f32_e32 v129, v215, v196
	v_sub_f32_e32 v128, v214, v196
	v_sub_f32_e32 v131, v217, v196
	v_sub_f32_e32 v130, v216, v196
	v_pk_mul_f32 v[130:131], v[196:197], v[130:131] op_sel:[1,0]
	v_pk_mul_f32 v[128:129], v[196:197], v[128:129] op_sel:[1,0]
	v_pk_fma_f32 v[126:127], v[192:193], v[130:131], v[126:127]
	v_pk_fma_f32 v[124:125], v[194:195], v[128:129], v[124:125]
	v_add_u32_e32 v128, 0x8000, v148
	v_mov_b32_e32 v129, v159
	v_pk_fma_f32 v[126:127], v[102:103], s[78:79], v[126:127] op_sel_hi:[1,0,1]
	v_pk_fma_f32 v[124:125], v[100:101], s[78:79], v[124:125] op_sel_hi:[1,0,1]
	v_lshl_add_u64 v[128:129], v[128:129], 2, s[88:89]
	global_store_dwordx4 v[128:129], v[124:127], off
	s_nop 1
	v_sub_f32_e32 v125, v137, v196
	v_sub_f32_e32 v124, v136, v196
	v_sub_f32_e32 v127, v139, v196
	v_sub_f32_e32 v126, v138, v196
	v_pk_mul_f32 v[126:127], v[196:197], v[126:127] op_sel:[1,0]
	v_pk_mul_f32 v[124:125], v[196:197], v[124:125] op_sel:[1,0]
	v_pk_fma_f32 v[122:123], v[188:189], v[126:127], v[122:123]
	v_pk_fma_f32 v[120:121], v[190:191], v[124:125], v[120:121]
	v_add_u32_e32 v124, 0x8010, v148
	v_mov_b32_e32 v125, v159
	v_pk_fma_f32 v[122:123], v[98:99], s[78:79], v[122:123] op_sel_hi:[1,0,1]
	v_pk_fma_f32 v[120:121], v[96:97], s[78:79], v[120:121] op_sel_hi:[1,0,1]
	v_lshl_add_u64 v[124:125], v[124:125], 2, s[88:89]
	global_store_dwordx4 v[124:125], v[120:123], off
	s_nop 1
	v_or_b32_e32 v122, 32, v203
	v_lshlrev_b32_e32 v124, 11, v122
	v_lshlrev_b32_e32 v120, 1, v122
	v_mov_b32_e32 v121, v159
	v_add_u32_e32 v122, v124, v158
	v_mov_b32_e32 v123, v159
	v_lshl_add_u64 v[120:121], v[120:121], 2, s[96:97]
	v_lshl_add_u64 v[122:123], v[122:123], 2, s[90:91]
	global_load_dwordx2 v[138:139], v[120:121], off
	global_load_dwordx4 v[126:129], v[122:123], off
	v_add_u32_e32 v122, v124, v204
	v_mov_b32_e32 v123, v159
	v_lshl_add_u64 v[122:123], v[122:123], 2, s[90:91]
	global_load_dwordx4 v[130:133], v[122:123], off
	v_or_b32_e32 v125, 48, v203
	v_lshlrev_b32_e32 v122, 1, v125
	v_lshlrev_b32_e32 v125, 11, v125
	v_mov_b32_e32 v123, v159
	v_add_u32_e32 v134, v125, v158
	v_mov_b32_e32 v135, v159
	v_lshl_add_u64 v[122:123], v[122:123], 2, s[96:97]
	v_lshl_add_u64 v[134:135], v[134:135], 2, s[90:91]
	global_load_dwordx2 v[196:197], v[122:123], off
	v_add_u32_e32 v206, v125, v204
	global_load_dwordx4 v[134:137], v[134:135], off
	v_mov_b32_e32 v207, v159
	v_lshl_add_u64 v[206:207], v[206:207], 2, s[90:91]
	global_load_dwordx4 v[206:209], v[206:207], off
	s_waitcnt vmcnt(0)
	v_sub_f32_e32 v127, v127, v138
	v_sub_f32_e32 v126, v126, v138
	v_sub_f32_e32 v129, v129, v138
	v_sub_f32_e32 v128, v128, v138
	v_pk_mul_f32 v[128:129], v[138:139], v[128:129] op_sel:[1,0]
	v_pk_mul_f32 v[126:127], v[138:139], v[126:127] op_sel:[1,0]
	v_pk_fma_f32 v[118:119], v[192:193], v[128:129], v[118:119]
	v_pk_fma_f32 v[116:117], v[194:195], v[126:127], v[116:117]
	v_add_u32_e32 v126, 0x10000, v148
	v_mov_b32_e32 v127, v159
	v_pk_fma_f32 v[118:119], v[102:103], s[78:79], v[118:119] op_sel_hi:[1,0,1]
	v_pk_fma_f32 v[116:117], v[100:101], s[78:79], v[116:117] op_sel_hi:[1,0,1]
	v_lshl_add_u64 v[126:127], v[126:127], 2, s[88:89]
	global_store_dwordx4 v[126:127], v[116:119], off
	s_nop 1
	v_sub_f32_e32 v117, v131, v138
	v_sub_f32_e32 v116, v130, v138
	v_sub_f32_e32 v119, v133, v138
	v_sub_f32_e32 v118, v132, v138
	v_pk_mul_f32 v[118:119], v[138:139], v[118:119] op_sel:[1,0]
	v_pk_mul_f32 v[116:117], v[138:139], v[116:117] op_sel:[1,0]
	v_pk_fma_f32 v[114:115], v[188:189], v[118:119], v[114:115]
	v_pk_fma_f32 v[112:113], v[190:191], v[116:117], v[112:113]
	v_add_u32_e32 v116, 0x10010, v148
	v_mov_b32_e32 v117, v159
	v_pk_fma_f32 v[114:115], v[98:99], s[78:79], v[114:115] op_sel_hi:[1,0,1]
	v_pk_fma_f32 v[112:113], v[96:97], s[78:79], v[112:113] op_sel_hi:[1,0,1]
	v_lshl_add_u64 v[116:117], v[116:117], 2, s[88:89]
	global_store_dwordx4 v[116:117], v[112:115], off
	s_nop 1
	v_sub_f32_e32 v113, v135, v196
	v_sub_f32_e32 v112, v134, v196
	v_sub_f32_e32 v115, v137, v196
	v_sub_f32_e32 v114, v136, v196
	v_pk_mul_f32 v[114:115], v[196:197], v[114:115] op_sel:[1,0]
	v_pk_mul_f32 v[112:113], v[196:197], v[112:113] op_sel:[1,0]
	v_pk_fma_f32 v[110:111], v[192:193], v[114:115], v[110:111]
	v_pk_fma_f32 v[108:109], v[194:195], v[112:113], v[108:109]
	v_add_u32_e32 v112, 0x18000, v148
	v_mov_b32_e32 v113, v159
	v_pk_fma_f32 v[110:111], v[102:103], s[78:79], v[110:111] op_sel_hi:[1,0,1]
	v_pk_fma_f32 v[108:109], v[100:101], s[78:79], v[108:109] op_sel_hi:[1,0,1]
	v_lshl_add_u64 v[112:113], v[112:113], 2, s[88:89]
	global_store_dwordx4 v[112:113], v[108:111], off
	s_nop 1
	v_sub_f32_e32 v109, v207, v196
	v_sub_f32_e32 v108, v206, v196
	v_sub_f32_e32 v111, v209, v196
	v_sub_f32_e32 v110, v208, v196
	v_pk_mul_f32 v[110:111], v[196:197], v[110:111] op_sel:[1,0]
	v_pk_mul_f32 v[108:109], v[196:197], v[108:109] op_sel:[1,0]
	v_pk_fma_f32 v[106:107], v[188:189], v[110:111], v[106:107]
	v_pk_fma_f32 v[104:105], v[190:191], v[108:109], v[104:105]
	v_add_u32_e32 v108, 0x18010, v148
	v_mov_b32_e32 v109, v159
	v_pk_fma_f32 v[106:107], v[98:99], s[78:79], v[106:107] op_sel_hi:[1,0,1]
	v_pk_fma_f32 v[104:105], v[96:97], s[78:79], v[104:105] op_sel_hi:[1,0,1]
	v_lshl_add_u64 v[108:109], v[108:109], 2, s[88:89]
	global_store_dwordx4 v[108:109], v[104:107], off
	s_nop 1
	v_add_u32_e32 v106, 0x80, v203
	v_lshlrev_b32_e32 v114, 11, v106
	v_lshlrev_b32_e32 v104, 1, v106
	v_mov_b32_e32 v105, v159
	v_add_u32_e32 v106, v114, v158
	v_mov_b32_e32 v107, v159
	v_lshl_add_u64 v[104:105], v[104:105], 2, s[96:97]
	v_lshl_add_u64 v[106:107], v[106:107], 2, s[90:91]
	global_load_dwordx2 v[112:113], v[104:105], off
	global_load_dwordx4 v[108:111], v[106:107], off
	v_add_u32_e32 v106, v114, v204
	v_mov_b32_e32 v107, v159
	v_lshl_add_u64 v[106:107], v[106:107], 2, s[90:91]
	global_load_dwordx4 v[116:119], v[106:107], off
	v_add_u32_e32 v115, 0x90, v203
	v_lshlrev_b32_e32 v106, 1, v115
	v_lshlrev_b32_e32 v115, 11, v115
	v_mov_b32_e32 v107, v159
	v_add_u32_e32 v126, v115, v158
	v_mov_b32_e32 v127, v159
	v_lshl_add_u64 v[106:107], v[106:107], 2, s[96:97]
	v_lshl_add_u64 v[126:127], v[126:127], 2, s[90:91]
	global_load_dwordx2 v[134:135], v[106:107], off
	v_add_u32_e32 v130, v115, v204
	global_load_dwordx4 v[126:129], v[126:127], off
	v_mov_b32_e32 v131, v159
	v_lshl_add_u64 v[130:131], v[130:131], 2, s[90:91]
	global_load_dwordx4 v[130:133], v[130:131], off
	s_waitcnt vmcnt(0)
;     template <bool LN, int BJ, int LO, int HI> DI void batch(const f32x4 (&acc)[2][2][4][2], unsigned row0, unsigned col0, const f32x4 (&gv)[2], const f32x4 (&bv)[2]) const {
;         f32x4 r[HI - LO]; float mean[(HI - LO) / 2], rstd[(HI - LO) / 2];
; #pragma unroll
;         for (int i = LO; i < HI; ++i) { const int ai = i >> 3, m = (i >> 1) & 3, n = i & 1; const unsigned row = row0 + ai * HALF + m * 16;
;             if (n == 0) { mean[(i - LO) >> 1] = 0.f; rstd[(i - LO) >> 1] = 1.f;
;                 if (LN) { const float2 st = *(const float2*)(stats + row * 2u); mean[(i - LO) >> 1] = st.x; rstd[(i - LO) >> 1] = st.y; } }
;             r[i - LO] = *(const f32x4*)(src + (row * (unsigned)DM + col0 + BJ * HALF + n * 16)); }
; #pragma unroll
;         for (int i = LO; i < HI; ++i) { const int ai = i >> 3, m = (i >> 1) & 3, n = i & 1; const unsigned row = row0 + ai * HALF + m * 16;
;             *(f32x4*)(Y + (row * (unsigned)DM + col0 + BJ * HALF + n * 16)) = acc[ai][BJ][m][n] + ((r[i - LO] - mean[(i - LO) >> 1]) * rstd[(i - LO) >> 1]) * gv[n] + bv[n]; }
;     template <bool LN, int BJ> DI void load_gb(unsigned col0, f32x4 (&gv)[2], f32x4 (&bv)[2]) const {
; #pragma unroll
;         for (int n = 0; n < 2; ++n) {
;             if (LN) { gv[n] = *(const f32x4*)(gam + col0 + BJ * HALF + n * 16) * ALPHA; bv[n] = *(const f32x4*)(bet + col0 + BJ * HALF + n * 16) * ALPHA; }
;             else { gv[n] = (f32x4){ALPHA, ALPHA, ALPHA, ALPHA}; bv[n] = (f32x4){0.f, 0.f, 0.f, 0.f}; }
;         }
	v_sub_f32_e32 v109, v109, v112
	v_sub_f32_e32 v108, v108, v112
	v_sub_f32_e32 v111, v111, v112
	v_sub_f32_e32 v110, v110, v112
	v_pk_mul_f32 v[110:111], v[112:113], v[110:111] op_sel:[1,0]
	v_pk_mul_f32 v[108:109], v[112:113], v[108:109] op_sel:[1,0]
	v_pk_fma_f32 v[94:95], v[192:193], v[110:111], v[94:95]
	v_pk_fma_f32 v[92:93], v[194:195], v[108:109], v[92:93]
	v_add_u32_e32 v108, 0x40000, v148
	v_mov_b32_e32 v109, v159
	v_pk_fma_f32 v[94:95], v[102:103], s[78:79], v[94:95] op_sel_hi:[1,0,1]
	v_pk_fma_f32 v[92:93], v[100:101], s[78:79], v[92:93] op_sel_hi:[1,0,1]
	v_lshl_add_u64 v[108:109], v[108:109], 2, s[88:89]
	global_store_dwordx4 v[108:109], v[92:95], off
	s_nop 1
	v_sub_f32_e32 v93, v117, v112
	v_sub_f32_e32 v92, v116, v112
	v_sub_f32_e32 v95, v119, v112
	v_sub_f32_e32 v94, v118, v112
	v_pk_mul_f32 v[94:95], v[112:113], v[94:95] op_sel:[1,0]
	v_pk_mul_f32 v[92:93], v[112:113], v[92:93] op_sel:[1,0]
	v_pk_fma_f32 v[90:91], v[188:189], v[94:95], v[90:91]
	v_pk_fma_f32 v[88:89], v[190:191], v[92:93], v[88:89]
	v_add_u32_e32 v92, 0x40010, v148
	v_mov_b32_e32 v93, v159
	v_pk_fma_f32 v[90:91], v[98:99], s[78:79], v[90:91] op_sel_hi:[1,0,1]
	v_pk_fma_f32 v[88:89], v[96:97], s[78:79], v[88:89] op_sel_hi:[1,0,1]
	v_lshl_add_u64 v[92:93], v[92:93], 2, s[88:89]
	global_store_dwordx4 v[92:93], v[88:91], off
	s_nop 1
	v_sub_f32_e32 v89, v127, v134
	v_sub_f32_e32 v88, v126, v134
	v_sub_f32_e32 v91, v129, v134
	v_sub_f32_e32 v90, v128, v134
	v_pk_mul_f32 v[90:91], v[134:135], v[90:91] op_sel:[1,0]
	v_pk_mul_f32 v[88:89], v[134:135], v[88:89] op_sel:[1,0]
	v_pk_fma_f32 v[86:87], v[192:193], v[90:91], v[86:87]
	v_pk_fma_f32 v[84:85], v[194:195], v[88:89], v[84:85]
	v_add_u32_e32 v88, 0x48000, v148
	v_mov_b32_e32 v89, v159
	v_pk_fma_f32 v[86:87], v[102:103], s[78:79], v[86:87] op_sel_hi:[1,0,1]
	v_pk_fma_f32 v[84:85], v[100:101], s[78:79], v[84:85] op_sel_hi:[1,0,1]
	v_lshl_add_u64 v[88:89], v[88:89], 2, s[88:89]
	global_store_dwordx4 v[88:89], v[84:87], off
	s_nop 1
	v_sub_f32_e32 v85, v131, v134
	v_sub_f32_e32 v84, v130, v134
	v_sub_f32_e32 v87, v133, v134
	v_sub_f32_e32 v86, v132, v134
	v_pk_mul_f32 v[86:87], v[134:135], v[86:87] op_sel:[1,0]
	v_pk_mul_f32 v[84:85], v[134:135], v[84:85] op_sel:[1,0]
	v_pk_fma_f32 v[82:83], v[188:189], v[86:87], v[82:83]
	v_pk_fma_f32 v[80:81], v[190:191], v[84:85], v[80:81]
	v_add_u32_e32 v84, 0x48010, v148
	v_mov_b32_e32 v85, v159
	v_pk_fma_f32 v[82:83], v[98:99], s[78:79], v[82:83] op_sel_hi:[1,0,1]
	v_pk_fma_f32 v[80:81], v[96:97], s[78:79], v[80:81] op_sel_hi:[1,0,1]
	v_lshl_add_u64 v[84:85], v[84:85], 2, s[88:89]
	global_store_dwordx4 v[84:85], v[80:83], off
	s_nop 1
	v_add_u32_e32 v82, 0xa0, v203
	v_lshlrev_b32_e32 v80, 1, v82
	v_mov_b32_e32 v81, v159
	v_lshlrev_b32_e32 v116, 11, v82
	v_lshl_add_u64 v[108:109], v[80:81], 2, s[96:97]
	v_add_u32_e32 v80, v116, v158
	v_lshl_add_u64 v[80:81], v[80:81], 2, s[90:91]
	global_load_dwordx2 v[112:113], v[108:109], off
	v_add_u32_e32 v84, v116, v204
	global_load_dwordx4 v[80:83], v[80:81], off
	v_mov_b32_e32 v85, v159
	v_lshl_add_u64 v[84:85], v[84:85], 2, s[90:91]
	global_load_dwordx4 v[84:87], v[84:85], off
	v_add_u32_e32 v90, 0xb0, v203
	v_lshlrev_b32_e32 v88, 1, v90
	v_mov_b32_e32 v89, v159
	v_lshlrev_b32_e32 v117, 11, v90
	v_lshl_add_u64 v[110:111], v[88:89], 2, s[96:97]
	v_add_u32_e32 v88, v117, v158
	v_lshl_add_u64 v[88:89], v[88:89], 2, s[90:91]
	global_load_dwordx2 v[118:119], v[110:111], off
	v_add_u32_e32 v92, v117, v204
	global_load_dwordx4 v[88:91], v[88:89], off
	v_mov_b32_e32 v93, v159
	v_lshl_add_u64 v[92:93], v[92:93], 2, s[90:91]
	global_load_dwordx4 v[92:95], v[92:93], off
	s_waitcnt vmcnt(0)
	v_sub_f32_e32 v81, v81, v112
	v_sub_f32_e32 v80, v80, v112
	v_sub_f32_e32 v83, v83, v112
	v_sub_f32_e32 v82, v82, v112
	v_pk_mul_f32 v[82:83], v[112:113], v[82:83] op_sel:[1,0]
	v_pk_mul_f32 v[80:81], v[112:113], v[80:81] op_sel:[1,0]
	v_pk_fma_f32 v[78:79], v[192:193], v[82:83], v[78:79]
	v_pk_fma_f32 v[76:77], v[194:195], v[80:81], v[76:77]
	v_add_u32_e32 v80, 0x50000, v148
	v_mov_b32_e32 v81, v159
	v_pk_fma_f32 v[78:79], v[102:103], s[78:79], v[78:79] op_sel_hi:[1,0,1]
	v_pk_fma_f32 v[76:77], v[100:101], s[78:79], v[76:77] op_sel_hi:[1,0,1]
	v_lshl_add_u64 v[80:81], v[80:81], 2, s[88:89]
	global_store_dwordx4 v[80:81], v[76:79], off
	s_nop 1
	v_sub_f32_e32 v77, v85, v112
	v_sub_f32_e32 v76, v84, v112
	v_sub_f32_e32 v79, v87, v112
	v_sub_f32_e32 v78, v86, v112
	v_pk_mul_f32 v[78:79], v[112:113], v[78:79] op_sel:[1,0]
	v_pk_mul_f32 v[76:77], v[112:113], v[76:77] op_sel:[1,0]
	v_pk_fma_f32 v[74:75], v[188:189], v[78:79], v[74:75]
	v_pk_fma_f32 v[72:73], v[190:191], v[76:77], v[72:73]
	v_add_u32_e32 v76, 0x50010, v148
	v_mov_b32_e32 v77, v159
	v_pk_fma_f32 v[74:75], v[98:99], s[78:79], v[74:75] op_sel_hi:[1,0,1]
	v_pk_fma_f32 v[72:73], v[96:97], s[78:79], v[72:73] op_sel_hi:[1,0,1]
	v_lshl_add_u64 v[76:77], v[76:77], 2, s[88:89]
	global_store_dwordx4 v[76:77], v[72:75], off
	s_nop 1
	v_sub_f32_e32 v73, v89, v118
	v_sub_f32_e32 v72, v88, v118
	v_sub_f32_e32 v75, v91, v118
	v_sub_f32_e32 v74, v90, v118
	v_pk_mul_f32 v[74:75], v[118:119], v[74:75] op_sel:[1,0]
	v_pk_mul_f32 v[72:73], v[118:119], v[72:73] op_sel:[1,0]
	v_pk_fma_f32 v[70:71], v[192:193], v[74:75], v[70:71]
	v_pk_fma_f32 v[68:69], v[194:195], v[72:73], v[68:69]
	v_add_u32_e32 v72, 0x58000, v148
	v_mov_b32_e32 v73, v159
	v_pk_fma_f32 v[70:71], v[102:103], s[78:79], v[70:71] op_sel_hi:[1,0,1]
	v_pk_fma_f32 v[68:69], v[100:101], s[78:79], v[68:69] op_sel_hi:[1,0,1]
	v_lshl_add_u64 v[72:73], v[72:73], 2, s[88:89]
	global_store_dwordx4 v[72:73], v[68:71], off
	s_nop 1
	v_sub_f32_e32 v69, v93, v118
	v_sub_f32_e32 v68, v92, v118
	v_sub_f32_e32 v71, v95, v118
	v_sub_f32_e32 v70, v94, v118
	v_pk_mul_f32 v[70:71], v[118:119], v[70:71] op_sel:[1,0]
	v_pk_mul_f32 v[68:69], v[118:119], v[68:69] op_sel:[1,0]
	v_pk_fma_f32 v[66:67], v[188:189], v[70:71], v[66:67]
	v_pk_fma_f32 v[64:65], v[190:191], v[68:69], v[64:65]
	v_add_u32_e32 v68, 0x58010, v148
	v_mov_b32_e32 v69, v159
	v_pk_fma_f32 v[66:67], v[98:99], s[78:79], v[66:67] op_sel_hi:[1,0,1]
	v_pk_fma_f32 v[64:65], v[96:97], s[78:79], v[64:65] op_sel_hi:[1,0,1]
	v_lshl_add_u64 v[68:69], v[68:69], 2, s[88:89]
	global_store_dwordx4 v[68:69], v[64:67], off
	global_load_dwordx4 v[64:67], v[150:151], off offset:512
	v_or_b32_e32 v119, 0x80, v158
	v_add_u32_e32 v72, v202, v119
	v_mov_b32_e32 v73, v159
	v_lshl_add_u64 v[72:73], v[72:73], 2, s[90:91]
	v_or_b32_e32 v118, 0x90, v158
	v_add_u32_e32 v158, v202, v118
	s_waitcnt vmcnt(0)
;     template <bool LN, int BJ, int LO, int HI> DI void batch(const f32x4 (&acc)[2][2][4][2], unsigned row0, unsigned col0, const f32x4 (&gv)[2], const f32x4 (&bv)[2]) const {
;         f32x4 r[HI - LO]; float mean[(HI - LO) / 2], rstd[(HI - LO) / 2];
; #pragma unroll
;         for (int i = LO; i < HI; ++i) { const int ai = i >> 3, m = (i >> 1) & 3, n = i & 1; const unsigned row = row0 + ai * HALF + m * 16;
;             if (n == 0) { mean[(i - LO) >> 1] = 0.f; rstd[(i - LO) >> 1] = 1.f;
;                 if (LN) { const float2 st = *(const float2*)(stats + row * 2u); mean[(i - LO) >> 1] = st.x; rstd[(i - LO) >> 1] = st.y; } }
;             r[i - LO] = *(const f32x4*)(src + (row * (unsigned)DM + col0 + BJ * HALF + n * 16)); }
; #pragma unroll
;         for (int i = LO; i < HI; ++i) { const int ai = i >> 3, m = (i >> 1) & 3, n = i & 1; const unsigned row = row0 + ai * HALF + m * 16;
;             *(f32x4*)(Y + (row * (unsigned)DM + col0 + BJ * HALF + n * 16)) = acc[ai][BJ][m][n] + ((r[i - LO] - mean[(i - LO) >> 1]) * rstd[(i - LO) >> 1]) * gv[n] + bv[n]; }
;     template <bool LN, int BJ> DI void load_gb(unsigned col0, f32x4 (&gv)[2], f32x4 (&bv)[2]) const {
; #pragma unroll
;         for (int n = 0; n < 2; ++n) {
;             if (LN) { gv[n] = *(const f32x4*)(gam + col0 + BJ * HALF + n * 16) * ALPHA; bv[n] = *(const f32x4*)(bet + col0 + BJ * HALF + n * 16) * ALPHA; }
;             else { gv[n] = (f32x4){ALPHA, ALPHA, ALPHA, ALPHA}; bv[n] = (f32x4){0.f, 0.f, 0.f, 0.f}; }
;         }
	v_pk_mul_f32 v[96:97], v[66:67], s[78:79] op_sel_hi:[1,0]
	v_pk_mul_f32 v[98:99], v[64:65], s[78:79] op_sel_hi:[1,0]
	global_load_dwordx4 v[68:71], v[152:153], off offset:512
	global_load_dwordx4 v[64:67], v[150:151], off offset:576
	global_load_dwordx2 v[138:139], v[154:155], off
	global_load_dwordx4 v[126:129], v[72:73], off
	v_lshl_add_u64 v[72:73], v[158:159], 2, s[90:91]
	v_add_u32_e32 v158, v149, v119
	s_waitcnt vmcnt(0)
	v_pk_mul_f32 v[92:93], v[66:67], s[78:79] op_sel_hi:[1,0]
	v_pk_mul_f32 v[94:95], v[64:65], s[78:79] op_sel_hi:[1,0]
	global_load_dwordx4 v[64:67], v[152:153], off offset:576
	global_load_dwordx4 v[130:133], v[72:73], off
	global_load_dwordx2 v[112:113], v[186:187], off
	v_lshl_add_u64 v[72:73], v[158:159], 2, s[90:91]
	global_load_dwordx4 v[134:137], v[72:73], off
	v_add_u32_e32 v158, v149, v118
	v_lshl_add_u64 v[72:73], v[158:159], 2, s[90:91]
	global_load_dwordx4 v[88:91], v[72:73], off
	global_load_dwordx2 v[102:103], v[120:121], off
	v_add_u32_e32 v158, v124, v119
	v_lshl_add_u64 v[72:73], v[158:159], 2, s[90:91]
	global_load_dwordx4 v[84:87], v[72:73], off
	v_add_u32_e32 v158, v124, v118
	v_lshl_add_u64 v[72:73], v[158:159], 2, s[90:91]
	global_load_dwordx4 v[80:83], v[72:73], off
	global_load_dwordx2 v[100:101], v[122:123], off
	v_add_u32_e32 v158, v125, v119
	v_lshl_add_u64 v[72:73], v[158:159], 2, s[90:91]
	global_load_dwordx4 v[76:79], v[72:73], off
	v_add_u32_e32 v158, v125, v118
	v_lshl_add_u64 v[72:73], v[158:159], 2, s[90:91]
	global_load_dwordx4 v[72:75], v[72:73], off
	v_sub_f32_e32 v121, v127, v138
	v_sub_f32_e32 v120, v126, v138
	v_sub_f32_e32 v123, v129, v138
	v_sub_f32_e32 v122, v128, v138
	v_pk_mul_f32 v[122:123], v[138:139], v[122:123] op_sel:[1,0]
	v_pk_mul_f32 v[120:121], v[138:139], v[120:121] op_sel:[1,0]
	v_or_b32_e32 v158, 0x80, v148
	v_pk_fma_f32 v[60:61], v[98:99], v[120:121], v[60:61]
	v_pk_fma_f32 v[62:63], v[96:97], v[122:123], v[62:63]
	v_pk_fma_f32 v[60:61], v[68:69], s[78:79], v[60:61] op_sel_hi:[1,0,1]
	v_pk_fma_f32 v[62:63], v[70:71], s[78:79], v[62:63] op_sel_hi:[1,0,1]
	v_lshl_add_u64 v[120:121], v[158:159], 2, s[88:89]
	global_store_dwordx4 v[120:121], v[60:63], off
	v_or_b32_e32 v158, 0x90, v148
	s_waitcnt vmcnt(0)
	v_sub_f32_e32 v61, v131, v138
	v_sub_f32_e32 v60, v130, v138
	v_sub_f32_e32 v63, v133, v138
	v_sub_f32_e32 v62, v132, v138
	v_pk_mul_f32 v[62:63], v[138:139], v[62:63] op_sel:[1,0]
	v_pk_mul_f32 v[60:61], v[138:139], v[60:61] op_sel:[1,0]
	v_pk_fma_f32 v[58:59], v[92:93], v[62:63], v[58:59]
	v_pk_fma_f32 v[56:57], v[94:95], v[60:61], v[56:57]
	v_pk_fma_f32 v[58:59], v[66:67], s[78:79], v[58:59] op_sel_hi:[1,0,1]
	v_pk_fma_f32 v[56:57], v[64:65], s[78:79], v[56:57] op_sel_hi:[1,0,1]
	v_lshl_add_u64 v[60:61], v[158:159], 2, s[88:89]
	global_store_dwordx4 v[60:61], v[56:59], off
	v_add_u32_e32 v158, 0x8080, v148
	s_nop 0
	v_sub_f32_e32 v57, v135, v112
	v_sub_f32_e32 v56, v134, v112
	v_sub_f32_e32 v59, v137, v112
	v_sub_f32_e32 v58, v136, v112
	v_pk_mul_f32 v[58:59], v[112:113], v[58:59] op_sel:[1,0]
	v_pk_mul_f32 v[56:57], v[112:113], v[56:57] op_sel:[1,0]
	v_pk_fma_f32 v[54:55], v[96:97], v[58:59], v[54:55]
	v_pk_fma_f32 v[52:53], v[98:99], v[56:57], v[52:53]
	v_pk_fma_f32 v[54:55], v[70:71], s[78:79], v[54:55] op_sel_hi:[1,0,1]
	v_pk_fma_f32 v[52:53], v[68:69], s[78:79], v[52:53] op_sel_hi:[1,0,1]
	v_lshl_add_u64 v[56:57], v[158:159], 2, s[88:89]
	global_store_dwordx4 v[56:57], v[52:55], off
	v_add_u32_e32 v158, 0x8090, v148
	s_nop 0
	v_sub_f32_e32 v53, v89, v112
	v_sub_f32_e32 v52, v88, v112
	v_sub_f32_e32 v55, v91, v112
	v_sub_f32_e32 v54, v90, v112
	v_pk_mul_f32 v[54:55], v[112:113], v[54:55] op_sel:[1,0]
	v_pk_mul_f32 v[52:53], v[112:113], v[52:53] op_sel:[1,0]
	v_pk_fma_f32 v[50:51], v[92:93], v[54:55], v[50:51]
	v_pk_fma_f32 v[48:49], v[94:95], v[52:53], v[48:49]
	v_pk_fma_f32 v[50:51], v[66:67], s[78:79], v[50:51] op_sel_hi:[1,0,1]
	v_pk_fma_f32 v[48:49], v[64:65], s[78:79], v[48:49] op_sel_hi:[1,0,1]
	v_lshl_add_u64 v[52:53], v[158:159], 2, s[88:89]
	global_store_dwordx4 v[52:53], v[48:51], off
	v_add_u32_e32 v158, 0x10080, v148
	s_nop 0
	v_sub_f32_e32 v49, v85, v102
	v_sub_f32_e32 v48, v84, v102
	v_sub_f32_e32 v51, v87, v102
	v_sub_f32_e32 v50, v86, v102
	v_pk_mul_f32 v[50:51], v[102:103], v[50:51] op_sel:[1,0]
	v_pk_mul_f32 v[48:49], v[102:103], v[48:49] op_sel:[1,0]
	v_pk_fma_f32 v[46:47], v[96:97], v[50:51], v[46:47]
	v_pk_fma_f32 v[44:45], v[98:99], v[48:49], v[44:45]
	v_pk_fma_f32 v[46:47], v[70:71], s[78:79], v[46:47] op_sel_hi:[1,0,1]
	v_pk_fma_f32 v[44:45], v[68:69], s[78:79], v[44:45] op_sel_hi:[1,0,1]
	v_lshl_add_u64 v[48:49], v[158:159], 2, s[88:89]
	global_store_dwordx4 v[48:49], v[44:47], off
	v_add_u32_e32 v158, 0x10090, v148
	s_nop 0
	v_sub_f32_e32 v45, v81, v102
	v_sub_f32_e32 v44, v80, v102
	v_sub_f32_e32 v47, v83, v102
	v_sub_f32_e32 v46, v82, v102
	v_pk_mul_f32 v[46:47], v[102:103], v[46:47] op_sel:[1,0]
	v_pk_mul_f32 v[44:45], v[102:103], v[44:45] op_sel:[1,0]
	v_pk_fma_f32 v[42:43], v[92:93], v[46:47], v[42:43]
	v_pk_fma_f32 v[40:41], v[94:95], v[44:45], v[40:41]
	v_pk_fma_f32 v[42:43], v[66:67], s[78:79], v[42:43] op_sel_hi:[1,0,1]
	v_pk_fma_f32 v[40:41], v[64:65], s[78:79], v[40:41] op_sel_hi:[1,0,1]
	v_lshl_add_u64 v[44:45], v[158:159], 2, s[88:89]
	global_store_dwordx4 v[44:45], v[40:43], off
	v_add_u32_e32 v158, 0x18080, v148
	s_nop 0
	v_sub_f32_e32 v41, v77, v100
	v_sub_f32_e32 v40, v76, v100
	v_sub_f32_e32 v43, v79, v100
	v_sub_f32_e32 v42, v78, v100
	v_pk_mul_f32 v[42:43], v[100:101], v[42:43] op_sel:[1,0]
	v_pk_mul_f32 v[40:41], v[100:101], v[40:41] op_sel:[1,0]
	v_pk_fma_f32 v[38:39], v[96:97], v[42:43], v[38:39]
;     template <bool LN, int BJ, int LO, int HI> DI void batch(const f32x4 (&acc)[2][2][4][2], unsigned row0, unsigned col0, const f32x4 (&gv)[2], const f32x4 (&bv)[2]) const {
;         f32x4 r[HI - LO]; float mean[(HI - LO) / 2], rstd[(HI - LO) / 2];
; #pragma unroll
;         for (int i = LO; i < HI; ++i) { const int ai = i >> 3, m = (i >> 1) & 3, n = i & 1; const unsigned row = row0 + ai * HALF + m * 16;
;             if (n == 0) { mean[(i - LO) >> 1] = 0.f; rstd[(i - LO) >> 1] = 1.f;
;                 if (LN) { const float2 st = *(const float2*)(stats + row * 2u); mean[(i - LO) >> 1] = st.x; rstd[(i - LO) >> 1] = st.y; } }
;             r[i - LO] = *(const f32x4*)(src + (row * (unsigned)DM + col0 + BJ * HALF + n * 16)); }
; #pragma unroll
;         for (int i = LO; i < HI; ++i) { const int ai = i >> 3, m = (i >> 1) & 3, n = i & 1; const unsigned row = row0 + ai * HALF + m * 16;
;             *(f32x4*)(Y + (row * (unsigned)DM + col0 + BJ * HALF + n * 16)) = acc[ai][BJ][m][n] + ((r[i - LO] - mean[(i - LO) >> 1]) * rstd[(i - LO) >> 1]) * gv[n] + bv[n]; }
	v_pk_fma_f32 v[36:37], v[98:99], v[40:41], v[36:37]
	v_pk_fma_f32 v[38:39], v[70:71], s[78:79], v[38:39] op_sel_hi:[1,0,1]
	v_pk_fma_f32 v[36:37], v[68:69], s[78:79], v[36:37] op_sel_hi:[1,0,1]
	v_lshl_add_u64 v[40:41], v[158:159], 2, s[88:89]
	global_store_dwordx4 v[40:41], v[36:39], off
	v_add_u32_e32 v158, 0x18090, v148
	s_nop 0
	v_sub_f32_e32 v37, v73, v100
	v_sub_f32_e32 v36, v72, v100
	v_sub_f32_e32 v39, v75, v100
	v_sub_f32_e32 v38, v74, v100
	v_pk_mul_f32 v[38:39], v[100:101], v[38:39] op_sel:[1,0]
	v_pk_mul_f32 v[36:37], v[100:101], v[36:37] op_sel:[1,0]
	v_pk_fma_f32 v[34:35], v[92:93], v[38:39], v[34:35]
	v_pk_fma_f32 v[32:33], v[94:95], v[36:37], v[32:33]
	v_pk_fma_f32 v[34:35], v[66:67], s[78:79], v[34:35] op_sel_hi:[1,0,1]
	v_pk_fma_f32 v[32:33], v[64:65], s[78:79], v[32:33] op_sel_hi:[1,0,1]
	v_lshl_add_u64 v[36:37], v[158:159], 2, s[88:89]
	global_store_dwordx4 v[36:37], v[32:35], off
	v_add_u32_e32 v158, v114, v119
	s_nop 0
	v_lshl_add_u64 v[32:33], v[158:159], 2, s[90:91]
	global_load_dwordx2 v[62:63], v[104:105], off
	global_load_dwordx4 v[54:57], v[32:33], off
	v_add_u32_e32 v158, v114, v118
	v_lshl_add_u64 v[32:33], v[158:159], 2, s[90:91]
	global_load_dwordx4 v[58:61], v[32:33], off
	global_load_dwordx2 v[52:53], v[106:107], off
	v_add_u32_e32 v158, v115, v119
	v_lshl_add_u64 v[32:33], v[158:159], 2, s[90:91]
	global_load_dwordx4 v[72:75], v[32:33], off
	v_add_u32_e32 v158, v115, v118
	v_lshl_add_u64 v[32:33], v[158:159], 2, s[90:91]
	global_load_dwordx4 v[76:79], v[32:33], off
	global_load_dwordx2 v[50:51], v[108:109], off
	v_add_u32_e32 v158, v116, v119
	v_lshl_add_u64 v[32:33], v[158:159], 2, s[90:91]
	global_load_dwordx4 v[44:47], v[32:33], off
	v_add_u32_e32 v158, v116, v118
	v_lshl_add_u64 v[32:33], v[158:159], 2, s[90:91]
	global_load_dwordx4 v[40:43], v[32:33], off
	global_load_dwordx2 v[48:49], v[110:111], off
	v_add_u32_e32 v158, v117, v119
	v_lshl_add_u64 v[32:33], v[158:159], 2, s[90:91]
	global_load_dwordx4 v[36:39], v[32:33], off
	v_add_u32_e32 v158, v117, v118
	v_lshl_add_u64 v[32:33], v[158:159], 2, s[90:91]
	global_load_dwordx4 v[32:35], v[32:33], off
	v_add_u32_e32 v158, 0x40080, v148
	s_waitcnt vmcnt(0)
; #define PG8_WAIT_V(n) asm volatile("s_waitcnt vmcnt(" #n ")" ::: "memory")
; #define PG8_BAR __builtin_amdgcn_s_barrier()
; template <class Epi>
; DI void gemm_phase(LAS unsigned char* lds, const Gemm g, const StaticOrder& S, const Epi& E) {
;     ...
;         E(acc, cur, wr, wc, fr, fq);
;         if (!has_next) break;
; #pragma unroll
;         for (int a = 0; a < 2; ++a)
; #pragma unroll
;             for (int b = 0; b < 2; ++b)
; #pragma unroll
;                 for (int m = 0; m < 4; ++m)
; #pragma unroll
;                     for (int n = 0; n < 2; ++n) acc[a][b][m][n] = (f32x4){0.f, 0.f, 0.f, 0.f};
;         cur = nxt; cA = nA; cB = nB; ++ui;
;     }
;     PG8_WAIT_V(0);
;     if (wr == 0) PG8_BAR;
;     template <bool LN, int BJ, int LO, int HI> DI void batch(const f32x4 (&acc)[2][2][4][2], unsigned row0, unsigned col0, const f32x4 (&gv)[2], const f32x4 (&bv)[2]) const {
;         f32x4 r[HI - LO]; float mean[(HI - LO) / 2], rstd[(HI - LO) / 2];
; #pragma unroll
;         for (int i = LO; i < HI; ++i) { const int ai = i >> 3, m = (i >> 1) & 3, n = i & 1; const unsigned row = row0 + ai * HALF + m * 16;
;             if (n == 0) { mean[(i - LO) >> 1] = 0.f; rstd[(i - LO) >> 1] = 1.f;
;                 if (LN) { const float2 st = *(const float2*)(stats + row * 2u); mean[(i - LO) >> 1] = st.x; rstd[(i - LO) >> 1] = st.y; } }
;             r[i - LO] = *(const f32x4*)(src + (row * (unsigned)DM + col0 + BJ * HALF + n * 16)); }
; #pragma unroll
;         for (int i = LO; i < HI; ++i) { const int ai = i >> 3, m = (i >> 1) & 3, n = i & 1; const unsigned row = row0 + ai * HALF + m * 16;
;             *(f32x4*)(Y + (row * (unsigned)DM + col0 + BJ * HALF + n * 16)) = acc[ai][BJ][m][n] + ((r[i - LO] - mean[(i - LO) >> 1]) * rstd[(i - LO) >> 1]) * gv[n] + bv[n]; }
	v_sub_f32_e32 v55, v55, v62
	v_sub_f32_e32 v54, v54, v62
	v_sub_f32_e32 v57, v57, v62
	v_sub_f32_e32 v56, v56, v62
	v_pk_mul_f32 v[56:57], v[62:63], v[56:57] op_sel:[1,0]
	v_pk_mul_f32 v[54:55], v[62:63], v[54:55] op_sel:[1,0]
	v_pk_fma_f32 v[30:31], v[96:97], v[56:57], v[30:31]
	v_pk_fma_f32 v[28:29], v[98:99], v[54:55], v[28:29]
	v_pk_fma_f32 v[30:31], v[70:71], s[78:79], v[30:31] op_sel_hi:[1,0,1]
	v_pk_fma_f32 v[28:29], v[68:69], s[78:79], v[28:29] op_sel_hi:[1,0,1]
	v_lshl_add_u64 v[54:55], v[158:159], 2, s[88:89]
	global_store_dwordx4 v[54:55], v[28:31], off
	v_add_u32_e32 v158, 0x40090, v148
	s_nop 0
	v_sub_f32_e32 v29, v59, v62
	v_sub_f32_e32 v28, v58, v62
	v_sub_f32_e32 v31, v61, v62
	v_sub_f32_e32 v30, v60, v62
	v_pk_mul_f32 v[30:31], v[62:63], v[30:31] op_sel:[1,0]
	v_pk_mul_f32 v[28:29], v[62:63], v[28:29] op_sel:[1,0]
	v_pk_fma_f32 v[26:27], v[92:93], v[30:31], v[26:27]
	v_pk_fma_f32 v[24:25], v[94:95], v[28:29], v[24:25]
	v_pk_fma_f32 v[26:27], v[66:67], s[78:79], v[26:27] op_sel_hi:[1,0,1]
	v_pk_fma_f32 v[24:25], v[64:65], s[78:79], v[24:25] op_sel_hi:[1,0,1]
	v_lshl_add_u64 v[28:29], v[158:159], 2, s[88:89]
	global_store_dwordx4 v[28:29], v[24:27], off
	v_add_u32_e32 v158, 0x48080, v148
	s_nop 0
	v_sub_f32_e32 v25, v73, v52
	v_sub_f32_e32 v24, v72, v52
	v_sub_f32_e32 v27, v75, v52
	v_sub_f32_e32 v26, v74, v52
	v_pk_mul_f32 v[26:27], v[52:53], v[26:27] op_sel:[1,0]
	v_pk_mul_f32 v[24:25], v[52:53], v[24:25] op_sel:[1,0]
	v_pk_fma_f32 v[22:23], v[96:97], v[26:27], v[22:23]
	v_pk_fma_f32 v[20:21], v[98:99], v[24:25], v[20:21]
	v_pk_fma_f32 v[22:23], v[70:71], s[78:79], v[22:23] op_sel_hi:[1,0,1]
	v_pk_fma_f32 v[20:21], v[68:69], s[78:79], v[20:21] op_sel_hi:[1,0,1]
	v_lshl_add_u64 v[24:25], v[158:159], 2, s[88:89]
	global_store_dwordx4 v[24:25], v[20:23], off
	v_add_u32_e32 v158, 0x48090, v148
	s_nop 0
	v_sub_f32_e32 v21, v77, v52
	v_sub_f32_e32 v20, v76, v52
	v_sub_f32_e32 v23, v79, v52
	v_sub_f32_e32 v22, v78, v52
	v_pk_mul_f32 v[22:23], v[52:53], v[22:23] op_sel:[1,0]
	v_pk_mul_f32 v[20:21], v[52:53], v[20:21] op_sel:[1,0]
	v_pk_fma_f32 v[18:19], v[92:93], v[22:23], v[18:19]
	v_pk_fma_f32 v[16:17], v[94:95], v[20:21], v[16:17]
	v_pk_fma_f32 v[18:19], v[66:67], s[78:79], v[18:19] op_sel_hi:[1,0,1]
	v_pk_fma_f32 v[16:17], v[64:65], s[78:79], v[16:17] op_sel_hi:[1,0,1]
	v_lshl_add_u64 v[20:21], v[158:159], 2, s[88:89]
	global_store_dwordx4 v[20:21], v[16:19], off
	v_add_u32_e32 v158, 0x50080, v148
	s_nop 0
	v_sub_f32_e32 v17, v45, v50
	v_sub_f32_e32 v16, v44, v50
	v_sub_f32_e32 v19, v47, v50
	v_sub_f32_e32 v18, v46, v50
	v_pk_mul_f32 v[18:19], v[50:51], v[18:19] op_sel:[1,0]
	v_pk_mul_f32 v[16:17], v[50:51], v[16:17] op_sel:[1,0]
	v_pk_fma_f32 v[14:15], v[96:97], v[18:19], v[14:15]
	v_pk_fma_f32 v[12:13], v[98:99], v[16:17], v[12:13]
	v_pk_fma_f32 v[14:15], v[70:71], s[78:79], v[14:15] op_sel_hi:[1,0,1]
	v_pk_fma_f32 v[12:13], v[68:69], s[78:79], v[12:13] op_sel_hi:[1,0,1]
	v_lshl_add_u64 v[16:17], v[158:159], 2, s[88:89]
	global_store_dwordx4 v[16:17], v[12:15], off
	v_add_u32_e32 v158, 0x50090, v148
	s_nop 0
	v_sub_f32_e32 v13, v41, v50
	v_sub_f32_e32 v12, v40, v50
	v_sub_f32_e32 v15, v43, v50
	v_sub_f32_e32 v14, v42, v50
	v_pk_mul_f32 v[14:15], v[50:51], v[14:15] op_sel:[1,0]
	v_pk_mul_f32 v[12:13], v[50:51], v[12:13] op_sel:[1,0]
	v_pk_fma_f32 v[10:11], v[92:93], v[14:15], v[10:11]
	v_pk_fma_f32 v[8:9], v[94:95], v[12:13], v[8:9]
	v_pk_fma_f32 v[10:11], v[66:67], s[78:79], v[10:11] op_sel_hi:[1,0,1]
	v_pk_fma_f32 v[8:9], v[64:65], s[78:79], v[8:9] op_sel_hi:[1,0,1]
	v_lshl_add_u64 v[12:13], v[158:159], 2, s[88:89]
	global_store_dwordx4 v[12:13], v[8:11], off
	v_add_u32_e32 v158, 0x58080, v148
	s_nop 0
	v_sub_f32_e32 v9, v37, v48
	v_sub_f32_e32 v8, v36, v48
	v_sub_f32_e32 v11, v39, v48
	v_sub_f32_e32 v10, v38, v48
	v_pk_mul_f32 v[10:11], v[48:49], v[10:11] op_sel:[1,0]
	v_pk_mul_f32 v[8:9], v[48:49], v[8:9] op_sel:[1,0]
	v_pk_fma_f32 v[6:7], v[96:97], v[10:11], v[6:7]
	v_pk_fma_f32 v[4:5], v[98:99], v[8:9], v[4:5]
	v_pk_fma_f32 v[6:7], v[70:71], s[78:79], v[6:7] op_sel_hi:[1,0,1]
	v_pk_fma_f32 v[4:5], v[68:69], s[78:79], v[4:5] op_sel_hi:[1,0,1]
	v_lshl_add_u64 v[8:9], v[158:159], 2, s[88:89]
	global_store_dwordx4 v[8:9], v[4:7], off
	v_add_u32_e32 v158, 0x58090, v148
	s_nop 0
	v_sub_f32_e32 v5, v33, v48
	v_sub_f32_e32 v4, v32, v48
	v_sub_f32_e32 v7, v35, v48
	v_sub_f32_e32 v6, v34, v48
	v_pk_mul_f32 v[6:7], v[48:49], v[6:7] op_sel:[1,0]
	v_pk_mul_f32 v[4:5], v[48:49], v[4:5] op_sel:[1,0]
	v_pk_fma_f32 v[2:3], v[92:93], v[6:7], v[2:3]
	v_pk_fma_f32 v[0:1], v[94:95], v[4:5], v[0:1]
	v_pk_fma_f32 v[2:3], v[66:67], s[78:79], v[2:3] op_sel_hi:[1,0,1]
	v_pk_fma_f32 v[0:1], v[64:65], s[78:79], v[0:1] op_sel_hi:[1,0,1]
	v_lshl_add_u64 v[4:5], v[158:159], 2, s[88:89]
	global_store_dwordx4 v[4:5], v[0:3], off
	s_and_b64 vcc, exec, s[6:7]
	s_mov_b32 s2, s37
	s_mov_b32 s3, s38
	s_mov_b64 s[18:19], s[10:11]
	s_mov_b64 s[16:17], s[8:9]
	v_readlane_b32 s33, v255, 39
	s_cbranch_vccz .LBB0_123
	s_waitcnt vmcnt(0)
	s_cmpk_gt_u32 s24, 0xff
	s_cbranch_scc1 .LBB0_138
	s_barrier

; #define PG8_STAGE(bufoff, gbase) do { _Pragma("unroll") for (int _i = 0; _i < 2; ++_i) \
;         __builtin_amdgcn_global_load_lds((const unsigned*)((const char*)(gbase) + voff[_i]), (LAS unsigned*)(lds + (bufoff) + ldsw + _i * 8192), 16, 0, 0); } while (0)
; #define PG8_LDA(dst, b, h) do { _Pragma("unroll") for (int m = 0; m < 4; ++m) _Pragma("unroll") for (int k = 0; k < 2; ++k) dst[m][k] = *(const LAS bf16x8*)(lds + PG8_SA(b, h) + aoff + m * 2048 + k * 1024); } while (0)
; #define PG8_LDB(dst, b, h) do { _Pragma("unroll") for (int n = 0; n < 2; ++n) _Pragma("unroll") for (int k = 0; k < 2; ++k) dst[n][k] = *(const LAS bf16x8*)(lds + PG8_SB(b, h) + boff + n * 2048 + k * 1024); } while (0)
; #define PG8_MMA(ai, bj, At, Bt) do { __builtin_amdgcn_s_setprio(1); _Pragma("unroll") for (int m = 0; m < 4; ++m) _Pragma("unroll") for (int n = 0; n < 2; ++n) _Pragma("unroll") for (int k = 0; k < 2; ++k) \
;         acc[ai][bj][m][n] = __builtin_amdgcn_mfma_f32_16x16x32_bf16(Bt[n][k], At[m][k], acc[ai][bj][m][n], 0, 0, 0); __builtin_amdgcn_s_setprio(0); } while (0)
; #define PG8_WAIT_V(n) asm volatile("s_waitcnt vmcnt(" #n ")" ::: "memory")
; #define PG8_WAIT_L(n) asm volatile("s_waitcnt lgkmcnt(" #n ")" ::: "memory")
; #define PG8_BAR __builtin_amdgcn_s_barrier()
; #define PG8_SCHED __builtin_amdgcn_sched_barrier(0)
; template <class Epi>
; DI void gemm_phase(LAS unsigned char* lds, const Gemm g, const StaticOrder& S, const Epi& E) {
;     ...
;             const bool last = (t == nt - 2);
;             const char* a1 = cA + (size_t)(t + 1) * kstep;
;             const char* a2 = last ? nA : cA + (size_t)(t + 2) * kstep; const char* b2 = last ? nB : cB + (size_t)(t + 2) * kstep;
;             const char* a3 = a2 + kstep; const char* b3 = b2 + kstep;
;             PG8_LDB(B0, 0, 0); PG8_SCHED; PG8_LDA(At, 0, 0); PG8_STAGE(PG8_SA(1, 1), a1 + hstep);
;             PG8_WAIT_L(8); PG8_BAR; PG8_WAIT_L(0); PG8_MMA(0, 0, At, B0); PG8_BAR; PG8_SCHED;
;             PG8_LDB(B1, 0, 1); PG8_STAGE(PG8_SB(0, 0), b2);
;             PG8_BAR; PG8_WAIT_L(0); PG8_MMA(0, 1, At, B1); PG8_BAR;
;             PG8_LDA(At, 0, 1); PG8_STAGE(PG8_SA(0, 0), a2);
;             PG8_BAR; PG8_WAIT_L(0); PG8_MMA(1, 0, At, B0); PG8_BAR; PG8_SCHED;
;             PG8_STAGE(PG8_SB(0, 1), b2 + hstep);
;             PG8_WAIT_V(6); PG8_BAR; PG8_MMA(1, 1, At, B1); PG8_BAR;
.LBB0_202:
	s_add_u32 s18, s8, 0xfff80080
	s_addc_u32 s19, s9, -1
	s_add_i32 s37, 0, 0x10000
	s_waitcnt lgkmcnt(0)
	ds_read_b128 v[128:131], v187
	ds_read_b128 v[132:135], v187 offset:1024
	ds_read_b128 v[136:139], v187 offset:2048
	ds_read_b128 v[190:193], v187 offset:3072
	s_cmp_eq_u32 s36, 28
	s_cselect_b32 s21, s4, s19
	s_cselect_b32 s20, s5, s18
	s_cselect_b32 s19, s11, s35
	s_cselect_b32 s18, s13, s33
	s_add_i32 m0, s26, 0xc000
	ds_read_b128 v[194:197], v189
	ds_read_b128 v[198:201], v189 offset:1024
	ds_read_b128 v[202:205], v189 offset:2048
	ds_read_b128 v[206:209], v189 offset:3072
	ds_read_b128 v[210:213], v189 offset:4096
	ds_read_b128 v[214:217], v189 offset:5120
	ds_read_b128 v[226:229], v189 offset:6144
	ds_read_b128 v[230:233], v189 offset:7168
	global_load_lds_dwordx4 v150, s[8:9]
	s_add_i32 m0, s26, 0xe000
	s_nop 0
	global_load_lds_dwordx4 v152, s[8:9]
	s_waitcnt lgkmcnt(8)
	s_setprio 1
	s_barrier
	s_waitcnt lgkmcnt(0)
	v_mfma_f32_16x16x32_bf16 v[124:127], v[128:131], v[194:197], v[124:127]
	v_mfma_f32_16x16x32_bf16 v[120:123], v[136:139], v[194:197], v[120:123]
	v_mfma_f32_16x16x32_bf16 v[108:111], v[128:131], v[202:205], v[108:111]
	v_mfma_f32_16x16x32_bf16 v[104:107], v[136:139], v[202:205], v[104:107]
	v_mfma_f32_16x16x32_bf16 v[92:95], v[128:131], v[210:213], v[92:95]
	v_mfma_f32_16x16x32_bf16 v[88:91], v[136:139], v[210:213], v[88:91]
	v_mfma_f32_16x16x32_bf16 v[76:79], v[128:131], v[226:229], v[76:79]
	v_mfma_f32_16x16x32_bf16 v[72:75], v[136:139], v[226:229], v[72:75]
	v_mfma_f32_16x16x32_bf16 v[124:127], v[132:135], v[198:201], v[124:127]
	v_mfma_f32_16x16x32_bf16 v[120:123], v[190:193], v[198:201], v[120:123]
	v_mfma_f32_16x16x32_bf16 v[108:111], v[132:135], v[206:209], v[108:111]
	v_mfma_f32_16x16x32_bf16 v[104:107], v[190:193], v[206:209], v[104:107]
	v_mfma_f32_16x16x32_bf16 v[92:95], v[132:135], v[214:217], v[92:95]
	v_mfma_f32_16x16x32_bf16 v[88:91], v[190:193], v[214:217], v[88:91]
	v_mfma_f32_16x16x32_bf16 v[76:79], v[132:135], v[230:233], v[76:79]
	s_setprio 0
	v_mfma_f32_16x16x32_bf16 v[72:75], v[190:193], v[230:233], v[72:75]
	s_barrier
	ds_read_b128 v[234:237], v187 offset:16384
	ds_read_b128 v[238:241], v187 offset:17408
	ds_read_b128 v[242:245], v187 offset:18432
	ds_read_b128 v[246:249], v187 offset:19456
	s_add_i32 s40, 0, 0x14000
	s_add_i32 s37, s37, s25
	s_mov_b32 m0, s37
	s_nop 0
	global_load_lds_dwordx4 v144, s[18:19]
	s_add_i32 m0, s37, 0x2000
	s_nop 0
	global_load_lds_dwordx4 v142, s[18:19]
	s_waitcnt lgkmcnt(0)
	s_setprio 1
	s_barrier
	v_mfma_f32_16x16x32_bf16 v[116:119], v[234:237], v[194:197], v[116:119]
	v_mfma_f32_16x16x32_bf16 v[112:115], v[242:245], v[194:197], v[112:115]
	v_mfma_f32_16x16x32_bf16 v[100:103], v[234:237], v[202:205], v[100:103]
	v_mfma_f32_16x16x32_bf16 v[96:99], v[242:245], v[202:205], v[96:99]
	v_mfma_f32_16x16x32_bf16 v[84:87], v[234:237], v[210:213], v[84:87]
	v_mfma_f32_16x16x32_bf16 v[80:83], v[242:245], v[210:213], v[80:83]
	v_mfma_f32_16x16x32_bf16 v[68:71], v[234:237], v[226:229], v[68:71]
	v_mfma_f32_16x16x32_bf16 v[64:67], v[242:245], v[226:229], v[64:67]
	v_mfma_f32_16x16x32_bf16 v[116:119], v[238:241], v[198:201], v[116:119]
	s_mov_b32 m0, s26
	v_mfma_f32_16x16x32_bf16 v[112:115], v[246:249], v[198:201], v[112:115]
	s_mov_b64 s[100:101], s[20:21]
	v_mfma_f32_16x16x32_bf16 v[100:103], v[238:241], v[206:209], v[100:103]
	v_mfma_f32_16x16x32_bf16 v[96:99], v[246:249], v[206:209], v[96:99]
	v_mfma_f32_16x16x32_bf16 v[84:87], v[238:241], v[214:217], v[84:87]
	v_mfma_f32_16x16x32_bf16 v[80:83], v[246:249], v[214:217], v[80:83]
	v_mfma_f32_16x16x32_bf16 v[68:71], v[238:241], v[230:233], v[68:71]
	s_setprio 0
	v_mfma_f32_16x16x32_bf16 v[64:67], v[246:249], v[230:233], v[64:67]
	s_barrier
	ds_read_b128 v[194:197], v189 offset:16384
	ds_read_b128 v[198:201], v189 offset:17408
	ds_read_b128 v[202:205], v189 offset:18432
	ds_read_b128 v[206:209], v189 offset:19456
	ds_read_b128 v[210:213], v189 offset:20480
	ds_read_b128 v[214:217], v189 offset:21504
	ds_read_b128 v[226:229], v189 offset:22528
	ds_read_b128 v[230:233], v189 offset:23552
	global_load_lds_dwordx4 v144, s[20:21]
	s_mov_b64 s[100:101], s[20:21]
	s_mov_b32 m0, s27
	s_nop 0
	global_load_lds_dwordx4 v142, s[20:21]
	s_waitcnt lgkmcnt(0)
	s_setprio 1
	s_barrier
	v_mfma_f32_16x16x32_bf16 v[60:63], v[128:131], v[194:197], v[60:63]
	v_mfma_f32_16x16x32_bf16 v[56:59], v[136:139], v[194:197], v[56:59]
	v_mfma_f32_16x16x32_bf16 v[44:47], v[128:131], v[202:205], v[44:47]
	v_mfma_f32_16x16x32_bf16 v[40:43], v[136:139], v[202:205], v[40:43]
	v_mfma_f32_16x16x32_bf16 v[28:31], v[128:131], v[210:213], v[28:31]
	v_mfma_f32_16x16x32_bf16 v[24:27], v[136:139], v[210:213], v[24:27]
	v_mfma_f32_16x16x32_bf16 v[12:15], v[128:131], v[226:229], v[12:15]
	v_mfma_f32_16x16x32_bf16 v[8:11], v[136:139], v[226:229], v[8:11]
	v_mfma_f32_16x16x32_bf16 v[60:63], v[132:135], v[198:201], v[60:63]
	v_mfma_f32_16x16x32_bf16 v[56:59], v[190:193], v[198:201], v[56:59]
	v_mfma_f32_16x16x32_bf16 v[44:47], v[132:135], v[206:209], v[44:47]
	v_mfma_f32_16x16x32_bf16 v[40:43], v[190:193], v[206:209], v[40:43]
	v_mfma_f32_16x16x32_bf16 v[28:31], v[132:135], v[214:217], v[28:31]
	v_mfma_f32_16x16x32_bf16 v[24:27], v[190:193], v[214:217], v[24:27]
	v_mfma_f32_16x16x32_bf16 v[12:15], v[132:135], v[230:233], v[12:15]
	s_setprio 0
	v_mfma_f32_16x16x32_bf16 v[8:11], v[190:193], v[230:233], v[8:11]
	s_barrier
	s_add_u32 s38, s18, 0x80000
	s_addc_u32 s39, s19, 0
	s_add_i32 s37, s40, s25
	s_mov_b32 m0, s37
	s_nop 0
	global_load_lds_dwordx4 v144, s[38:39]
	s_add_i32 m0, s37, 0x2000
	s_nop 0
	global_load_lds_dwordx4 v142, s[38:39]
	s_waitcnt vmcnt(6)
	s_setprio 1
	s_barrier
; #define PG8_STAGE(bufoff, gbase) do { _Pragma("unroll") for (int _i = 0; _i < 2; ++_i) \
;         __builtin_amdgcn_global_load_lds((const unsigned*)((const char*)(gbase) + voff[_i]), (LAS unsigned*)(lds + (bufoff) + ldsw + _i * 8192), 16, 0, 0); } while (0)
; #define PG8_LDA(dst, b, h) do { _Pragma("unroll") for (int m = 0; m < 4; ++m) _Pragma("unroll") for (int k = 0; k < 2; ++k) dst[m][k] = *(const LAS bf16x8*)(lds + PG8_SA(b, h) + aoff + m * 2048 + k * 1024); } while (0)
; #define PG8_LDB(dst, b, h) do { _Pragma("unroll") for (int n = 0; n < 2; ++n) _Pragma("unroll") for (int k = 0; k < 2; ++k) dst[n][k] = *(const LAS bf16x8*)(lds + PG8_SB(b, h) + boff + n * 2048 + k * 1024); } while (0)
; #define PG8_MMA(ai, bj, At, Bt) do { __builtin_amdgcn_s_setprio(1); _Pragma("unroll") for (int m = 0; m < 4; ++m) _Pragma("unroll") for (int n = 0; n < 2; ++n) _Pragma("unroll") for (int k = 0; k < 2; ++k) \
;         acc[ai][bj][m][n] = __builtin_amdgcn_mfma_f32_16x16x32_bf16(Bt[n][k], At[m][k], acc[ai][bj][m][n], 0, 0, 0); __builtin_amdgcn_s_setprio(0); } while (0)
; #define PG8_WAIT_V(n) asm volatile("s_waitcnt vmcnt(" #n ")" ::: "memory")
; #define PG8_WAIT_L(n) asm volatile("s_waitcnt lgkmcnt(" #n ")" ::: "memory")
; #define PG8_BAR __builtin_amdgcn_s_barrier()
; #define PG8_SCHED __builtin_amdgcn_sched_barrier(0)
; template <class Epi>
; DI void gemm_phase(LAS unsigned char* lds, const Gemm g, const StaticOrder& S, const Epi& E) {
;     ...
;             PG8_WAIT_V(6); PG8_BAR; PG8_MMA(1, 1, At, B1); PG8_BAR;
;             PG8_LDB(B0, 1, 0); PG8_SCHED; PG8_LDA(At, 1, 0); PG8_STAGE(PG8_SA(0, 1), a2 + hstep);
;             PG8_WAIT_L(8); PG8_BAR; PG8_WAIT_L(0); PG8_MMA(0, 0, At, B0); PG8_BAR; PG8_SCHED;
;             PG8_LDB(B1, 1, 1); PG8_STAGE(PG8_SB(1, 0), b3);
;             PG8_BAR; PG8_WAIT_L(0); PG8_MMA(0, 1, At, B1); PG8_BAR;
;             PG8_LDA(At, 1, 1); PG8_STAGE(PG8_SA(1, 0), a3);
;             PG8_BAR; PG8_WAIT_L(0); PG8_MMA(1, 0, At, B0); PG8_BAR; PG8_SCHED;
	v_mfma_f32_16x16x32_bf16 v[52:55], v[234:237], v[194:197], v[52:55]
	v_mfma_f32_16x16x32_bf16 v[48:51], v[242:245], v[194:197], v[48:51]
	v_mfma_f32_16x16x32_bf16 v[36:39], v[234:237], v[202:205], v[36:39]
	v_mfma_f32_16x16x32_bf16 v[32:35], v[242:245], v[202:205], v[32:35]
	v_mfma_f32_16x16x32_bf16 v[20:23], v[234:237], v[210:213], v[20:23]
	v_mfma_f32_16x16x32_bf16 v[16:19], v[242:245], v[210:213], v[16:19]
	v_mfma_f32_16x16x32_bf16 v[4:7], v[234:237], v[226:229], v[4:7]
	v_mfma_f32_16x16x32_bf16 v[0:3], v[242:245], v[226:229], v[0:3]
	v_mfma_f32_16x16x32_bf16 v[52:55], v[238:241], v[198:201], v[52:55]
	s_add_i32 s37, 0, 0x18000
	v_mfma_f32_16x16x32_bf16 v[48:51], v[246:249], v[198:201], v[48:51]
	v_mfma_f32_16x16x32_bf16 v[36:39], v[238:241], v[206:209], v[36:39]
	v_mfma_f32_16x16x32_bf16 v[32:35], v[246:249], v[206:209], v[32:35]
	v_mfma_f32_16x16x32_bf16 v[20:23], v[238:241], v[214:217], v[20:23]
	v_mfma_f32_16x16x32_bf16 v[16:19], v[246:249], v[214:217], v[16:19]
	v_mfma_f32_16x16x32_bf16 v[4:7], v[238:241], v[230:233], v[4:7]
	s_setprio 0
	v_mfma_f32_16x16x32_bf16 v[0:3], v[246:249], v[230:233], v[0:3]
	s_barrier
	ds_read_b128 v[128:131], v187 offset:32768
	ds_read_b128 v[132:135], v187 offset:33792
	ds_read_b128 v[136:139], v187 offset:34816
	ds_read_b128 v[190:193], v187 offset:35840
	ds_read_b128 v[194:197], v189 offset:32768
	ds_read_b128 v[198:201], v189 offset:33792
	ds_read_b128 v[202:205], v189 offset:34816
	ds_read_b128 v[206:209], v189 offset:35840
	ds_read_b128 v[210:213], v189 offset:36864
	ds_read_b128 v[214:217], v189 offset:37888
	ds_read_b128 v[226:229], v189 offset:38912
	ds_read_b128 v[230:233], v189 offset:39936
	s_add_u32 s20, s20, 0x80000
	s_addc_u32 s21, s21, 0
	s_mov_b32 m0, s28
	s_nop 0
	global_load_lds_dwordx4 v144, s[20:21]
	s_mov_b32 m0, s29
	s_nop 0
	global_load_lds_dwordx4 v142, s[20:21]
	s_waitcnt lgkmcnt(8)
	s_setprio 1
	s_barrier
	s_waitcnt lgkmcnt(0)
	v_mfma_f32_16x16x32_bf16 v[124:127], v[128:131], v[194:197], v[124:127]
	v_mfma_f32_16x16x32_bf16 v[120:123], v[136:139], v[194:197], v[120:123]
	v_mfma_f32_16x16x32_bf16 v[108:111], v[128:131], v[202:205], v[108:111]
	v_mfma_f32_16x16x32_bf16 v[104:107], v[136:139], v[202:205], v[104:107]
	v_mfma_f32_16x16x32_bf16 v[92:95], v[128:131], v[210:213], v[92:95]
	v_mfma_f32_16x16x32_bf16 v[88:91], v[136:139], v[210:213], v[88:91]
	v_mfma_f32_16x16x32_bf16 v[76:79], v[128:131], v[226:229], v[76:79]
	v_mfma_f32_16x16x32_bf16 v[72:75], v[136:139], v[226:229], v[72:75]
	v_mfma_f32_16x16x32_bf16 v[124:127], v[132:135], v[198:201], v[124:127]
	v_mfma_f32_16x16x32_bf16 v[120:123], v[190:193], v[198:201], v[120:123]
	v_mfma_f32_16x16x32_bf16 v[108:111], v[132:135], v[206:209], v[108:111]
	v_mfma_f32_16x16x32_bf16 v[104:107], v[190:193], v[206:209], v[104:107]
	v_mfma_f32_16x16x32_bf16 v[92:95], v[132:135], v[214:217], v[92:95]
	v_mfma_f32_16x16x32_bf16 v[88:91], v[190:193], v[214:217], v[88:91]
	v_mfma_f32_16x16x32_bf16 v[76:79], v[132:135], v[230:233], v[76:79]
	s_setprio 0
	v_mfma_f32_16x16x32_bf16 v[72:75], v[190:193], v[230:233], v[72:75]
	s_barrier
	ds_read_b128 v[234:237], v187 offset:49152
	ds_read_b128 v[238:241], v187 offset:50176
	ds_read_b128 v[242:245], v187 offset:51200
	ds_read_b128 v[246:249], v187 offset:52224
	s_add_i32 s20, 0, 0x1c000
	s_add_i32 s21, s37, s25
	s_add_i32 m0, s21, 0xffffff80
	s_nop 0
	global_load_lds_dwordx4 v144, s[18:19] offset:128
	s_add_i32 m0, s21, 0x1f80
	s_nop 0
	global_load_lds_dwordx4 v142, s[18:19] offset:128
	s_waitcnt lgkmcnt(0)
	s_setprio 1
	s_barrier
	v_mfma_f32_16x16x32_bf16 v[116:119], v[234:237], v[194:197], v[116:119]
	v_mfma_f32_16x16x32_bf16 v[112:115], v[242:245], v[194:197], v[112:115]
	v_mfma_f32_16x16x32_bf16 v[100:103], v[234:237], v[202:205], v[100:103]
	v_mfma_f32_16x16x32_bf16 v[96:99], v[242:245], v[202:205], v[96:99]
	v_mfma_f32_16x16x32_bf16 v[84:87], v[234:237], v[210:213], v[84:87]
	v_mfma_f32_16x16x32_bf16 v[80:83], v[242:245], v[210:213], v[80:83]
	v_mfma_f32_16x16x32_bf16 v[68:71], v[234:237], v[226:229], v[68:71]
	v_mfma_f32_16x16x32_bf16 v[64:67], v[242:245], v[226:229], v[64:67]
	v_mfma_f32_16x16x32_bf16 v[116:119], v[238:241], v[198:201], v[116:119]
	s_add_i32 m0, s30, 0xffffff80
	v_mfma_f32_16x16x32_bf16 v[112:115], v[246:249], v[198:201], v[112:115]
	v_mfma_f32_16x16x32_bf16 v[100:103], v[238:241], v[206:209], v[100:103]
	v_mfma_f32_16x16x32_bf16 v[96:99], v[246:249], v[206:209], v[96:99]
	v_mfma_f32_16x16x32_bf16 v[84:87], v[238:241], v[214:217], v[84:87]
	v_mfma_f32_16x16x32_bf16 v[80:83], v[246:249], v[214:217], v[80:83]
	v_mfma_f32_16x16x32_bf16 v[68:71], v[238:241], v[230:233], v[68:71]
	s_setprio 0
	v_mfma_f32_16x16x32_bf16 v[64:67], v[246:249], v[230:233], v[64:67]
	s_barrier
; #define PG8_STAGE(bufoff, gbase) do { _Pragma("unroll") for (int _i = 0; _i < 2; ++_i) \
;         __builtin_amdgcn_global_load_lds((const unsigned*)((const char*)(gbase) + voff[_i]), (LAS unsigned*)(lds + (bufoff) + ldsw + _i * 8192), 16, 0, 0); } while (0)
; #define PG8_LDA(dst, b, h) do { _Pragma("unroll") for (int m = 0; m < 4; ++m) _Pragma("unroll") for (int k = 0; k < 2; ++k) dst[m][k] = *(const LAS bf16x8*)(lds + PG8_SA(b, h) + aoff + m * 2048 + k * 1024); } while (0)
; #define PG8_LDB(dst, b, h) do { _Pragma("unroll") for (int n = 0; n < 2; ++n) _Pragma("unroll") for (int k = 0; k < 2; ++k) dst[n][k] = *(const LAS bf16x8*)(lds + PG8_SB(b, h) + boff + n * 2048 + k * 1024); } while (0)
; #define PG8_WAIT_V(n) asm volatile("s_waitcnt vmcnt(" #n ")" ::: "memory")
; #define PG8_WAIT_L(n) asm volatile("s_waitcnt lgkmcnt(" #n ")" ::: "memory")
; template <class Epi>
; DI void gemm_phase(LAS unsigned char* lds, const Gemm g, const StaticOrder& S, const Epi& E) {
;     ...
;             PG8_WAIT_V(6); PG8_BAR; PG8_MMA(1, 1, At, B1); PG8_BAR;
;             PG8_LDB(B0, 1, 0); PG8_SCHED; PG8_LDA(At, 1, 0); PG8_STAGE(PG8_SA(0, 1), a2 + hstep);
;             PG8_WAIT_L(8); PG8_BAR; PG8_WAIT_L(0); PG8_MMA(0, 0, At, B0); PG8_BAR; PG8_SCHED;
;             PG8_LDB(B1, 1, 1); PG8_STAGE(PG8_SB(1, 0), b3);
;             PG8_BAR; PG8_WAIT_L(0); PG8_MMA(0, 1, At, B1); PG8_BAR;
;             PG8_LDA(At, 1, 1); PG8_STAGE(PG8_SA(1, 0), a3);
;             PG8_BAR; PG8_WAIT_L(0); PG8_MMA(1, 0, At, B0); PG8_BAR; PG8_SCHED;
;             PG8_STAGE(PG8_SB(1, 1), b3 + hstep);
;             PG8_WAIT_V(6); PG8_BAR; PG8_MMA(1, 1, At, B1); PG8_BAR;
;     DI void operator()(const f32x4 (&acc)[2][2][4][2], const Unit& u, int wr, int wc, int fr, int fq) const {
;         const int row0 = u.pm * BM + wr * 64 + fr, col0 = u.pn * BM + wc * 16 + 4 * fq;
;         const bool rot = u.pn < 18;
; #pragma unroll
;         for (int ai = 0; ai < 2; ++ai)
; #pragma unroll
;             for (int m = 0; m < 4; ++m) { const int row = row0 + ai * HALF + m * 16; u16* rowp = O + (size_t)row * NQKV_DIL + col0;
;                 f32x4 c4 = (f32x4){1.f, 1.f, 1.f, 1.f}, s4 = (f32x4){0.f, 0.f, 0.f, 0.f};
;                 if (rot) { const int pos = row & (SEQ - 1); c4 = *(const f32x4*)(cs + pos * 64 + wc * 16 + 4 * fq); s4 = *(const f32x4*)(sn + pos * 64 + wc * 16 + 4 * fq); }
	ds_read_b128 v[194:197], v189 offset:49152
	ds_read_b128 v[198:201], v189 offset:50176
	ds_read_b128 v[202:205], v189 offset:51200
	ds_read_b128 v[206:209], v189 offset:52224
	ds_read_b128 v[210:213], v189 offset:53248
	ds_read_b128 v[214:217], v189 offset:54272
	ds_read_b128 v[226:229], v189 offset:55296
	ds_read_b128 v[230:233], v189 offset:56320
	global_load_lds_dwordx4 v144, s[100:101] offset:128
	s_add_i32 m0, s31, 0xffffff80
	s_nop 0
	global_load_lds_dwordx4 v142, s[100:101] offset:128
	s_waitcnt lgkmcnt(0)
	s_setprio 1
	s_barrier
	v_mfma_f32_16x16x32_bf16 v[60:63], v[128:131], v[194:197], v[60:63]
	v_mfma_f32_16x16x32_bf16 v[56:59], v[136:139], v[194:197], v[56:59]
	v_mfma_f32_16x16x32_bf16 v[44:47], v[128:131], v[202:205], v[44:47]
	v_mfma_f32_16x16x32_bf16 v[40:43], v[136:139], v[202:205], v[40:43]
	v_mfma_f32_16x16x32_bf16 v[28:31], v[128:131], v[210:213], v[28:31]
	v_mfma_f32_16x16x32_bf16 v[24:27], v[136:139], v[210:213], v[24:27]
	v_mfma_f32_16x16x32_bf16 v[12:15], v[128:131], v[226:229], v[12:15]
	v_mfma_f32_16x16x32_bf16 v[8:11], v[136:139], v[226:229], v[8:11]
	v_mfma_f32_16x16x32_bf16 v[60:63], v[132:135], v[198:201], v[60:63]
	v_mfma_f32_16x16x32_bf16 v[56:59], v[190:193], v[198:201], v[56:59]
	v_mfma_f32_16x16x32_bf16 v[44:47], v[132:135], v[206:209], v[44:47]
	v_mfma_f32_16x16x32_bf16 v[40:43], v[190:193], v[206:209], v[40:43]
	v_mfma_f32_16x16x32_bf16 v[28:31], v[132:135], v[214:217], v[28:31]
	v_mfma_f32_16x16x32_bf16 v[24:27], v[190:193], v[214:217], v[24:27]
	v_mfma_f32_16x16x32_bf16 v[12:15], v[132:135], v[230:233], v[12:15]
	s_setprio 0
	v_mfma_f32_16x16x32_bf16 v[8:11], v[190:193], v[230:233], v[8:11]
	s_barrier
	s_add_u32 s18, s18, 0x80080
	s_addc_u32 s19, s19, 0
	s_add_i32 s20, s20, s25
	s_mov_b32 m0, s20
	s_nop 0
	global_load_lds_dwordx4 v144, s[18:19]
	s_add_i32 m0, s20, 0x2000
	s_nop 0
	global_load_lds_dwordx4 v142, s[18:19]
	s_waitcnt vmcnt(6)
	s_setprio 1
	s_barrier
	v_mfma_f32_16x16x32_bf16 v[52:55], v[234:237], v[194:197], v[52:55]
	v_mfma_f32_16x16x32_bf16 v[48:51], v[242:245], v[194:197], v[48:51]
	v_mfma_f32_16x16x32_bf16 v[36:39], v[234:237], v[202:205], v[36:39]
	v_mfma_f32_16x16x32_bf16 v[32:35], v[242:245], v[202:205], v[32:35]
	v_mfma_f32_16x16x32_bf16 v[20:23], v[234:237], v[210:213], v[20:23]
	v_mfma_f32_16x16x32_bf16 v[16:19], v[242:245], v[210:213], v[16:19]
	v_mfma_f32_16x16x32_bf16 v[4:7], v[234:237], v[226:229], v[4:7]
	v_mfma_f32_16x16x32_bf16 v[0:3], v[242:245], v[226:229], v[0:3]
	v_mfma_f32_16x16x32_bf16 v[52:55], v[238:241], v[198:201], v[52:55]
	s_add_i32 s36, s36, 2
	v_mfma_f32_16x16x32_bf16 v[48:51], v[246:249], v[198:201], v[48:51]
	s_add_u32 s8, s8, 0x100
	v_mfma_f32_16x16x32_bf16 v[36:39], v[238:241], v[206:209], v[36:39]
	s_addc_u32 s9, s9, 0
	v_mfma_f32_16x16x32_bf16 v[32:35], v[246:249], v[206:209], v[32:35]
	s_add_u32 s33, s33, 0x100
	v_mfma_f32_16x16x32_bf16 v[20:23], v[238:241], v[214:217], v[20:23]
	s_addc_u32 s35, s35, 0
	v_mfma_f32_16x16x32_bf16 v[16:19], v[246:249], v[214:217], v[16:19]
	s_cmp_gt_u32 s36, 29
	v_mfma_f32_16x16x32_bf16 v[4:7], v[238:241], v[230:233], v[4:7]
	s_setprio 0
	v_mfma_f32_16x16x32_bf16 v[0:3], v[246:249], v[230:233], v[0:3]
	s_barrier
	s_cbranch_scc0 .LBB0_202
	s_cmp_lt_i32 s2, 18
	v_lshl_add_u32 v190, s3, 8, v186
	v_mov_b32_e32 v128, 1.0
	v_mov_b32_e32 v132, 0
	s_cselect_b64 s[18:19], -1, 0
	s_cmp_gt_i32 s2, 17
	v_mov_b32_e32 v134, 0
	v_mov_b32_e32 v135, 0
	v_mov_b32_e32 v136, 0
	v_mov_b32_e32 v137, 0
	v_mov_b32_e32 v138, 1.0
	v_mov_b32_e32 v139, 1.0
	v_mov_b32_e32 v140, 1.0
	v_mov_b32_e32 v141, 1.0
	s_cbranch_scc1 .LBB0_205
	v_lshlrev_b32_e32 v129, 8, v190
	v_and_b32_e32 v158, 0xfcf00, v129
	v_lshl_add_u64 v[130:131], v[146:147], 0, v[158:159]
	v_lshl_add_u64 v[134:135], v[148:149], 0, v[158:159]
	global_load_dwordx4 v[138:141], v[130:131], off
	s_nop 0
	global_load_dwordx4 v[134:137], v[134:135], off

; #define PG8_STAGE(bufoff, gbase) do { _Pragma("unroll") for (int _i = 0; _i < 2; ++_i) \
;         __builtin_amdgcn_global_load_lds((const unsigned*)((const char*)(gbase) + voff[_i]), (LAS unsigned*)(lds + (bufoff) + ldsw + _i * 8192), 16, 0, 0); } while (0)
; #define PG8_LDA(dst, b, h) do { _Pragma("unroll") for (int m = 0; m < 4; ++m) _Pragma("unroll") for (int k = 0; k < 2; ++k) dst[m][k] = *(const LAS bf16x8*)(lds + PG8_SA(b, h) + aoff + m * 2048 + k * 1024); } while (0)
; #define PG8_LDB(dst, b, h) do { _Pragma("unroll") for (int n = 0; n < 2; ++n) _Pragma("unroll") for (int k = 0; k < 2; ++k) dst[n][k] = *(const LAS bf16x8*)(lds + PG8_SB(b, h) + boff + n * 2048 + k * 1024); } while (0)
; #define PG8_MMA(ai, bj, At, Bt) do { __builtin_amdgcn_s_setprio(1); _Pragma("unroll") for (int m = 0; m < 4; ++m) _Pragma("unroll") for (int n = 0; n < 2; ++n) _Pragma("unroll") for (int k = 0; k < 2; ++k) \
;         acc[ai][bj][m][n] = __builtin_amdgcn_mfma_f32_16x16x32_bf16(Bt[n][k], At[m][k], acc[ai][bj][m][n], 0, 0, 0); __builtin_amdgcn_s_setprio(0); } while (0)
; #define PG8_WAIT_V(n) asm volatile("s_waitcnt vmcnt(" #n ")" ::: "memory")
; #define PG8_WAIT_L(n) asm volatile("s_waitcnt lgkmcnt(" #n ")" ::: "memory")
; #define PG8_BAR __builtin_amdgcn_s_barrier()
; #define PG8_SCHED __builtin_amdgcn_sched_barrier(0)
; template <class Epi>
; DI void gemm_phase(LAS unsigned char* lds, const Gemm g, const StaticOrder& S, const Epi& E) {
;     ...
;         for (int t = 0; t < nt; t += 2) {
;             const bool last = (t == nt - 2);
;             const char* a1 = cA + (size_t)(t + 1) * kstep;
;             const char* a2 = last ? nA : cA + (size_t)(t + 2) * kstep; const char* b2 = last ? nB : cB + (size_t)(t + 2) * kstep;
;             const char* a3 = a2 + kstep; const char* b3 = b2 + kstep;
;             PG8_LDB(B0, 0, 0); PG8_SCHED; PG8_LDA(At, 0, 0); PG8_STAGE(PG8_SA(1, 1), a1 + hstep);
;             PG8_WAIT_L(8); PG8_BAR; PG8_WAIT_L(0); PG8_MMA(0, 0, At, B0); PG8_BAR; PG8_SCHED;
;             PG8_LDB(B1, 0, 1); PG8_STAGE(PG8_SB(0, 0), b2);
;             PG8_BAR; PG8_WAIT_L(0); PG8_MMA(0, 1, At, B1); PG8_BAR;
;             PG8_LDA(At, 0, 1); PG8_STAGE(PG8_SA(0, 0), a2);
;             PG8_BAR; PG8_WAIT_L(0); PG8_MMA(1, 0, At, B0); PG8_BAR; PG8_SCHED;
;             PG8_STAGE(PG8_SB(0, 1), b2 + hstep);
;             PG8_WAIT_V(6); PG8_BAR; PG8_MMA(1, 1, At, B1); PG8_BAR;
.LBB0_231:
	ds_read_b128 v[138:141], v135
	ds_read_b128 v[142:145], v135 offset:1024
	ds_read_b128 v[146:149], v135 offset:2048
	ds_read_b128 v[150:153], v135 offset:3072
	ds_read_b128 v[186:189], v137
	ds_read_b128 v[190:193], v137 offset:1024
	ds_read_b128 v[194:197], v137 offset:2048
	ds_read_b128 v[198:201], v137 offset:3072
	ds_read_b128 v[202:205], v137 offset:4096
	ds_read_b128 v[206:209], v137 offset:5120
	ds_read_b128 v[210:213], v137 offset:6144
	ds_read_b128 v[214:217], v137 offset:7168
	s_add_u32 s18, s16, 0xfff80080
	s_addc_u32 s19, s17, -1
	s_add_i32 s37, 0, 0x10000
	s_cmp_eq_u32 s36, 28
	s_cselect_b32 s21, s4, s19
	s_cselect_b32 s20, s5, s18
	s_cselect_b32 s19, s9, s35
	s_cselect_b32 s18, s11, s34
	s_add_i32 m0, s24, 0xc000
	s_nop 0
	global_load_lds_dwordx4 v130, s[16:17]
	s_add_i32 m0, s24, 0xe000
	s_nop 0
	global_load_lds_dwordx4 v132, s[16:17]
	s_waitcnt lgkmcnt(8)
	s_setprio 1
	s_barrier
	s_waitcnt lgkmcnt(0)
	v_mfma_f32_16x16x32_bf16 v[124:127], v[138:141], v[186:189], v[124:127]
	v_mfma_f32_16x16x32_bf16 v[120:123], v[146:149], v[186:189], v[120:123]
	v_mfma_f32_16x16x32_bf16 v[116:119], v[138:141], v[194:197], v[116:119]
	v_mfma_f32_16x16x32_bf16 v[112:115], v[146:149], v[194:197], v[112:115]
	v_mfma_f32_16x16x32_bf16 v[100:103], v[138:141], v[202:205], v[100:103]
	v_mfma_f32_16x16x32_bf16 v[96:99], v[146:149], v[202:205], v[96:99]
	v_mfma_f32_16x16x32_bf16 v[84:87], v[138:141], v[210:213], v[84:87]
	v_mfma_f32_16x16x32_bf16 v[80:83], v[146:149], v[210:213], v[80:83]
	v_mfma_f32_16x16x32_bf16 v[124:127], v[142:145], v[190:193], v[124:127]
	v_mfma_f32_16x16x32_bf16 v[120:123], v[150:153], v[190:193], v[120:123]
	v_mfma_f32_16x16x32_bf16 v[116:119], v[142:145], v[198:201], v[116:119]
	v_mfma_f32_16x16x32_bf16 v[112:115], v[150:153], v[198:201], v[112:115]
	v_mfma_f32_16x16x32_bf16 v[100:103], v[142:145], v[206:209], v[100:103]
	v_mfma_f32_16x16x32_bf16 v[96:99], v[150:153], v[206:209], v[96:99]
	v_mfma_f32_16x16x32_bf16 v[84:87], v[142:145], v[214:217], v[84:87]
	s_setprio 0
	v_mfma_f32_16x16x32_bf16 v[80:83], v[150:153], v[214:217], v[80:83]
	s_barrier
	ds_read_b128 v[226:229], v135 offset:16384
	ds_read_b128 v[230:233], v135 offset:17408
	ds_read_b128 v[234:237], v135 offset:18432
	ds_read_b128 v[238:241], v135 offset:19456
	s_add_i32 s40, 0, 0x14000
	s_add_i32 s37, s37, s23
	s_mov_b32 m0, s37
	s_nop 0
	global_load_lds_dwordx4 v158, s[18:19]
	s_add_i32 m0, s37, 0x2000
	s_nop 0
	global_load_lds_dwordx4 v128, s[18:19]
	s_waitcnt lgkmcnt(0)
	s_setprio 1
	s_barrier
	v_mfma_f32_16x16x32_bf16 v[108:111], v[226:229], v[186:189], v[108:111]
	v_mfma_f32_16x16x32_bf16 v[104:107], v[234:237], v[186:189], v[104:107]
	v_mfma_f32_16x16x32_bf16 v[92:95], v[226:229], v[194:197], v[92:95]
	v_mfma_f32_16x16x32_bf16 v[88:91], v[234:237], v[194:197], v[88:91]
	v_mfma_f32_16x16x32_bf16 v[76:79], v[226:229], v[202:205], v[76:79]
	v_mfma_f32_16x16x32_bf16 v[72:75], v[234:237], v[202:205], v[72:75]
	v_mfma_f32_16x16x32_bf16 v[68:71], v[226:229], v[210:213], v[68:71]
	v_mfma_f32_16x16x32_bf16 v[64:67], v[234:237], v[210:213], v[64:67]
	v_mfma_f32_16x16x32_bf16 v[108:111], v[230:233], v[190:193], v[108:111]
	s_mov_b32 m0, s24
	v_mfma_f32_16x16x32_bf16 v[104:107], v[238:241], v[190:193], v[104:107]
	s_mov_b64 s[100:101], s[20:21]
	v_mfma_f32_16x16x32_bf16 v[92:95], v[230:233], v[198:201], v[92:95]
	v_mfma_f32_16x16x32_bf16 v[88:91], v[238:241], v[198:201], v[88:91]
	v_mfma_f32_16x16x32_bf16 v[76:79], v[230:233], v[206:209], v[76:79]
	v_mfma_f32_16x16x32_bf16 v[72:75], v[238:241], v[206:209], v[72:75]
	v_mfma_f32_16x16x32_bf16 v[68:71], v[230:233], v[214:217], v[68:71]
	s_setprio 0
	v_mfma_f32_16x16x32_bf16 v[64:67], v[238:241], v[214:217], v[64:67]
	s_barrier
	ds_read_b128 v[186:189], v137 offset:16384
	ds_read_b128 v[190:193], v137 offset:17408
	ds_read_b128 v[194:197], v137 offset:18432
	ds_read_b128 v[198:201], v137 offset:19456
	ds_read_b128 v[202:205], v137 offset:20480
	ds_read_b128 v[206:209], v137 offset:21504
	ds_read_b128 v[210:213], v137 offset:22528
	ds_read_b128 v[214:217], v137 offset:23552
	global_load_lds_dwordx4 v158, s[20:21]
	s_mov_b64 s[100:101], s[20:21]
	s_mov_b32 m0, s25
	s_nop 0
	global_load_lds_dwordx4 v128, s[20:21]
	s_waitcnt lgkmcnt(0)
	s_setprio 1
	s_barrier
	v_mfma_f32_16x16x32_bf16 v[60:63], v[138:141], v[186:189], v[60:63]
	v_mfma_f32_16x16x32_bf16 v[56:59], v[146:149], v[186:189], v[56:59]
	v_mfma_f32_16x16x32_bf16 v[52:55], v[138:141], v[194:197], v[52:55]
	v_mfma_f32_16x16x32_bf16 v[48:51], v[146:149], v[194:197], v[48:51]
	v_mfma_f32_16x16x32_bf16 v[36:39], v[138:141], v[202:205], v[36:39]
	v_mfma_f32_16x16x32_bf16 v[32:35], v[146:149], v[202:205], v[32:35]
	v_mfma_f32_16x16x32_bf16 v[20:23], v[138:141], v[210:213], v[20:23]
	v_mfma_f32_16x16x32_bf16 v[16:19], v[146:149], v[210:213], v[16:19]
	v_mfma_f32_16x16x32_bf16 v[60:63], v[142:145], v[190:193], v[60:63]
	v_mfma_f32_16x16x32_bf16 v[56:59], v[150:153], v[190:193], v[56:59]
	v_mfma_f32_16x16x32_bf16 v[52:55], v[142:145], v[198:201], v[52:55]
	v_mfma_f32_16x16x32_bf16 v[48:51], v[150:153], v[198:201], v[48:51]
	v_mfma_f32_16x16x32_bf16 v[36:39], v[142:145], v[206:209], v[36:39]
	v_mfma_f32_16x16x32_bf16 v[32:35], v[150:153], v[206:209], v[32:35]
	v_mfma_f32_16x16x32_bf16 v[20:23], v[142:145], v[214:217], v[20:23]
	s_setprio 0
	v_mfma_f32_16x16x32_bf16 v[16:19], v[150:153], v[214:217], v[16:19]
	s_barrier
	s_add_u32 s38, s18, 0x80000
	s_addc_u32 s39, s19, 0
	s_add_i32 s37, s40, s23
	s_mov_b32 m0, s37
	s_nop 0
	global_load_lds_dwordx4 v158, s[38:39]
	s_add_i32 m0, s37, 0x2000
	s_nop 0
	global_load_lds_dwordx4 v128, s[38:39]
	s_waitcnt vmcnt(6)
	s_setprio 1
	s_barrier
; #define PG8_STAGE(bufoff, gbase) do { _Pragma("unroll") for (int _i = 0; _i < 2; ++_i) \
;         __builtin_amdgcn_global_load_lds((const unsigned*)((const char*)(gbase) + voff[_i]), (LAS unsigned*)(lds + (bufoff) + ldsw + _i * 8192), 16, 0, 0); } while (0)
; #define PG8_LDA(dst, b, h) do { _Pragma("unroll") for (int m = 0; m < 4; ++m) _Pragma("unroll") for (int k = 0; k < 2; ++k) dst[m][k] = *(const LAS bf16x8*)(lds + PG8_SA(b, h) + aoff + m * 2048 + k * 1024); } while (0)
; #define PG8_LDB(dst, b, h) do { _Pragma("unroll") for (int n = 0; n < 2; ++n) _Pragma("unroll") for (int k = 0; k < 2; ++k) dst[n][k] = *(const LAS bf16x8*)(lds + PG8_SB(b, h) + boff + n * 2048 + k * 1024); } while (0)
; #define PG8_MMA(ai, bj, At, Bt) do { __builtin_amdgcn_s_setprio(1); _Pragma("unroll") for (int m = 0; m < 4; ++m) _Pragma("unroll") for (int n = 0; n < 2; ++n) _Pragma("unroll") for (int k = 0; k < 2; ++k) \
;         acc[ai][bj][m][n] = __builtin_amdgcn_mfma_f32_16x16x32_bf16(Bt[n][k], At[m][k], acc[ai][bj][m][n], 0, 0, 0); __builtin_amdgcn_s_setprio(0); } while (0)
; #define PG8_WAIT_V(n) asm volatile("s_waitcnt vmcnt(" #n ")" ::: "memory")
; #define PG8_WAIT_L(n) asm volatile("s_waitcnt lgkmcnt(" #n ")" ::: "memory")
; #define PG8_BAR __builtin_amdgcn_s_barrier()
; #define PG8_SCHED __builtin_amdgcn_sched_barrier(0)
; template <class Epi>
; DI void gemm_phase(LAS unsigned char* lds, const Gemm g, const StaticOrder& S, const Epi& E) {
;     ...
;             PG8_WAIT_V(6); PG8_BAR; PG8_MMA(1, 1, At, B1); PG8_BAR;
;             PG8_LDB(B0, 1, 0); PG8_SCHED; PG8_LDA(At, 1, 0); PG8_STAGE(PG8_SA(0, 1), a2 + hstep);
;             PG8_WAIT_L(8); PG8_BAR; PG8_WAIT_L(0); PG8_MMA(0, 0, At, B0); PG8_BAR; PG8_SCHED;
;             PG8_LDB(B1, 1, 1); PG8_STAGE(PG8_SB(1, 0), b3);
;             PG8_BAR; PG8_WAIT_L(0); PG8_MMA(0, 1, At, B1); PG8_BAR;
;             PG8_LDA(At, 1, 1); PG8_STAGE(PG8_SA(1, 0), a3);
;             PG8_BAR; PG8_WAIT_L(0); PG8_MMA(1, 0, At, B0); PG8_BAR; PG8_SCHED;
;             PG8_STAGE(PG8_SB(1, 1), b3 + hstep);
	v_mfma_f32_16x16x32_bf16 v[44:47], v[226:229], v[186:189], v[44:47]
	v_mfma_f32_16x16x32_bf16 v[40:43], v[234:237], v[186:189], v[40:43]
	v_mfma_f32_16x16x32_bf16 v[28:31], v[226:229], v[194:197], v[28:31]
	v_mfma_f32_16x16x32_bf16 v[24:27], v[234:237], v[194:197], v[24:27]
	v_mfma_f32_16x16x32_bf16 v[12:15], v[226:229], v[202:205], v[12:15]
	v_mfma_f32_16x16x32_bf16 v[8:11], v[234:237], v[202:205], v[8:11]
	v_mfma_f32_16x16x32_bf16 v[4:7], v[226:229], v[210:213], v[4:7]
	v_mfma_f32_16x16x32_bf16 v[0:3], v[234:237], v[210:213], v[0:3]
	v_mfma_f32_16x16x32_bf16 v[44:47], v[230:233], v[190:193], v[44:47]
	s_add_i32 s37, 0, 0x18000
	v_mfma_f32_16x16x32_bf16 v[40:43], v[238:241], v[190:193], v[40:43]
	v_mfma_f32_16x16x32_bf16 v[28:31], v[230:233], v[198:201], v[28:31]
	v_mfma_f32_16x16x32_bf16 v[24:27], v[238:241], v[198:201], v[24:27]
	v_mfma_f32_16x16x32_bf16 v[12:15], v[230:233], v[206:209], v[12:15]
	v_mfma_f32_16x16x32_bf16 v[8:11], v[238:241], v[206:209], v[8:11]
	v_mfma_f32_16x16x32_bf16 v[4:7], v[230:233], v[214:217], v[4:7]
	s_setprio 0
	v_mfma_f32_16x16x32_bf16 v[0:3], v[238:241], v[214:217], v[0:3]
	s_barrier
	ds_read_b128 v[138:141], v135 offset:32768
	ds_read_b128 v[142:145], v135 offset:33792
	ds_read_b128 v[146:149], v135 offset:34816
	ds_read_b128 v[150:153], v135 offset:35840
	ds_read_b128 v[186:189], v137 offset:32768
	ds_read_b128 v[190:193], v137 offset:33792
	ds_read_b128 v[194:197], v137 offset:34816
	ds_read_b128 v[198:201], v137 offset:35840
	ds_read_b128 v[202:205], v137 offset:36864
	ds_read_b128 v[206:209], v137 offset:37888
	ds_read_b128 v[210:213], v137 offset:38912
	ds_read_b128 v[214:217], v137 offset:39936
	s_add_u32 s20, s20, 0x80000
	s_addc_u32 s21, s21, 0
	s_mov_b32 m0, s26
	s_nop 0
	global_load_lds_dwordx4 v158, s[20:21]
	s_mov_b32 m0, s27
	s_nop 0
	global_load_lds_dwordx4 v128, s[20:21]
	s_waitcnt lgkmcnt(8)
	s_setprio 1
	s_barrier
	s_waitcnt lgkmcnt(0)
	v_mfma_f32_16x16x32_bf16 v[124:127], v[138:141], v[186:189], v[124:127]
	v_mfma_f32_16x16x32_bf16 v[120:123], v[146:149], v[186:189], v[120:123]
	v_mfma_f32_16x16x32_bf16 v[116:119], v[138:141], v[194:197], v[116:119]
	v_mfma_f32_16x16x32_bf16 v[112:115], v[146:149], v[194:197], v[112:115]
	v_mfma_f32_16x16x32_bf16 v[100:103], v[138:141], v[202:205], v[100:103]
	v_mfma_f32_16x16x32_bf16 v[96:99], v[146:149], v[202:205], v[96:99]
	v_mfma_f32_16x16x32_bf16 v[84:87], v[138:141], v[210:213], v[84:87]
	v_mfma_f32_16x16x32_bf16 v[80:83], v[146:149], v[210:213], v[80:83]
	v_mfma_f32_16x16x32_bf16 v[124:127], v[142:145], v[190:193], v[124:127]
	v_mfma_f32_16x16x32_bf16 v[120:123], v[150:153], v[190:193], v[120:123]
	v_mfma_f32_16x16x32_bf16 v[116:119], v[142:145], v[198:201], v[116:119]
	v_mfma_f32_16x16x32_bf16 v[112:115], v[150:153], v[198:201], v[112:115]
	v_mfma_f32_16x16x32_bf16 v[100:103], v[142:145], v[206:209], v[100:103]
	v_mfma_f32_16x16x32_bf16 v[96:99], v[150:153], v[206:209], v[96:99]
	v_mfma_f32_16x16x32_bf16 v[84:87], v[142:145], v[214:217], v[84:87]
	s_setprio 0
	v_mfma_f32_16x16x32_bf16 v[80:83], v[150:153], v[214:217], v[80:83]
	s_barrier
	ds_read_b128 v[226:229], v135 offset:49152
	ds_read_b128 v[230:233], v135 offset:50176
	ds_read_b128 v[234:237], v135 offset:51200
	ds_read_b128 v[238:241], v135 offset:52224
	s_add_i32 s20, 0, 0x1c000
	s_add_i32 s21, s37, s23
	s_add_i32 m0, s21, 0xffffff80
	s_nop 0
	global_load_lds_dwordx4 v158, s[18:19] offset:128
	s_add_i32 m0, s21, 0x1f80
	s_nop 0
	global_load_lds_dwordx4 v128, s[18:19] offset:128
	s_waitcnt lgkmcnt(0)
	s_setprio 1
	s_barrier
	v_mfma_f32_16x16x32_bf16 v[108:111], v[226:229], v[186:189], v[108:111]
	v_mfma_f32_16x16x32_bf16 v[104:107], v[234:237], v[186:189], v[104:107]
	v_mfma_f32_16x16x32_bf16 v[92:95], v[226:229], v[194:197], v[92:95]
	v_mfma_f32_16x16x32_bf16 v[88:91], v[234:237], v[194:197], v[88:91]
	v_mfma_f32_16x16x32_bf16 v[76:79], v[226:229], v[202:205], v[76:79]
	v_mfma_f32_16x16x32_bf16 v[72:75], v[234:237], v[202:205], v[72:75]
	v_mfma_f32_16x16x32_bf16 v[68:71], v[226:229], v[210:213], v[68:71]
	v_mfma_f32_16x16x32_bf16 v[64:67], v[234:237], v[210:213], v[64:67]
	v_mfma_f32_16x16x32_bf16 v[108:111], v[230:233], v[190:193], v[108:111]
	s_add_i32 m0, s28, 0xffffff80
	v_mfma_f32_16x16x32_bf16 v[104:107], v[238:241], v[190:193], v[104:107]
	v_mfma_f32_16x16x32_bf16 v[92:95], v[230:233], v[198:201], v[92:95]
	v_mfma_f32_16x16x32_bf16 v[88:91], v[238:241], v[198:201], v[88:91]
	v_mfma_f32_16x16x32_bf16 v[76:79], v[230:233], v[206:209], v[76:79]
	v_mfma_f32_16x16x32_bf16 v[72:75], v[238:241], v[206:209], v[72:75]
	v_mfma_f32_16x16x32_bf16 v[68:71], v[230:233], v[214:217], v[68:71]
	s_setprio 0
	v_mfma_f32_16x16x32_bf16 v[64:67], v[238:241], v[214:217], v[64:67]
	s_barrier
	ds_read_b128 v[186:189], v137 offset:49152
	ds_read_b128 v[190:193], v137 offset:50176
	ds_read_b128 v[194:197], v137 offset:51200
	ds_read_b128 v[198:201], v137 offset:52224
	ds_read_b128 v[202:205], v137 offset:53248
	ds_read_b128 v[206:209], v137 offset:54272
	ds_read_b128 v[210:213], v137 offset:55296
	ds_read_b128 v[214:217], v137 offset:56320
	global_load_lds_dwordx4 v158, s[100:101] offset:128
	s_add_i32 m0, s29, 0xffffff80
	s_nop 0
	global_load_lds_dwordx4 v128, s[100:101] offset:128
	s_waitcnt lgkmcnt(0)
	s_setprio 1
	s_barrier
; #define PG8_STAGE(bufoff, gbase) do { _Pragma("unroll") for (int _i = 0; _i < 2; ++_i) \
;         __builtin_amdgcn_global_load_lds((const unsigned*)((const char*)(gbase) + voff[_i]), (LAS unsigned*)(lds + (bufoff) + ldsw + _i * 8192), 16, 0, 0); } while (0)
; #define PG8_MMA(ai, bj, At, Bt) do { __builtin_amdgcn_s_setprio(1); _Pragma("unroll") for (int m = 0; m < 4; ++m) _Pragma("unroll") for (int n = 0; n < 2; ++n) _Pragma("unroll") for (int k = 0; k < 2; ++k) \
;         acc[ai][bj][m][n] = __builtin_amdgcn_mfma_f32_16x16x32_bf16(Bt[n][k], At[m][k], acc[ai][bj][m][n], 0, 0, 0); __builtin_amdgcn_s_setprio(0); } while (0)
; #define PG8_WAIT_V(n) asm volatile("s_waitcnt vmcnt(" #n ")" ::: "memory")
; #define PG8_WAIT_L(n) asm volatile("s_waitcnt lgkmcnt(" #n ")" ::: "memory")
; #define PG8_BAR __builtin_amdgcn_s_barrier()
; #define PG8_SCHED __builtin_amdgcn_sched_barrier(0)
; template <class Epi>
; DI void gemm_phase(LAS unsigned char* lds, const Gemm g, const StaticOrder& S, const Epi& E) {
;     ...
;             PG8_BAR; PG8_WAIT_L(0); PG8_MMA(1, 0, At, B0); PG8_BAR; PG8_SCHED;
;             PG8_STAGE(PG8_SB(1, 1), b3 + hstep);
;             PG8_WAIT_V(6); PG8_BAR; PG8_MMA(1, 1, At, B1); PG8_BAR;
	v_mfma_f32_16x16x32_bf16 v[60:63], v[138:141], v[186:189], v[60:63]
	v_mfma_f32_16x16x32_bf16 v[56:59], v[146:149], v[186:189], v[56:59]
	v_mfma_f32_16x16x32_bf16 v[52:55], v[138:141], v[194:197], v[52:55]
	v_mfma_f32_16x16x32_bf16 v[48:51], v[146:149], v[194:197], v[48:51]
	v_mfma_f32_16x16x32_bf16 v[36:39], v[138:141], v[202:205], v[36:39]
	v_mfma_f32_16x16x32_bf16 v[32:35], v[146:149], v[202:205], v[32:35]
	v_mfma_f32_16x16x32_bf16 v[20:23], v[138:141], v[210:213], v[20:23]
	v_mfma_f32_16x16x32_bf16 v[16:19], v[146:149], v[210:213], v[16:19]
	v_mfma_f32_16x16x32_bf16 v[60:63], v[142:145], v[190:193], v[60:63]
	v_mfma_f32_16x16x32_bf16 v[56:59], v[150:153], v[190:193], v[56:59]
	v_mfma_f32_16x16x32_bf16 v[52:55], v[142:145], v[198:201], v[52:55]
	v_mfma_f32_16x16x32_bf16 v[48:51], v[150:153], v[198:201], v[48:51]
	v_mfma_f32_16x16x32_bf16 v[36:39], v[142:145], v[206:209], v[36:39]
	v_mfma_f32_16x16x32_bf16 v[32:35], v[150:153], v[206:209], v[32:35]
	v_mfma_f32_16x16x32_bf16 v[20:23], v[142:145], v[214:217], v[20:23]
	s_setprio 0
	v_mfma_f32_16x16x32_bf16 v[16:19], v[150:153], v[214:217], v[16:19]
	s_barrier
	s_add_u32 s18, s18, 0x80080
	s_addc_u32 s19, s19, 0
	s_add_i32 s20, s20, s23
	s_mov_b32 m0, s20
	s_nop 0
	global_load_lds_dwordx4 v158, s[18:19]
	s_add_i32 m0, s20, 0x2000
	s_nop 0
	global_load_lds_dwordx4 v128, s[18:19]
	s_waitcnt vmcnt(6)
	s_setprio 1
	s_barrier
	v_mfma_f32_16x16x32_bf16 v[44:47], v[226:229], v[186:189], v[44:47]
	v_mfma_f32_16x16x32_bf16 v[40:43], v[234:237], v[186:189], v[40:43]
	v_mfma_f32_16x16x32_bf16 v[28:31], v[226:229], v[194:197], v[28:31]
	v_mfma_f32_16x16x32_bf16 v[24:27], v[234:237], v[194:197], v[24:27]
	v_mfma_f32_16x16x32_bf16 v[12:15], v[226:229], v[202:205], v[12:15]
	v_mfma_f32_16x16x32_bf16 v[8:11], v[234:237], v[202:205], v[8:11]
	v_mfma_f32_16x16x32_bf16 v[4:7], v[226:229], v[210:213], v[4:7]
	v_mfma_f32_16x16x32_bf16 v[0:3], v[234:237], v[210:213], v[0:3]
	v_mfma_f32_16x16x32_bf16 v[44:47], v[230:233], v[190:193], v[44:47]
	s_add_i32 s36, s36, 2
	v_mfma_f32_16x16x32_bf16 v[40:43], v[238:241], v[190:193], v[40:43]
	s_add_u32 s16, s16, 0x100
	v_mfma_f32_16x16x32_bf16 v[28:31], v[230:233], v[198:201], v[28:31]
	s_addc_u32 s17, s17, 0
	v_mfma_f32_16x16x32_bf16 v[24:27], v[238:241], v[198:201], v[24:27]
	s_add_u32 s34, s34, 0x100
	v_mfma_f32_16x16x32_bf16 v[12:15], v[230:233], v[206:209], v[12:15]
	s_addc_u32 s35, s35, 0
	v_mfma_f32_16x16x32_bf16 v[8:11], v[238:241], v[206:209], v[8:11]
	s_cmp_gt_u32 s36, 29
	v_mfma_f32_16x16x32_bf16 v[4:7], v[230:233], v[214:217], v[4:7]
	s_setprio 0
	v_mfma_f32_16x16x32_bf16 v[0:3], v[238:241], v[214:217], v[0:3]
	s_barrier
	s_cbranch_scc0 .LBB0_231
; #define PG8_WAIT_V(n) asm volatile("s_waitcnt vmcnt(" #n ")" ::: "memory")
; #define PG8_BAR __builtin_amdgcn_s_barrier()
; template <class Epi>
; DI void gemm_phase(LAS unsigned char* lds, const Gemm g, const StaticOrder& S, const Epi& E) {
;     ...
;         cur = nxt; cA = nA; cB = nB; ++ui;
;     }
;     PG8_WAIT_V(0);
;     if (wr == 0) PG8_BAR;
;     PG8_BAR;
;     DI void operator()(const f32x4 (&acc)[2][2][4][2], const Unit& u, int wr, int wc, int fr, int fq) const {
;         const int row0 = u.pm * BM + wr * 64 + fr, col0 = u.pn * BM + wc * 32 + 8 * fq;
; #pragma unroll
;         for (int ai = 0; ai < 2; ++ai)
; #pragma unroll
;             for (int m = 0; m < 4; ++m) { u16* rowp = O + (size_t)(row0 + ai * HALF + m * 16) * ldc + col0;
; #pragma unroll
;                 for (int bj = 0; bj < 2; ++bj) { const f32x4 v0 = acc[ai][bj][m][0], v1 = acc[ai][bj][m][1];
;                     *(u32x4*)(rowp + bj * HALF) = (u32x4){pk(v0[0], v0[1]), pk(v0[2], v0[3]), pk(v1[0], v1[1]), pk(v1[2], v1[3])}; } }
	v_lshl_add_u32 v144, s33, 8, v134
	v_lshl_or_b32 v138, s31, 8, v136
	v_ashrrev_i32_e32 v139, 31, v138
	v_mov_b64_e32 v[140:141], s[50:51]
	s_movk_i32 s9, 0x3000
	v_cvt_pk_bf16_f32 v68, v68, v69
	v_cvt_pk_bf16_f32 v69, v70, v71
	v_cvt_pk_bf16_f32 v70, v64, v65
	v_add_u32_e32 v64, 0x80, v144
	v_mad_i64_i32 v[142:143], s[4:5], v144, s9, v[140:141]
	v_lshlrev_b64 v[138:139], 1, v[138:139]
	v_cvt_pk_bf16_f32 v108, v108, v109
	v_cvt_pk_bf16_f32 v109, v110, v111
	v_cvt_pk_bf16_f32 v110, v104, v105
	v_or_b32_e32 v104, 16, v144
	v_mad_i64_i32 v[64:65], s[4:5], v64, s9, v[140:141]
	v_cvt_pk_bf16_f32 v44, v44, v45
	v_cvt_pk_bf16_f32 v45, v46, v47
	v_cvt_pk_bf16_f32 v46, v40, v41
	v_add_u32_e32 v40, 0x90, v144
	v_lshl_add_u64 v[142:143], v[142:143], 0, v[138:139]
	v_cvt_pk_bf16_f32 v111, v106, v107
	v_mad_i64_i32 v[104:105], s[4:5], v104, s9, v[140:141]
	v_cvt_pk_bf16_f32 v92, v92, v93
	v_cvt_pk_bf16_f32 v93, v94, v95
	v_cvt_pk_bf16_f32 v94, v88, v89
	v_or_b32_e32 v88, 32, v144
	v_lshl_add_u64 v[64:65], v[64:65], 0, v[138:139]
	v_cvt_pk_bf16_f32 v47, v42, v43
	v_mad_i64_i32 v[40:41], s[4:5], v40, s9, v[140:141]
	v_cvt_pk_bf16_f32 v28, v28, v29
	v_cvt_pk_bf16_f32 v29, v30, v31
	v_cvt_pk_bf16_f32 v30, v24, v25
	v_add_u32_e32 v24, 0xa0, v144
	global_store_dwordx4 v[142:143], v[108:111], off offset:256
	v_cvt_pk_bf16_f32 v95, v90, v91
	v_mad_i64_i32 v[88:89], s[4:5], v88, s9, v[140:141]
	v_lshl_add_u64 v[108:109], v[104:105], 0, v[138:139]
	v_cvt_pk_bf16_f32 v76, v76, v77
	v_cvt_pk_bf16_f32 v77, v78, v79
	v_cvt_pk_bf16_f32 v78, v72, v73
	v_or_b32_e32 v72, 48, v144
	global_store_dwordx4 v[64:65], v[44:47], off offset:256
	v_cvt_pk_bf16_f32 v31, v26, v27
	v_mad_i64_i32 v[24:25], s[4:5], v24, s9, v[140:141]
	v_lshl_add_u64 v[44:45], v[40:41], 0, v[138:139]
	v_cvt_pk_bf16_f32 v12, v12, v13
	v_cvt_pk_bf16_f32 v13, v14, v15
	v_cvt_pk_bf16_f32 v14, v8, v9
	v_add_u32_e32 v8, 0xb0, v144
	global_store_dwordx4 v[108:109], v[92:95], off offset:256
	v_cvt_pk_bf16_f32 v79, v74, v75
	v_mad_i64_i32 v[72:73], s[4:5], v72, s9, v[140:141]
	v_lshl_add_u64 v[92:93], v[88:89], 0, v[138:139]
	global_store_dwordx4 v[44:45], v[28:31], off offset:256
	v_cvt_pk_bf16_f32 v15, v10, v11
	v_mad_i64_i32 v[8:9], s[4:5], v8, s9, v[140:141]
	v_lshl_add_u64 v[28:29], v[24:25], 0, v[138:139]
	v_cvt_pk_bf16_f32 v124, v124, v125
	v_cvt_pk_bf16_f32 v125, v126, v127
	v_cvt_pk_bf16_f32 v126, v120, v121
	v_cvt_pk_bf16_f32 v127, v122, v123
	v_cvt_pk_bf16_f32 v104, v116, v117
	v_cvt_pk_bf16_f32 v105, v118, v119
	v_cvt_pk_bf16_f32 v106, v112, v113
	v_cvt_pk_bf16_f32 v107, v114, v115
	v_cvt_pk_bf16_f32 v88, v100, v101
	v_cvt_pk_bf16_f32 v89, v102, v103
	v_cvt_pk_bf16_f32 v90, v96, v97
	v_cvt_pk_bf16_f32 v91, v98, v99
	global_store_dwordx4 v[92:93], v[76:79], off offset:256
	v_cvt_pk_bf16_f32 v74, v80, v81
	v_cvt_pk_bf16_f32 v75, v82, v83
	v_lshl_add_u64 v[76:77], v[72:73], 0, v[138:139]
	v_cvt_pk_bf16_f32 v72, v84, v85
	v_cvt_pk_bf16_f32 v73, v86, v87
	v_cvt_pk_bf16_f32 v71, v66, v67
	v_cvt_pk_bf16_f32 v60, v60, v61
	v_cvt_pk_bf16_f32 v61, v62, v63
	v_cvt_pk_bf16_f32 v62, v56, v57
	v_cvt_pk_bf16_f32 v63, v58, v59
	v_cvt_pk_bf16_f32 v40, v52, v53
	v_cvt_pk_bf16_f32 v41, v54, v55
	v_cvt_pk_bf16_f32 v42, v48, v49
	v_cvt_pk_bf16_f32 v43, v50, v51
	v_cvt_pk_bf16_f32 v24, v36, v37
	v_cvt_pk_bf16_f32 v25, v38, v39
	v_cvt_pk_bf16_f32 v26, v32, v33
	v_cvt_pk_bf16_f32 v27, v34, v35
	global_store_dwordx4 v[28:29], v[12:15], off offset:256
	v_cvt_pk_bf16_f32 v10, v16, v17
	v_cvt_pk_bf16_f32 v11, v18, v19
	v_lshl_add_u64 v[12:13], v[8:9], 0, v[138:139]
	v_cvt_pk_bf16_f32 v8, v20, v21
	v_cvt_pk_bf16_f32 v9, v22, v23
	v_cvt_pk_bf16_f32 v4, v4, v5
	v_cvt_pk_bf16_f32 v5, v6, v7
	v_cvt_pk_bf16_f32 v6, v0, v1
	v_cvt_pk_bf16_f32 v7, v2, v3
	s_and_b64 vcc, exec, s[6:7]
	s_mov_b32 s31, s8
	s_mov_b32 s33, s10
	s_mov_b64 s[18:19], s[14:15]
	s_mov_b64 s[16:17], s[12:13]
	global_store_dwordx4 v[142:143], v[124:127], off
	global_store_dwordx4 v[108:109], v[104:107], off
	global_store_dwordx4 v[92:93], v[88:91], off
	global_store_dwordx4 v[76:77], v[72:75], off
	global_store_dwordx4 v[76:77], v[68:71], off offset:256
	global_store_dwordx4 v[64:65], v[60:63], off
	global_store_dwordx4 v[44:45], v[40:43], off
	global_store_dwordx4 v[28:29], v[24:27], off
	global_store_dwordx4 v[12:13], v[8:11], off
	global_store_dwordx4 v[12:13], v[4:7], off offset:256
	s_cbranch_vccz .LBB0_228
	s_waitcnt vmcnt(0)
	s_cmpk_gt_u32 s2, 0xff
	s_cbranch_scc1 .LBB0_235
	s_barrier

; #define PG8_STAGE(bufoff, gbase) do { _Pragma("unroll") for (int _i = 0; _i < 2; ++_i) \
;         __builtin_amdgcn_global_load_lds((const unsigned*)((const char*)(gbase) + voff[_i]), (LAS unsigned*)(lds + (bufoff) + ldsw + _i * 8192), 16, 0, 0); } while (0)
; #define PG8_LDA(dst, b, h) do { _Pragma("unroll") for (int m = 0; m < 4; ++m) _Pragma("unroll") for (int k = 0; k < 2; ++k) dst[m][k] = *(const LAS bf16x8*)(lds + PG8_SA(b, h) + aoff + m * 2048 + k * 1024); } while (0)
; #define PG8_LDB(dst, b, h) do { _Pragma("unroll") for (int n = 0; n < 2; ++n) _Pragma("unroll") for (int k = 0; k < 2; ++k) dst[n][k] = *(const LAS bf16x8*)(lds + PG8_SB(b, h) + boff + n * 2048 + k * 1024); } while (0)
; #define PG8_MMA(ai, bj, At, Bt) do { __builtin_amdgcn_s_setprio(1); _Pragma("unroll") for (int m = 0; m < 4; ++m) _Pragma("unroll") for (int n = 0; n < 2; ++n) _Pragma("unroll") for (int k = 0; k < 2; ++k) \
;         acc[ai][bj][m][n] = __builtin_amdgcn_mfma_f32_16x16x32_bf16(Bt[n][k], At[m][k], acc[ai][bj][m][n], 0, 0, 0); __builtin_amdgcn_s_setprio(0); } while (0)
; #define PG8_WAIT_V(n) asm volatile("s_waitcnt vmcnt(" #n ")" ::: "memory")
; #define PG8_WAIT_L(n) asm volatile("s_waitcnt lgkmcnt(" #n ")" ::: "memory")
; #define PG8_BAR __builtin_amdgcn_s_barrier()
; #define PG8_SCHED __builtin_amdgcn_sched_barrier(0)
; template <class Epi>
; DI void gemm_phase(LAS unsigned char* lds, const Gemm g, const StaticOrder& S, const Epi& E) {
;     ...
;         for (int t = 0; t < nt; t += 2) {
;             const bool last = (t == nt - 2);
;             const char* a1 = cA + (size_t)(t + 1) * kstep;
;             const char* a2 = last ? nA : cA + (size_t)(t + 2) * kstep; const char* b2 = last ? nB : cB + (size_t)(t + 2) * kstep;
;             const char* a3 = a2 + kstep; const char* b3 = b2 + kstep;
;             PG8_LDB(B0, 0, 0); PG8_SCHED; PG8_LDA(At, 0, 0); PG8_STAGE(PG8_SA(1, 1), a1 + hstep);
;             PG8_WAIT_L(8); PG8_BAR; PG8_WAIT_L(0); PG8_MMA(0, 0, At, B0); PG8_BAR; PG8_SCHED;
;             PG8_LDB(B1, 0, 1); PG8_STAGE(PG8_SB(0, 0), b2);
;             PG8_BAR; PG8_WAIT_L(0); PG8_MMA(0, 1, At, B1); PG8_BAR;
;             PG8_LDA(At, 0, 1); PG8_STAGE(PG8_SA(0, 0), a2);
;             PG8_BAR; PG8_WAIT_L(0); PG8_MMA(1, 0, At, B0); PG8_BAR; PG8_SCHED;
;             PG8_STAGE(PG8_SB(0, 1), b2 + hstep);
;             PG8_WAIT_V(6); PG8_BAR; PG8_MMA(1, 1, At, B1); PG8_BAR;
.LBB0_320:
	s_add_u32 s26, s24, 0x100
	s_addc_u32 s27, s25, 0
	s_add_i32 s47, 0, 0x10000
	ds_read_b128 v[128:131], v226
	ds_read_b128 v[132:135], v226 offset:1024
	ds_read_b128 v[136:139], v226 offset:2048
	ds_read_b128 v[140:143], v226 offset:3072
	s_cmp_eq_u32 s46, 28
	s_cselect_b32 s31, s4, s27
	s_cselect_b32 s30, s5, s26
	s_cselect_b32 s29, s9, s45
	s_cselect_b32 s28, s11, s33
	v_lshl_add_u64 v[214:215], s[24:25], 0, v[190:191]
	s_add_i32 m0, s38, 0xc000
	ds_read_b128 v[144:147], v228
	ds_read_b128 v[148:151], v228 offset:1024
	ds_read_b128 v[152:155], v228 offset:2048
	ds_read_b128 v[194:197], v228 offset:3072
	ds_read_b128 v[198:201], v228 offset:4096
	ds_read_b128 v[202:205], v228 offset:5120
	ds_read_b128 v[206:209], v228 offset:6144
	ds_read_b128 v[210:213], v228 offset:7168
	global_load_lds_dwordx4 v[214:215], off
	v_lshl_add_u64 v[214:215], s[24:25], 0, v[192:193]
	s_add_i32 m0, s38, 0xe000
	s_nop 0
	global_load_lds_dwordx4 v[214:215], off
	s_waitcnt lgkmcnt(8)
	s_setprio 1
	s_barrier
	s_waitcnt lgkmcnt(0)
	v_mfma_f32_16x16x32_bf16 v[124:127], v[128:131], v[144:147], v[124:127]
	v_mfma_f32_16x16x32_bf16 v[120:123], v[136:139], v[144:147], v[120:123]
	v_mfma_f32_16x16x32_bf16 v[116:119], v[128:131], v[152:155], v[116:119]
	v_mfma_f32_16x16x32_bf16 v[112:115], v[136:139], v[152:155], v[112:115]
	v_mfma_f32_16x16x32_bf16 v[108:111], v[128:131], v[198:201], v[108:111]
	v_mfma_f32_16x16x32_bf16 v[104:107], v[136:139], v[198:201], v[104:107]
	v_mfma_f32_16x16x32_bf16 v[100:103], v[128:131], v[206:209], v[100:103]
	v_mfma_f32_16x16x32_bf16 v[96:99], v[136:139], v[206:209], v[96:99]
	v_mfma_f32_16x16x32_bf16 v[124:127], v[132:135], v[148:151], v[124:127]
	v_mfma_f32_16x16x32_bf16 v[120:123], v[140:143], v[148:151], v[120:123]
	v_mfma_f32_16x16x32_bf16 v[116:119], v[132:135], v[194:197], v[116:119]
	v_mfma_f32_16x16x32_bf16 v[112:115], v[140:143], v[194:197], v[112:115]
	v_mfma_f32_16x16x32_bf16 v[108:111], v[132:135], v[202:205], v[108:111]
	v_mfma_f32_16x16x32_bf16 v[104:107], v[140:143], v[202:205], v[104:107]
	v_mfma_f32_16x16x32_bf16 v[100:103], v[132:135], v[210:213], v[100:103]
	s_setprio 0
	v_mfma_f32_16x16x32_bf16 v[96:99], v[140:143], v[210:213], v[96:99]
	s_barrier
	ds_read_b128 v[214:217], v226 offset:16384
	ds_read_b128 v[230:233], v226 offset:17408
	ds_read_b128 v[234:237], v226 offset:18432
	ds_read_b128 v[238:241], v226 offset:19456
	s_add_i32 s48, 0, 0x14000
	s_add_i32 s24, s47, s37
	s_mov_b32 m0, s24
	s_nop 0
	global_load_lds_dwordx4 v188, s[28:29]
	s_add_i32 m0, s24, 0x2000
	s_nop 0
	global_load_lds_dwordx4 v186, s[28:29]
	s_waitcnt lgkmcnt(0)
	s_setprio 1
	s_barrier
	v_mfma_f32_16x16x32_bf16 v[60:63], v[214:217], v[144:147], v[60:63]
	v_mfma_f32_16x16x32_bf16 v[56:59], v[234:237], v[144:147], v[56:59]
	v_mfma_f32_16x16x32_bf16 v[52:55], v[214:217], v[152:155], v[52:55]
	v_mfma_f32_16x16x32_bf16 v[48:51], v[234:237], v[152:155], v[48:51]
	v_mfma_f32_16x16x32_bf16 v[44:47], v[214:217], v[198:201], v[44:47]
	v_mfma_f32_16x16x32_bf16 v[40:43], v[234:237], v[198:201], v[40:43]
	v_mfma_f32_16x16x32_bf16 v[36:39], v[214:217], v[206:209], v[36:39]
	v_mfma_f32_16x16x32_bf16 v[32:35], v[234:237], v[206:209], v[32:35]
	v_mfma_f32_16x16x32_bf16 v[60:63], v[230:233], v[148:151], v[60:63]
	s_mov_b32 m0, s38
	v_mfma_f32_16x16x32_bf16 v[56:59], v[238:241], v[148:151], v[56:59]
	s_mov_b64 s[100:101], s[30:31]
	v_mfma_f32_16x16x32_bf16 v[52:55], v[230:233], v[194:197], v[52:55]
	v_mfma_f32_16x16x32_bf16 v[48:51], v[238:241], v[194:197], v[48:51]
	v_mfma_f32_16x16x32_bf16 v[44:47], v[230:233], v[202:205], v[44:47]
	v_mfma_f32_16x16x32_bf16 v[40:43], v[238:241], v[202:205], v[40:43]
	v_mfma_f32_16x16x32_bf16 v[36:39], v[230:233], v[210:213], v[36:39]
	s_setprio 0
	v_mfma_f32_16x16x32_bf16 v[32:35], v[238:241], v[210:213], v[32:35]
	s_barrier
	ds_read_b128 v[144:147], v228 offset:16384
	ds_read_b128 v[148:151], v228 offset:17408
	ds_read_b128 v[152:155], v228 offset:18432
	ds_read_b128 v[194:197], v228 offset:19456
	ds_read_b128 v[198:201], v228 offset:20480
	ds_read_b128 v[202:205], v228 offset:21504
	ds_read_b128 v[206:209], v228 offset:22528
	ds_read_b128 v[210:213], v228 offset:23552
	global_load_lds_dwordx4 v188, s[30:31]
	s_mov_b64 s[100:101], s[30:31]
	s_mov_b32 m0, s39
	s_nop 0
	global_load_lds_dwordx4 v186, s[30:31]
	s_waitcnt lgkmcnt(0)
	s_setprio 1
	s_barrier
	v_mfma_f32_16x16x32_bf16 v[92:95], v[128:131], v[144:147], v[92:95]
	v_mfma_f32_16x16x32_bf16 v[88:91], v[136:139], v[144:147], v[88:91]
	v_mfma_f32_16x16x32_bf16 v[84:87], v[128:131], v[152:155], v[84:87]
	v_mfma_f32_16x16x32_bf16 v[80:83], v[136:139], v[152:155], v[80:83]
	v_mfma_f32_16x16x32_bf16 v[76:79], v[128:131], v[198:201], v[76:79]
	v_mfma_f32_16x16x32_bf16 v[72:75], v[136:139], v[198:201], v[72:75]
	v_mfma_f32_16x16x32_bf16 v[68:71], v[128:131], v[206:209], v[68:71]
	v_mfma_f32_16x16x32_bf16 v[64:67], v[136:139], v[206:209], v[64:67]
	v_mfma_f32_16x16x32_bf16 v[92:95], v[132:135], v[148:151], v[92:95]
	v_mfma_f32_16x16x32_bf16 v[88:91], v[140:143], v[148:151], v[88:91]
	v_mfma_f32_16x16x32_bf16 v[84:87], v[132:135], v[194:197], v[84:87]
	v_mfma_f32_16x16x32_bf16 v[80:83], v[140:143], v[194:197], v[80:83]
	v_mfma_f32_16x16x32_bf16 v[76:79], v[132:135], v[202:205], v[76:79]
	v_mfma_f32_16x16x32_bf16 v[72:75], v[140:143], v[202:205], v[72:75]
	v_mfma_f32_16x16x32_bf16 v[68:71], v[132:135], v[210:213], v[68:71]
	s_setprio 0
	v_mfma_f32_16x16x32_bf16 v[64:67], v[140:143], v[210:213], v[64:67]
	s_barrier
	s_add_u32 s24, s28, 0x80000
	s_addc_u32 s25, s29, 0
	s_add_i32 s47, s48, s37
	s_mov_b32 m0, s47
	s_nop 0
	global_load_lds_dwordx4 v188, s[24:25]
	s_add_i32 m0, s47, 0x2000
	s_nop 0
	global_load_lds_dwordx4 v186, s[24:25]
	s_waitcnt vmcnt(6)
	s_setprio 1
	s_barrier
; #define PG8_STAGE(bufoff, gbase) do { _Pragma("unroll") for (int _i = 0; _i < 2; ++_i) \
;         __builtin_amdgcn_global_load_lds((const unsigned*)((const char*)(gbase) + voff[_i]), (LAS unsigned*)(lds + (bufoff) + ldsw + _i * 8192), 16, 0, 0); } while (0)
; #define PG8_LDA(dst, b, h) do { _Pragma("unroll") for (int m = 0; m < 4; ++m) _Pragma("unroll") for (int k = 0; k < 2; ++k) dst[m][k] = *(const LAS bf16x8*)(lds + PG8_SA(b, h) + aoff + m * 2048 + k * 1024); } while (0)
; #define PG8_LDB(dst, b, h) do { _Pragma("unroll") for (int n = 0; n < 2; ++n) _Pragma("unroll") for (int k = 0; k < 2; ++k) dst[n][k] = *(const LAS bf16x8*)(lds + PG8_SB(b, h) + boff + n * 2048 + k * 1024); } while (0)
; #define PG8_MMA(ai, bj, At, Bt) do { __builtin_amdgcn_s_setprio(1); _Pragma("unroll") for (int m = 0; m < 4; ++m) _Pragma("unroll") for (int n = 0; n < 2; ++n) _Pragma("unroll") for (int k = 0; k < 2; ++k) \
;         acc[ai][bj][m][n] = __builtin_amdgcn_mfma_f32_16x16x32_bf16(Bt[n][k], At[m][k], acc[ai][bj][m][n], 0, 0, 0); __builtin_amdgcn_s_setprio(0); } while (0)
; #define PG8_WAIT_V(n) asm volatile("s_waitcnt vmcnt(" #n ")" ::: "memory")
; #define PG8_WAIT_L(n) asm volatile("s_waitcnt lgkmcnt(" #n ")" ::: "memory")
; #define PG8_BAR __builtin_amdgcn_s_barrier()
; #define PG8_SCHED __builtin_amdgcn_sched_barrier(0)
; template <class Epi>
; DI void gemm_phase(LAS unsigned char* lds, const Gemm g, const StaticOrder& S, const Epi& E) {
;     ...
;             PG8_WAIT_V(6); PG8_BAR; PG8_MMA(1, 1, At, B1); PG8_BAR;
;             PG8_LDB(B0, 1, 0); PG8_SCHED; PG8_LDA(At, 1, 0); PG8_STAGE(PG8_SA(0, 1), a2 + hstep);
;             PG8_WAIT_L(8); PG8_BAR; PG8_WAIT_L(0); PG8_MMA(0, 0, At, B0); PG8_BAR; PG8_SCHED;
;             PG8_LDB(B1, 1, 1); PG8_STAGE(PG8_SB(1, 0), b3);
;             PG8_BAR; PG8_WAIT_L(0); PG8_MMA(0, 1, At, B1); PG8_BAR;
;             PG8_LDA(At, 1, 1); PG8_STAGE(PG8_SA(1, 0), a3);
;             PG8_BAR; PG8_WAIT_L(0); PG8_MMA(1, 0, At, B0); PG8_BAR; PG8_SCHED;
;             PG8_STAGE(PG8_SB(1, 1), b3 + hstep);
	v_mfma_f32_16x16x32_bf16 v[28:31], v[214:217], v[144:147], v[28:31]
	v_mfma_f32_16x16x32_bf16 v[24:27], v[234:237], v[144:147], v[24:27]
	v_mfma_f32_16x16x32_bf16 v[20:23], v[214:217], v[152:155], v[20:23]
	v_mfma_f32_16x16x32_bf16 v[16:19], v[234:237], v[152:155], v[16:19]
	v_mfma_f32_16x16x32_bf16 v[12:15], v[214:217], v[198:201], v[12:15]
	v_mfma_f32_16x16x32_bf16 v[8:11], v[234:237], v[198:201], v[8:11]
	v_mfma_f32_16x16x32_bf16 v[4:7], v[214:217], v[206:209], v[4:7]
	v_mfma_f32_16x16x32_bf16 v[0:3], v[234:237], v[206:209], v[0:3]
	v_mfma_f32_16x16x32_bf16 v[28:31], v[230:233], v[148:151], v[28:31]
	s_add_i32 s47, 0, 0x18000
	v_mfma_f32_16x16x32_bf16 v[24:27], v[238:241], v[148:151], v[24:27]
	v_mfma_f32_16x16x32_bf16 v[20:23], v[230:233], v[194:197], v[20:23]
	v_mfma_f32_16x16x32_bf16 v[16:19], v[238:241], v[194:197], v[16:19]
	v_mfma_f32_16x16x32_bf16 v[12:15], v[230:233], v[202:205], v[12:15]
	v_mfma_f32_16x16x32_bf16 v[8:11], v[238:241], v[202:205], v[8:11]
	v_mfma_f32_16x16x32_bf16 v[4:7], v[230:233], v[210:213], v[4:7]
	s_setprio 0
	v_mfma_f32_16x16x32_bf16 v[0:3], v[238:241], v[210:213], v[0:3]
	s_barrier
	ds_read_b128 v[128:131], v226 offset:32768
	ds_read_b128 v[132:135], v226 offset:33792
	ds_read_b128 v[136:139], v226 offset:34816
	ds_read_b128 v[140:143], v226 offset:35840
	ds_read_b128 v[144:147], v228 offset:32768
	ds_read_b128 v[148:151], v228 offset:33792
	ds_read_b128 v[152:155], v228 offset:34816
	ds_read_b128 v[194:197], v228 offset:35840
	ds_read_b128 v[198:201], v228 offset:36864
	ds_read_b128 v[202:205], v228 offset:37888
	ds_read_b128 v[206:209], v228 offset:38912
	ds_read_b128 v[210:213], v228 offset:39936
	s_add_u32 s24, s30, 0x80000
	s_addc_u32 s25, s31, 0
	s_mov_b32 m0, s40
	s_nop 0
	global_load_lds_dwordx4 v188, s[24:25]
	s_mov_b32 m0, s41
	s_nop 0
	global_load_lds_dwordx4 v186, s[24:25]
	s_waitcnt lgkmcnt(8)
	s_setprio 1
	s_barrier
	s_waitcnt lgkmcnt(0)
	v_mfma_f32_16x16x32_bf16 v[124:127], v[128:131], v[144:147], v[124:127]
	v_mfma_f32_16x16x32_bf16 v[120:123], v[136:139], v[144:147], v[120:123]
	v_mfma_f32_16x16x32_bf16 v[116:119], v[128:131], v[152:155], v[116:119]
	v_mfma_f32_16x16x32_bf16 v[112:115], v[136:139], v[152:155], v[112:115]
	v_mfma_f32_16x16x32_bf16 v[108:111], v[128:131], v[198:201], v[108:111]
	v_mfma_f32_16x16x32_bf16 v[104:107], v[136:139], v[198:201], v[104:107]
	v_mfma_f32_16x16x32_bf16 v[100:103], v[128:131], v[206:209], v[100:103]
	v_mfma_f32_16x16x32_bf16 v[96:99], v[136:139], v[206:209], v[96:99]
	v_mfma_f32_16x16x32_bf16 v[124:127], v[132:135], v[148:151], v[124:127]
	v_mfma_f32_16x16x32_bf16 v[120:123], v[140:143], v[148:151], v[120:123]
	v_mfma_f32_16x16x32_bf16 v[116:119], v[132:135], v[194:197], v[116:119]
	v_mfma_f32_16x16x32_bf16 v[112:115], v[140:143], v[194:197], v[112:115]
	v_mfma_f32_16x16x32_bf16 v[108:111], v[132:135], v[202:205], v[108:111]
	v_mfma_f32_16x16x32_bf16 v[104:107], v[140:143], v[202:205], v[104:107]
	v_mfma_f32_16x16x32_bf16 v[100:103], v[132:135], v[210:213], v[100:103]
	s_setprio 0
	v_mfma_f32_16x16x32_bf16 v[96:99], v[140:143], v[210:213], v[96:99]
	s_barrier
	ds_read_b128 v[214:217], v226 offset:49152
	ds_read_b128 v[230:233], v226 offset:50176
	ds_read_b128 v[234:237], v226 offset:51200
	ds_read_b128 v[238:241], v226 offset:52224
	s_add_i32 s30, 0, 0x1c000
	s_add_i32 s24, s47, s37
	s_add_i32 m0, s24, 0xffffff80
	s_nop 0
	global_load_lds_dwordx4 v188, s[28:29] offset:128
	s_add_i32 m0, s24, 0x1f80
	s_nop 0
	global_load_lds_dwordx4 v186, s[28:29] offset:128
	s_waitcnt lgkmcnt(0)
	s_setprio 1
	s_barrier
	v_mfma_f32_16x16x32_bf16 v[60:63], v[214:217], v[144:147], v[60:63]
	v_mfma_f32_16x16x32_bf16 v[56:59], v[234:237], v[144:147], v[56:59]
	v_mfma_f32_16x16x32_bf16 v[52:55], v[214:217], v[152:155], v[52:55]
	v_mfma_f32_16x16x32_bf16 v[48:51], v[234:237], v[152:155], v[48:51]
	v_mfma_f32_16x16x32_bf16 v[44:47], v[214:217], v[198:201], v[44:47]
	v_mfma_f32_16x16x32_bf16 v[40:43], v[234:237], v[198:201], v[40:43]
	v_mfma_f32_16x16x32_bf16 v[36:39], v[214:217], v[206:209], v[36:39]
	v_mfma_f32_16x16x32_bf16 v[32:35], v[234:237], v[206:209], v[32:35]
	v_mfma_f32_16x16x32_bf16 v[60:63], v[230:233], v[148:151], v[60:63]
	s_add_i32 m0, s42, 0xffffff80
	v_mfma_f32_16x16x32_bf16 v[56:59], v[238:241], v[148:151], v[56:59]
	v_mfma_f32_16x16x32_bf16 v[52:55], v[230:233], v[194:197], v[52:55]
	v_mfma_f32_16x16x32_bf16 v[48:51], v[238:241], v[194:197], v[48:51]
	v_mfma_f32_16x16x32_bf16 v[44:47], v[230:233], v[202:205], v[44:47]
	v_mfma_f32_16x16x32_bf16 v[40:43], v[238:241], v[202:205], v[40:43]
	v_mfma_f32_16x16x32_bf16 v[36:39], v[230:233], v[210:213], v[36:39]
	s_setprio 0
	v_mfma_f32_16x16x32_bf16 v[32:35], v[238:241], v[210:213], v[32:35]
	s_barrier
	ds_read_b128 v[144:147], v228 offset:49152
	ds_read_b128 v[148:151], v228 offset:50176
	ds_read_b128 v[152:155], v228 offset:51200
	ds_read_b128 v[194:197], v228 offset:52224
	ds_read_b128 v[198:201], v228 offset:53248
	ds_read_b128 v[202:205], v228 offset:54272
	ds_read_b128 v[206:209], v228 offset:55296
	ds_read_b128 v[210:213], v228 offset:56320
	global_load_lds_dwordx4 v188, s[100:101] offset:128
	s_add_i32 m0, s43, 0xffffff80
	s_nop 0
	global_load_lds_dwordx4 v186, s[100:101] offset:128
	s_waitcnt lgkmcnt(0)
	s_setprio 1
	s_barrier
; #define PG8_STAGE(bufoff, gbase) do { _Pragma("unroll") for (int _i = 0; _i < 2; ++_i) \
;         __builtin_amdgcn_global_load_lds((const unsigned*)((const char*)(gbase) + voff[_i]), (LAS unsigned*)(lds + (bufoff) + ldsw + _i * 8192), 16, 0, 0); } while (0)
; #define PG8_MMA(ai, bj, At, Bt) do { __builtin_amdgcn_s_setprio(1); _Pragma("unroll") for (int m = 0; m < 4; ++m) _Pragma("unroll") for (int n = 0; n < 2; ++n) _Pragma("unroll") for (int k = 0; k < 2; ++k) \
;         acc[ai][bj][m][n] = __builtin_amdgcn_mfma_f32_16x16x32_bf16(Bt[n][k], At[m][k], acc[ai][bj][m][n], 0, 0, 0); __builtin_amdgcn_s_setprio(0); } while (0)
; #define PG8_WAIT_V(n) asm volatile("s_waitcnt vmcnt(" #n ")" ::: "memory")
; #define PG8_WAIT_L(n) asm volatile("s_waitcnt lgkmcnt(" #n ")" ::: "memory")
; #define PG8_BAR __builtin_amdgcn_s_barrier()
; #define PG8_SCHED __builtin_amdgcn_sched_barrier(0)
; template <class Epi>
; DI void gemm_phase(LAS unsigned char* lds, const Gemm g, const StaticOrder& S, const Epi& E) {
;     ...
;             PG8_BAR; PG8_WAIT_L(0); PG8_MMA(1, 0, At, B0); PG8_BAR; PG8_SCHED;
;             PG8_STAGE(PG8_SB(1, 1), b3 + hstep);
;             PG8_WAIT_V(6); PG8_BAR; PG8_MMA(1, 1, At, B1); PG8_BAR;
;     template <bool LN, int BJ> DI void load_gb(unsigned col0, f32x4 (&gv)[2], f32x4 (&bv)[2]) const {
; #pragma unroll
;         for (int n = 0; n < 2; ++n) {
;             if (LN) { gv[n] = *(const f32x4*)(gam + col0 + BJ * HALF + n * 16) * ALPHA; bv[n] = *(const f32x4*)(bet + col0 + BJ * HALF + n * 16) * ALPHA; }
;             else { gv[n] = (f32x4){ALPHA, ALPHA, ALPHA, ALPHA}; bv[n] = (f32x4){0.f, 0.f, 0.f, 0.f}; }
;         }
;     }
;     template <bool LN> DI void run(const f32x4 (&acc)[2][2][4][2], const Unit& u, int wr, int wc, int fr, int fq) const {
;         const unsigned row0 = u.pm * BM + wr * 64 + fr, col0 = u.pn * BM + wc * 32 + 4 * fq;
;         f32x4 gv[2], bv[2];
;         load_gb<LN, 0>(col0, gv, bv);
;         batch<LN, 0, 0, 4>(acc, row0, col0, gv, bv);
	v_mfma_f32_16x16x32_bf16 v[92:95], v[128:131], v[144:147], v[92:95]
	v_mfma_f32_16x16x32_bf16 v[88:91], v[136:139], v[144:147], v[88:91]
	v_mfma_f32_16x16x32_bf16 v[84:87], v[128:131], v[152:155], v[84:87]
	v_mfma_f32_16x16x32_bf16 v[80:83], v[136:139], v[152:155], v[80:83]
	v_mfma_f32_16x16x32_bf16 v[76:79], v[128:131], v[198:201], v[76:79]
	v_mfma_f32_16x16x32_bf16 v[72:75], v[136:139], v[198:201], v[72:75]
	v_mfma_f32_16x16x32_bf16 v[68:71], v[128:131], v[206:209], v[68:71]
	v_mfma_f32_16x16x32_bf16 v[64:67], v[136:139], v[206:209], v[64:67]
	v_mfma_f32_16x16x32_bf16 v[92:95], v[132:135], v[148:151], v[92:95]
	v_mfma_f32_16x16x32_bf16 v[88:91], v[140:143], v[148:151], v[88:91]
	v_mfma_f32_16x16x32_bf16 v[84:87], v[132:135], v[194:197], v[84:87]
	v_mfma_f32_16x16x32_bf16 v[80:83], v[140:143], v[194:197], v[80:83]
	v_mfma_f32_16x16x32_bf16 v[76:79], v[132:135], v[202:205], v[76:79]
	v_mfma_f32_16x16x32_bf16 v[72:75], v[140:143], v[202:205], v[72:75]
	v_mfma_f32_16x16x32_bf16 v[68:71], v[132:135], v[210:213], v[68:71]
	s_setprio 0
	v_mfma_f32_16x16x32_bf16 v[64:67], v[140:143], v[210:213], v[64:67]
	s_barrier
	s_add_u32 s24, s28, 0x80080
	s_addc_u32 s25, s29, 0
	s_add_i32 s28, s30, s37
	s_mov_b32 m0, s28
	s_nop 0
	global_load_lds_dwordx4 v188, s[24:25]
	s_add_i32 m0, s28, 0x2000
	s_nop 0
	global_load_lds_dwordx4 v186, s[24:25]
	s_waitcnt vmcnt(6)
	s_setprio 1
	s_barrier
	v_mfma_f32_16x16x32_bf16 v[28:31], v[214:217], v[144:147], v[28:31]
	v_mfma_f32_16x16x32_bf16 v[24:27], v[234:237], v[144:147], v[24:27]
	v_mfma_f32_16x16x32_bf16 v[20:23], v[214:217], v[152:155], v[20:23]
	v_mfma_f32_16x16x32_bf16 v[16:19], v[234:237], v[152:155], v[16:19]
	v_mfma_f32_16x16x32_bf16 v[12:15], v[214:217], v[198:201], v[12:15]
	v_mfma_f32_16x16x32_bf16 v[8:11], v[234:237], v[198:201], v[8:11]
	v_mfma_f32_16x16x32_bf16 v[4:7], v[214:217], v[206:209], v[4:7]
	v_mfma_f32_16x16x32_bf16 v[0:3], v[234:237], v[206:209], v[0:3]
	v_mfma_f32_16x16x32_bf16 v[28:31], v[230:233], v[148:151], v[28:31]
	s_add_i32 s46, s46, 2
	v_mfma_f32_16x16x32_bf16 v[24:27], v[238:241], v[148:151], v[24:27]
	s_add_u32 s33, s33, 0x100
	v_mfma_f32_16x16x32_bf16 v[20:23], v[230:233], v[194:197], v[20:23]
	s_addc_u32 s45, s45, 0
	v_mfma_f32_16x16x32_bf16 v[16:19], v[238:241], v[194:197], v[16:19]
	s_cmp_gt_u32 s46, 29
	v_mfma_f32_16x16x32_bf16 v[12:15], v[230:233], v[202:205], v[12:15]
	s_mov_b64 s[24:25], s[26:27]
	v_mfma_f32_16x16x32_bf16 v[8:11], v[238:241], v[202:205], v[8:11]
	v_mfma_f32_16x16x32_bf16 v[4:7], v[230:233], v[210:213], v[4:7]
	s_setprio 0
	v_mfma_f32_16x16x32_bf16 v[0:3], v[238:241], v[210:213], v[0:3]
	s_barrier
	s_cbranch_scc0 .LBB0_320
	v_lshl_add_u32 v206, s3, 8, v225
	v_lshl_or_b32 v158, s2, 8, v227
	v_lshlrev_b32_e32 v232, 11, v206
	s_andn2_b64 vcc, exec, s[14:15]
	v_or_b32_e32 v231, 16, v158
	v_add_u32_e32 v194, v232, v158
	v_or_b32_e32 v230, 0x80, v158
	v_or_b32_e32 v229, 0x90, v158
	s_cbranch_vccnz .LBB0_323
	v_lshlrev_b64 v[132:133], 2, v[158:159]
	v_lshl_add_u64 v[140:141], s[16:17], 0, v[132:133]
	global_load_dwordx4 v[128:131], v[140:141], off
	v_lshl_add_u64 v[142:143], s[18:19], 0, v[132:133]
	v_readlane_b32 s2, v253, 8
	v_mov_b32_e32 v195, v159
	v_lshlrev_b32_e32 v136, 1, v206
	v_mov_b32_e32 v137, v159
	v_readlane_b32 s3, v253, 9
	v_lshlrev_b64 v[212:213], 2, v[194:195]
	v_add_u32_e32 v146, v232, v231
	v_lshl_add_u64 v[144:145], v[136:137], 2, s[2:3]
	v_lshl_add_u64 v[136:137], s[88:89], 0, v[212:213]
	v_mov_b32_e32 v147, v159
	v_lshl_add_u64 v[146:147], v[146:147], 2, s[88:89]
	v_or_b32_e32 v195, 16, v206
	v_mov_b32_e32 v201, v159
	v_mov_b32_e32 v209, v159
	v_lshl_add_u64 v[212:213], s[90:91], 0, v[212:213]
	s_waitcnt vmcnt(0)
	v_pk_mul_f32 v[152:153], v[130:131], s[78:79] op_sel_hi:[1,0]
	v_pk_mul_f32 v[154:155], v[128:129], s[78:79] op_sel_hi:[1,0]
	global_load_dwordx4 v[132:135], v[142:143], off
	global_load_dwordx4 v[128:131], v[140:141], off offset:64
	global_load_dwordx2 v[204:205], v[144:145], off
	global_load_dwordx4 v[196:199], v[146:147], off
	v_lshlrev_b32_e32 v146, 1, v195
	global_load_dwordx4 v[136:139], v[136:137], off
	v_lshlrev_b32_e32 v195, 11, v195
	v_mov_b32_e32 v147, v159
	v_add_u32_e32 v200, v195, v158
	v_lshl_add_u64 v[146:147], v[146:147], 2, s[2:3]
	v_lshl_add_u64 v[200:201], v[200:201], 2, s[88:89]
	global_load_dwordx2 v[214:215], v[146:147], off
	v_add_u32_e32 v208, v195, v231
	global_load_dwordx4 v[200:203], v[200:201], off
	v_lshl_add_u64 v[208:209], v[208:209], 2, s[88:89]
	global_load_dwordx4 v[208:211], v[208:209], off
	s_waitcnt vmcnt(0)
	v_pk_mul_f32 v[148:149], v[130:131], s[78:79] op_sel_hi:[1,0]
	v_pk_mul_f32 v[150:151], v[128:129], s[78:79] op_sel_hi:[1,0]
	global_load_dwordx4 v[128:131], v[142:143], off offset:64
	v_sub_f32_e32 v137, v137, v204
	v_sub_f32_e32 v136, v136, v204
	v_sub_f32_e32 v139, v139, v204
	v_sub_f32_e32 v138, v138, v204
	v_pk_mul_f32 v[138:139], v[204:205], v[138:139] op_sel:[1,0]
	v_pk_mul_f32 v[136:137], v[204:205], v[136:137] op_sel:[1,0]
	v_pk_fma_f32 v[138:139], v[152:153], v[138:139], v[126:127]
	v_pk_fma_f32 v[136:137], v[154:155], v[136:137], v[124:125]
	v_pk_fma_f32 v[138:139], v[134:135], s[78:79], v[138:139] op_sel_hi:[1,0,1]
	v_pk_fma_f32 v[136:137], v[132:133], s[78:79], v[136:137] op_sel_hi:[1,0,1]
	global_store_dwordx4 v[212:213], v[136:139], off
	s_nop 1
	v_sub_f32_e32 v137, v197, v204
	v_sub_f32_e32 v136, v196, v204
	v_sub_f32_e32 v139, v199, v204
	v_sub_f32_e32 v138, v198, v204
	v_pk_mul_f32 v[138:139], v[204:205], v[138:139] op_sel:[1,0]
	v_pk_mul_f32 v[136:137], v[204:205], v[136:137] op_sel:[1,0]
	v_pk_fma_f32 v[138:139], v[148:149], v[138:139], v[122:123]
	v_pk_fma_f32 v[136:137], v[150:151], v[136:137], v[120:121]
	v_or_b32_e32 v196, 16, v194
	v_mov_b32_e32 v197, v159
	v_lshl_add_u64 v[196:197], v[196:197], 2, s[90:91]
	s_waitcnt vmcnt(0)
;     template <bool LN, int BJ, int LO, int HI> DI void batch(const f32x4 (&acc)[2][2][4][2], unsigned row0, unsigned col0, const f32x4 (&gv)[2], const f32x4 (&bv)[2]) const {
;         f32x4 r[HI - LO]; float mean[(HI - LO) / 2], rstd[(HI - LO) / 2];
; #pragma unroll
;         for (int i = LO; i < HI; ++i) { const int ai = i >> 3, m = (i >> 1) & 3, n = i & 1; const unsigned row = row0 + ai * HALF + m * 16;
;             if (n == 0) { mean[(i - LO) >> 1] = 0.f; rstd[(i - LO) >> 1] = 1.f;
;                 if (LN) { const float2 st = *(const float2*)(stats + row * 2u); mean[(i - LO) >> 1] = st.x; rstd[(i - LO) >> 1] = st.y; } }
;             r[i - LO] = *(const f32x4*)(src + (row * (unsigned)DM + col0 + BJ * HALF + n * 16)); }
; #pragma unroll
;         for (int i = LO; i < HI; ++i) { const int ai = i >> 3, m = (i >> 1) & 3, n = i & 1; const unsigned row = row0 + ai * HALF + m * 16;
;             *(f32x4*)(Y + (row * (unsigned)DM + col0 + BJ * HALF + n * 16)) = acc[ai][BJ][m][n] + ((r[i - LO] - mean[(i - LO) >> 1]) * rstd[(i - LO) >> 1]) * gv[n] + bv[n]; }
	v_pk_fma_f32 v[138:139], v[130:131], s[78:79], v[138:139] op_sel_hi:[1,0,1]
	v_pk_fma_f32 v[136:137], v[128:129], s[78:79], v[136:137] op_sel_hi:[1,0,1]
	global_store_dwordx4 v[196:197], v[136:139], off
	v_add_u32_e32 v196, 0x8000, v194
	v_mov_b32_e32 v197, v159
	v_sub_f32_e32 v137, v201, v214
	v_sub_f32_e32 v136, v200, v214
	v_sub_f32_e32 v139, v203, v214
	v_sub_f32_e32 v138, v202, v214
	v_pk_mul_f32 v[138:139], v[214:215], v[138:139] op_sel:[1,0]
	v_pk_mul_f32 v[136:137], v[214:215], v[136:137] op_sel:[1,0]
	v_pk_fma_f32 v[138:139], v[152:153], v[138:139], v[118:119]
	v_pk_fma_f32 v[136:137], v[154:155], v[136:137], v[116:117]
	v_pk_fma_f32 v[138:139], v[134:135], s[78:79], v[138:139] op_sel_hi:[1,0,1]
	v_pk_fma_f32 v[136:137], v[132:133], s[78:79], v[136:137] op_sel_hi:[1,0,1]
	v_lshl_add_u64 v[196:197], v[196:197], 2, s[90:91]
	global_store_dwordx4 v[196:197], v[136:139], off
	v_add_u32_e32 v196, 0x8010, v194
	v_mov_b32_e32 v197, v159
	v_sub_f32_e32 v137, v209, v214
	v_sub_f32_e32 v136, v208, v214
	v_sub_f32_e32 v139, v211, v214
	v_sub_f32_e32 v138, v210, v214
	v_pk_mul_f32 v[138:139], v[214:215], v[138:139] op_sel:[1,0]
	v_pk_mul_f32 v[136:137], v[214:215], v[136:137] op_sel:[1,0]
	v_pk_fma_f32 v[138:139], v[148:149], v[138:139], v[114:115]
	v_pk_fma_f32 v[136:137], v[150:151], v[136:137], v[112:113]
	v_pk_fma_f32 v[138:139], v[130:131], s[78:79], v[138:139] op_sel_hi:[1,0,1]
	v_pk_fma_f32 v[136:137], v[128:129], s[78:79], v[136:137] op_sel_hi:[1,0,1]
	v_lshl_add_u64 v[196:197], v[196:197], 2, s[90:91]
	global_store_dwordx4 v[196:197], v[136:139], off
	s_nop 1
	v_or_b32_e32 v138, 32, v206
	v_lshlrev_b32_e32 v136, 1, v138
	v_mov_b32_e32 v137, v159
	v_lshlrev_b32_e32 v236, 11, v138
	v_lshl_add_u64 v[200:201], v[136:137], 2, s[2:3]
	v_add_u32_e32 v136, v236, v158
	v_lshl_add_u64 v[136:137], v[136:137], 2, s[88:89]
	global_load_dwordx2 v[204:205], v[200:201], off
	v_add_u32_e32 v196, v236, v231
	global_load_dwordx4 v[136:139], v[136:137], off
	v_mov_b32_e32 v197, v159
	v_lshl_add_u64 v[196:197], v[196:197], 2, s[88:89]
	global_load_dwordx4 v[196:199], v[196:197], off
	v_or_b32_e32 v207, 48, v206
	v_lshlrev_b32_e32 v235, 11, v207
	v_lshlrev_b32_e32 v202, 1, v207
	v_mov_b32_e32 v203, v159
	v_add_u32_e32 v208, v235, v158
	v_mov_b32_e32 v209, v159
	v_lshl_add_u64 v[202:203], v[202:203], 2, s[2:3]
	v_lshl_add_u64 v[208:209], v[208:209], 2, s[88:89]
	global_load_dwordx2 v[216:217], v[202:203], off
	v_add_u32_e32 v212, v235, v231
	global_load_dwordx4 v[208:211], v[208:209], off
	v_mov_b32_e32 v213, v159
	v_lshl_add_u64 v[212:213], v[212:213], 2, s[88:89]
	global_load_dwordx4 v[212:215], v[212:213], off
	v_add_u32_e32 v218, 0x10000, v194
	v_mov_b32_e32 v219, v159
	v_lshl_add_u64 v[218:219], v[218:219], 2, s[90:91]
	s_waitcnt vmcnt(0)
	v_sub_f32_e32 v137, v137, v204
	v_sub_f32_e32 v136, v136, v204
	v_sub_f32_e32 v139, v139, v204
	v_sub_f32_e32 v138, v138, v204
	v_pk_mul_f32 v[138:139], v[204:205], v[138:139] op_sel:[1,0]
	v_pk_mul_f32 v[136:137], v[204:205], v[136:137] op_sel:[1,0]
	v_pk_fma_f32 v[138:139], v[152:153], v[138:139], v[110:111]
	v_pk_fma_f32 v[136:137], v[154:155], v[136:137], v[108:109]
	v_pk_fma_f32 v[138:139], v[134:135], s[78:79], v[138:139] op_sel_hi:[1,0,1]
	v_pk_fma_f32 v[136:137], v[132:133], s[78:79], v[136:137] op_sel_hi:[1,0,1]
	global_store_dwordx4 v[218:219], v[136:139], off
	s_nop 1
	v_sub_f32_e32 v137, v197, v204
	v_sub_f32_e32 v136, v196, v204
	v_sub_f32_e32 v139, v199, v204
	v_sub_f32_e32 v138, v198, v204
	v_pk_mul_f32 v[138:139], v[204:205], v[138:139] op_sel:[1,0]
	v_pk_mul_f32 v[136:137], v[204:205], v[136:137] op_sel:[1,0]
	v_pk_fma_f32 v[138:139], v[148:149], v[138:139], v[106:107]
	v_pk_fma_f32 v[136:137], v[150:151], v[136:137], v[104:105]
	v_add_u32_e32 v196, 0x10010, v194
	v_mov_b32_e32 v197, v159
	v_pk_fma_f32 v[138:139], v[130:131], s[78:79], v[138:139] op_sel_hi:[1,0,1]
	v_pk_fma_f32 v[136:137], v[128:129], s[78:79], v[136:137] op_sel_hi:[1,0,1]
	v_lshl_add_u64 v[196:197], v[196:197], 2, s[90:91]
	global_store_dwordx4 v[196:197], v[136:139], off
	v_add_u32_e32 v196, 0x18000, v194
	v_mov_b32_e32 v197, v159
	v_sub_f32_e32 v137, v209, v216
	v_sub_f32_e32 v136, v208, v216
	v_sub_f32_e32 v139, v211, v216
	v_sub_f32_e32 v138, v210, v216
	v_pk_mul_f32 v[138:139], v[216:217], v[138:139] op_sel:[1,0]
	v_pk_mul_f32 v[136:137], v[216:217], v[136:137] op_sel:[1,0]
	v_pk_fma_f32 v[138:139], v[152:153], v[138:139], v[102:103]
	v_pk_fma_f32 v[136:137], v[154:155], v[136:137], v[100:101]
	v_pk_fma_f32 v[138:139], v[134:135], s[78:79], v[138:139] op_sel_hi:[1,0,1]
	v_pk_fma_f32 v[136:137], v[132:133], s[78:79], v[136:137] op_sel_hi:[1,0,1]
	v_lshl_add_u64 v[196:197], v[196:197], 2, s[90:91]
	global_store_dwordx4 v[196:197], v[136:139], off
	v_add_u32_e32 v196, 0x18010, v194
	v_mov_b32_e32 v197, v159
	v_sub_f32_e32 v137, v213, v216
	v_sub_f32_e32 v136, v212, v216
	v_sub_f32_e32 v139, v215, v216
	v_sub_f32_e32 v138, v214, v216
	v_pk_mul_f32 v[138:139], v[216:217], v[138:139] op_sel:[1,0]
	v_pk_mul_f32 v[136:137], v[216:217], v[136:137] op_sel:[1,0]
	v_pk_fma_f32 v[138:139], v[148:149], v[138:139], v[98:99]
	v_pk_fma_f32 v[136:137], v[150:151], v[136:137], v[96:97]
	v_pk_fma_f32 v[138:139], v[130:131], s[78:79], v[138:139] op_sel_hi:[1,0,1]
	v_pk_fma_f32 v[136:137], v[128:129], s[78:79], v[136:137] op_sel_hi:[1,0,1]
	v_lshl_add_u64 v[196:197], v[196:197], 2, s[90:91]
	global_store_dwordx4 v[196:197], v[136:139], off
	s_nop 1
	v_add_u32_e32 v138, 0x80, v206
	v_lshlrev_b32_e32 v136, 1, v138
	v_mov_b32_e32 v137, v159
	v_lshlrev_b32_e32 v233, 11, v138
	v_lshl_add_u64 v[196:197], v[136:137], 2, s[2:3]
	v_add_u32_e32 v136, v233, v158
	v_lshl_add_u64 v[136:137], v[136:137], 2, s[88:89]
	global_load_dwordx2 v[204:205], v[196:197], off
	v_add_u32_e32 v198, v233, v231
	global_load_dwordx4 v[136:139], v[136:137], off
	v_mov_b32_e32 v199, v159
	v_add_u32_e32 v207, 0x90, v206
	v_lshl_add_u64 v[198:199], v[198:199], 2, s[88:89]
	v_lshlrev_b32_e32 v234, 11, v207
	global_load_dwordx4 v[208:211], v[198:199], off
	v_add_u32_e32 v212, v234, v158
	v_mov_b32_e32 v213, v159
	v_lshl_add_u64 v[212:213], v[212:213], 2, s[88:89]
	global_load_dwordx4 v[212:215], v[212:213], off
	v_lshlrev_b32_e32 v198, 1, v207
	v_mov_b32_e32 v199, v159
	v_lshl_add_u64 v[198:199], v[198:199], 2, s[2:3]
	global_load_dwordx2 v[238:239], v[198:199], off
	v_add_u32_e32 v216, v234, v231
	v_mov_b32_e32 v217, v159
	v_lshl_add_u64 v[216:217], v[216:217], 2, s[88:89]
	global_load_dwordx4 v[216:219], v[216:217], off
	v_add_u32_e32 v240, 0x40000, v194
	v_mov_b32_e32 v241, v159
	v_lshl_add_u64 v[240:241], v[240:241], 2, s[90:91]
	s_waitcnt vmcnt(0)
;     template <bool LN, int BJ, int LO, int HI> DI void batch(const f32x4 (&acc)[2][2][4][2], unsigned row0, unsigned col0, const f32x4 (&gv)[2], const f32x4 (&bv)[2]) const {
;         f32x4 r[HI - LO]; float mean[(HI - LO) / 2], rstd[(HI - LO) / 2];
; #pragma unroll
;         for (int i = LO; i < HI; ++i) { const int ai = i >> 3, m = (i >> 1) & 3, n = i & 1; const unsigned row = row0 + ai * HALF + m * 16;
;             if (n == 0) { mean[(i - LO) >> 1] = 0.f; rstd[(i - LO) >> 1] = 1.f;
;                 if (LN) { const float2 st = *(const float2*)(stats + row * 2u); mean[(i - LO) >> 1] = st.x; rstd[(i - LO) >> 1] = st.y; } }
;             r[i - LO] = *(const f32x4*)(src + (row * (unsigned)DM + col0 + BJ * HALF + n * 16)); }
; #pragma unroll
;         for (int i = LO; i < HI; ++i) { const int ai = i >> 3, m = (i >> 1) & 3, n = i & 1; const unsigned row = row0 + ai * HALF + m * 16;
;             *(f32x4*)(Y + (row * (unsigned)DM + col0 + BJ * HALF + n * 16)) = acc[ai][BJ][m][n] + ((r[i - LO] - mean[(i - LO) >> 1]) * rstd[(i - LO) >> 1]) * gv[n] + bv[n]; }
	v_sub_f32_e32 v137, v137, v204
	v_sub_f32_e32 v136, v136, v204
	v_sub_f32_e32 v139, v139, v204
	v_sub_f32_e32 v138, v138, v204
	v_pk_mul_f32 v[138:139], v[204:205], v[138:139] op_sel:[1,0]
	v_pk_mul_f32 v[136:137], v[204:205], v[136:137] op_sel:[1,0]
	v_pk_fma_f32 v[138:139], v[152:153], v[138:139], v[94:95]
	v_pk_fma_f32 v[136:137], v[154:155], v[136:137], v[92:93]
	v_pk_fma_f32 v[138:139], v[134:135], s[78:79], v[138:139] op_sel_hi:[1,0,1]
	v_pk_fma_f32 v[136:137], v[132:133], s[78:79], v[136:137] op_sel_hi:[1,0,1]
	global_store_dwordx4 v[240:241], v[136:139], off
	s_nop 1
	v_sub_f32_e32 v137, v209, v204
	v_sub_f32_e32 v136, v208, v204
	v_sub_f32_e32 v139, v211, v204
	v_sub_f32_e32 v138, v210, v204
	v_pk_mul_f32 v[138:139], v[204:205], v[138:139] op_sel:[1,0]
	v_pk_mul_f32 v[136:137], v[204:205], v[136:137] op_sel:[1,0]
	v_pk_fma_f32 v[138:139], v[148:149], v[138:139], v[90:91]
	v_pk_fma_f32 v[136:137], v[150:151], v[136:137], v[88:89]
	v_add_u32_e32 v204, 0x40010, v194
	v_mov_b32_e32 v205, v159
	v_pk_fma_f32 v[138:139], v[130:131], s[78:79], v[138:139] op_sel_hi:[1,0,1]
	v_pk_fma_f32 v[136:137], v[128:129], s[78:79], v[136:137] op_sel_hi:[1,0,1]
	v_lshl_add_u64 v[204:205], v[204:205], 2, s[90:91]
	global_store_dwordx4 v[204:205], v[136:139], off
	v_add_u32_e32 v204, 0x48000, v194
	v_mov_b32_e32 v205, v159
	v_sub_f32_e32 v137, v213, v238
	v_sub_f32_e32 v136, v212, v238
	v_sub_f32_e32 v139, v215, v238
	v_sub_f32_e32 v138, v214, v238
	v_pk_mul_f32 v[138:139], v[238:239], v[138:139] op_sel:[1,0]
	v_pk_mul_f32 v[136:137], v[238:239], v[136:137] op_sel:[1,0]
	v_pk_fma_f32 v[138:139], v[152:153], v[138:139], v[86:87]
	v_pk_fma_f32 v[136:137], v[154:155], v[136:137], v[84:85]
	v_pk_fma_f32 v[138:139], v[134:135], s[78:79], v[138:139] op_sel_hi:[1,0,1]
	v_pk_fma_f32 v[136:137], v[132:133], s[78:79], v[136:137] op_sel_hi:[1,0,1]
	v_lshl_add_u64 v[204:205], v[204:205], 2, s[90:91]
	global_store_dwordx4 v[204:205], v[136:139], off
	v_add_u32_e32 v204, 0x48010, v194
	v_mov_b32_e32 v205, v159
	v_sub_f32_e32 v137, v217, v238
	v_sub_f32_e32 v136, v216, v238
	v_sub_f32_e32 v139, v219, v238
	v_sub_f32_e32 v138, v218, v238
	v_pk_mul_f32 v[138:139], v[238:239], v[138:139] op_sel:[1,0]
	v_pk_mul_f32 v[136:137], v[238:239], v[136:137] op_sel:[1,0]
	v_pk_fma_f32 v[138:139], v[148:149], v[138:139], v[82:83]
	v_pk_fma_f32 v[136:137], v[150:151], v[136:137], v[80:81]
	v_pk_fma_f32 v[138:139], v[130:131], s[78:79], v[138:139] op_sel_hi:[1,0,1]
	v_pk_fma_f32 v[136:137], v[128:129], s[78:79], v[136:137] op_sel_hi:[1,0,1]
	v_lshl_add_u64 v[204:205], v[204:205], 2, s[90:91]
	global_store_dwordx4 v[204:205], v[136:139], off
	s_nop 1
	v_add_u32_e32 v138, 0xa0, v206
	v_lshlrev_b32_e32 v136, 1, v138
	v_mov_b32_e32 v137, v159
	v_lshlrev_b32_e32 v237, 11, v138
	v_lshl_add_u64 v[204:205], v[136:137], 2, s[2:3]
	v_add_u32_e32 v136, v237, v158
	v_lshl_add_u64 v[136:137], v[136:137], 2, s[88:89]
	global_load_dwordx2 v[240:241], v[204:205], off
	v_add_u32_e32 v208, v237, v231
	global_load_dwordx4 v[136:139], v[136:137], off
	v_mov_b32_e32 v209, v159
	v_lshl_add_u64 v[208:209], v[208:209], 2, s[88:89]
	global_load_dwordx4 v[212:215], v[208:209], off
	v_add_u32_e32 v208, 0xb0, v206
	v_lshlrev_b32_e32 v206, 1, v208
	v_mov_b32_e32 v207, v159
	v_lshlrev_b32_e32 v238, 11, v208
	v_lshl_add_u64 v[210:211], v[206:207], 2, s[2:3]
	v_add_u32_e32 v206, v238, v158
	v_lshl_add_u64 v[206:207], v[206:207], 2, s[88:89]
	global_load_dwordx2 v[242:243], v[210:211], off
	v_add_u32_e32 v216, v238, v231
	global_load_dwordx4 v[206:209], v[206:207], off
	v_mov_b32_e32 v217, v159
	v_lshl_add_u64 v[216:217], v[216:217], 2, s[88:89]
	global_load_dwordx4 v[216:219], v[216:217], off
	v_add_u32_e32 v244, 0x50000, v194
	v_mov_b32_e32 v245, v159
	v_lshl_add_u64 v[244:245], v[244:245], 2, s[90:91]
	s_waitcnt vmcnt(0)
	v_sub_f32_e32 v137, v137, v240
	v_sub_f32_e32 v136, v136, v240
	v_sub_f32_e32 v139, v139, v240
	v_sub_f32_e32 v138, v138, v240
	v_pk_mul_f32 v[138:139], v[240:241], v[138:139] op_sel:[1,0]
	v_pk_mul_f32 v[136:137], v[240:241], v[136:137] op_sel:[1,0]
	v_pk_fma_f32 v[138:139], v[152:153], v[138:139], v[78:79]
	v_pk_fma_f32 v[136:137], v[154:155], v[136:137], v[76:77]
	v_pk_fma_f32 v[138:139], v[134:135], s[78:79], v[138:139] op_sel_hi:[1,0,1]
	v_pk_fma_f32 v[136:137], v[132:133], s[78:79], v[136:137] op_sel_hi:[1,0,1]
	global_store_dwordx4 v[244:245], v[136:139], off
	s_nop 1
	v_sub_f32_e32 v137, v213, v240
	v_sub_f32_e32 v136, v212, v240
	v_sub_f32_e32 v139, v215, v240
	v_sub_f32_e32 v138, v214, v240
	v_pk_mul_f32 v[138:139], v[240:241], v[138:139] op_sel:[1,0]
	v_pk_mul_f32 v[136:137], v[240:241], v[136:137] op_sel:[1,0]
	v_pk_fma_f32 v[138:139], v[148:149], v[138:139], v[74:75]
	v_pk_fma_f32 v[136:137], v[150:151], v[136:137], v[72:73]
	v_add_u32_e32 v212, 0x50010, v194
	v_mov_b32_e32 v213, v159
	v_pk_fma_f32 v[138:139], v[130:131], s[78:79], v[138:139] op_sel_hi:[1,0,1]
	v_pk_fma_f32 v[136:137], v[128:129], s[78:79], v[136:137] op_sel_hi:[1,0,1]
	v_lshl_add_u64 v[212:213], v[212:213], 2, s[90:91]
	global_store_dwordx4 v[212:213], v[136:139], off
	s_nop 1
	v_sub_f32_e32 v137, v207, v242
	v_sub_f32_e32 v136, v206, v242
	v_sub_f32_e32 v139, v209, v242
	v_sub_f32_e32 v138, v208, v242
	v_pk_mul_f32 v[136:137], v[242:243], v[136:137] op_sel:[1,0]
	v_pk_mul_f32 v[138:139], v[242:243], v[138:139] op_sel:[1,0]
	v_pk_fma_f32 v[136:137], v[154:155], v[136:137], v[68:69]
	v_pk_fma_f32 v[138:139], v[152:153], v[138:139], v[70:71]
	v_pk_fma_f32 v[132:133], v[132:133], s[78:79], v[136:137] op_sel_hi:[1,0,1]
	v_add_u32_e32 v136, 0x58000, v194
	v_mov_b32_e32 v137, v159
	v_pk_fma_f32 v[134:135], v[134:135], s[78:79], v[138:139] op_sel_hi:[1,0,1]
	v_lshl_add_u64 v[136:137], v[136:137], 2, s[90:91]
	global_store_dwordx4 v[136:137], v[132:135], off
	s_nop 1
	v_sub_f32_e32 v133, v217, v242
	v_sub_f32_e32 v132, v216, v242
	v_sub_f32_e32 v135, v219, v242
	v_sub_f32_e32 v134, v218, v242
	v_pk_mul_f32 v[132:133], v[242:243], v[132:133] op_sel:[1,0]
	v_pk_mul_f32 v[134:135], v[242:243], v[134:135] op_sel:[1,0]
	v_pk_fma_f32 v[132:133], v[150:151], v[132:133], v[64:65]
	v_pk_fma_f32 v[134:135], v[148:149], v[134:135], v[66:67]
	v_pk_fma_f32 v[128:129], v[128:129], s[78:79], v[132:133] op_sel_hi:[1,0,1]
	v_add_u32_e32 v132, 0x58010, v194
	v_mov_b32_e32 v133, v159
	v_pk_fma_f32 v[130:131], v[130:131], s[78:79], v[134:135] op_sel_hi:[1,0,1]
	v_lshl_add_u64 v[132:133], v[132:133], 2, s[90:91]
	global_store_dwordx4 v[132:133], v[128:131], off
	global_load_dwordx4 v[128:131], v[140:141], off offset:512
	v_add_u32_e32 v136, v232, v230
	v_mov_b32_e32 v137, v159
	v_lshl_add_u64 v[136:137], v[136:137], 2, s[88:89]
	s_waitcnt vmcnt(0)
;     template <bool LN, int BJ, int LO, int HI> DI void batch(const f32x4 (&acc)[2][2][4][2], unsigned row0, unsigned col0, const f32x4 (&gv)[2], const f32x4 (&bv)[2]) const {
;         f32x4 r[HI - LO]; float mean[(HI - LO) / 2], rstd[(HI - LO) / 2];
; #pragma unroll
;         for (int i = LO; i < HI; ++i) { const int ai = i >> 3, m = (i >> 1) & 3, n = i & 1; const unsigned row = row0 + ai * HALF + m * 16;
;             if (n == 0) { mean[(i - LO) >> 1] = 0.f; rstd[(i - LO) >> 1] = 1.f;
;                 if (LN) { const float2 st = *(const float2*)(stats + row * 2u); mean[(i - LO) >> 1] = st.x; rstd[(i - LO) >> 1] = st.y; } }
;             r[i - LO] = *(const f32x4*)(src + (row * (unsigned)DM + col0 + BJ * HALF + n * 16)); }
; #pragma unroll
;         for (int i = LO; i < HI; ++i) { const int ai = i >> 3, m = (i >> 1) & 3, n = i & 1; const unsigned row = row0 + ai * HALF + m * 16;
;             *(f32x4*)(Y + (row * (unsigned)DM + col0 + BJ * HALF + n * 16)) = acc[ai][BJ][m][n] + ((r[i - LO] - mean[(i - LO) >> 1]) * rstd[(i - LO) >> 1]) * gv[n] + bv[n]; }
;         __builtin_amdgcn_sched_barrier(0);
;     }
;     template <bool LN, int BJ> DI void load_gb(unsigned col0, f32x4 (&gv)[2], f32x4 (&bv)[2]) const {
; #pragma unroll
;         for (int n = 0; n < 2; ++n) {
;             if (LN) { gv[n] = *(const f32x4*)(gam + col0 + BJ * HALF + n * 16) * ALPHA; bv[n] = *(const f32x4*)(bet + col0 + BJ * HALF + n * 16) * ALPHA; }
;             else { gv[n] = (f32x4){ALPHA, ALPHA, ALPHA, ALPHA}; bv[n] = (f32x4){0.f, 0.f, 0.f, 0.f}; }
;         }
;     }
;     template <bool LN> DI void run(const f32x4 (&acc)[2][2][4][2], const Unit& u, int wr, int wc, int fr, int fq) const {
;         const unsigned row0 = u.pm * BM + wr * 64 + fr, col0 = u.pn * BM + wc * 32 + 4 * fq;
;         f32x4 gv[2], bv[2];
;         load_gb<LN, 0>(col0, gv, bv);
;         batch<LN, 0, 0, 4>(acc, row0, col0, gv, bv);
;         batch<LN, 0, 4, 8>(acc, row0, col0, gv, bv);
;         batch<LN, 0, 8, 12>(acc, row0, col0, gv, bv);
;         batch<LN, 0, 12, 16>(acc, row0, col0, gv, bv);
;         load_gb<LN, 1>(col0, gv, bv);
;         batch<LN, 1, 0, 8>(acc, row0, col0, gv, bv);
	v_pk_mul_f32 v[212:213], v[130:131], s[78:79] op_sel_hi:[1,0]
	v_pk_mul_f32 v[214:215], v[128:129], s[78:79] op_sel_hi:[1,0]
	global_load_dwordx4 v[132:135], v[142:143], off offset:512
	global_load_dwordx4 v[128:131], v[140:141], off offset:576
	s_waitcnt vmcnt(0)
	v_pk_mul_f32 v[206:207], v[130:131], s[78:79] op_sel_hi:[1,0]
	v_pk_mul_f32 v[208:209], v[128:129], s[78:79] op_sel_hi:[1,0]
	global_load_dwordx4 v[128:131], v[142:143], off offset:576
	global_load_dwordx2 v[220:221], v[144:145], off
	global_load_dwordx4 v[240:243], v[136:137], off
	v_add_u32_e32 v136, v232, v229
	v_mov_b32_e32 v137, v159
	v_lshl_add_u64 v[136:137], v[136:137], 2, s[88:89]
	global_load_dwordx4 v[244:247], v[136:137], off
	global_load_dwordx2 v[218:219], v[146:147], off
	v_add_u32_e32 v136, v195, v230
	v_mov_b32_e32 v137, v159
	v_lshl_add_u64 v[136:137], v[136:137], 2, s[88:89]
	global_load_dwordx4 v[248:251], v[136:137], off
	v_add_u32_e32 v136, v195, v229
	v_mov_b32_e32 v137, v159
	v_lshl_add_u64 v[136:137], v[136:137], 2, s[88:89]
	global_load_dwordx4 v[152:155], v[136:137], off
	global_load_dwordx2 v[216:217], v[200:201], off
	v_add_u32_e32 v136, v236, v230
	v_mov_b32_e32 v137, v159
	v_lshl_add_u64 v[136:137], v[136:137], 2, s[88:89]
	global_load_dwordx4 v[148:151], v[136:137], off
	v_add_u32_e32 v136, v236, v229
	v_mov_b32_e32 v137, v159
	v_lshl_add_u64 v[136:137], v[136:137], 2, s[88:89]
	global_load_dwordx4 v[144:147], v[136:137], off
	global_load_dwordx2 v[200:201], v[202:203], off
	v_add_u32_e32 v136, v235, v230
	v_mov_b32_e32 v137, v159
	v_lshl_add_u64 v[136:137], v[136:137], 2, s[88:89]
	global_load_dwordx4 v[140:143], v[136:137], off
	v_add_u32_e32 v136, v235, v229
	v_mov_b32_e32 v137, v159
	v_lshl_add_u64 v[136:137], v[136:137], 2, s[88:89]
	global_load_dwordx4 v[136:139], v[136:137], off
	v_add_u32_e32 v202, 0x80, v194
	v_mov_b32_e32 v203, v159
	v_lshl_add_u64 v[202:203], v[202:203], 2, s[90:91]
	s_waitcnt vmcnt(0)
	v_sub_f32_e32 v241, v241, v220
	v_sub_f32_e32 v240, v240, v220
	v_sub_f32_e32 v243, v243, v220
	v_sub_f32_e32 v242, v242, v220
	v_pk_mul_f32 v[242:243], v[220:221], v[242:243] op_sel:[1,0]
	v_pk_mul_f32 v[240:241], v[220:221], v[240:241] op_sel:[1,0]
	v_pk_fma_f32 v[242:243], v[212:213], v[242:243], v[62:63]
	v_pk_fma_f32 v[240:241], v[214:215], v[240:241], v[60:61]
	v_pk_fma_f32 v[242:243], v[134:135], s[78:79], v[242:243] op_sel_hi:[1,0,1]
	v_pk_fma_f32 v[240:241], v[132:133], s[78:79], v[240:241] op_sel_hi:[1,0,1]
	global_store_dwordx4 v[202:203], v[240:243], off
	v_sub_f32_e32 v203, v245, v220
	v_sub_f32_e32 v202, v244, v220
	v_sub_f32_e32 v241, v247, v220
	v_sub_f32_e32 v240, v246, v220
	v_pk_mul_f32 v[202:203], v[220:221], v[202:203] op_sel:[1,0]
	v_pk_mul_f32 v[240:241], v[220:221], v[240:241] op_sel:[1,0]
	v_pk_fma_f32 v[202:203], v[208:209], v[202:203], v[56:57]
	v_pk_fma_f32 v[220:221], v[206:207], v[240:241], v[58:59]
	v_pk_fma_f32 v[240:241], v[128:129], s[78:79], v[202:203] op_sel_hi:[1,0,1]
	v_add_u32_e32 v202, 0x90, v194
	v_mov_b32_e32 v203, v159
	v_pk_fma_f32 v[242:243], v[130:131], s[78:79], v[220:221] op_sel_hi:[1,0,1]
	v_lshl_add_u64 v[202:203], v[202:203], 2, s[90:91]
	global_store_dwordx4 v[202:203], v[240:243], off
	v_sub_f32_e32 v203, v249, v218
	v_sub_f32_e32 v202, v248, v218
	v_sub_f32_e32 v221, v251, v218
	v_sub_f32_e32 v220, v250, v218
	v_pk_mul_f32 v[202:203], v[218:219], v[202:203] op_sel:[1,0]
	v_pk_mul_f32 v[220:221], v[218:219], v[220:221] op_sel:[1,0]
	v_pk_fma_f32 v[202:203], v[214:215], v[202:203], v[52:53]
	v_pk_fma_f32 v[220:221], v[212:213], v[220:221], v[54:55]
	v_pk_fma_f32 v[240:241], v[132:133], s[78:79], v[202:203] op_sel_hi:[1,0,1]
	v_add_u32_e32 v202, 0x8080, v194
	v_mov_b32_e32 v203, v159
	v_sub_f32_e32 v153, v153, v218
	v_sub_f32_e32 v152, v152, v218
	v_sub_f32_e32 v155, v155, v218
	v_sub_f32_e32 v154, v154, v218
	v_pk_fma_f32 v[242:243], v[134:135], s[78:79], v[220:221] op_sel_hi:[1,0,1]
	v_lshl_add_u64 v[202:203], v[202:203], 2, s[90:91]
	v_pk_mul_f32 v[154:155], v[218:219], v[154:155] op_sel:[1,0]
	v_pk_mul_f32 v[152:153], v[218:219], v[152:153] op_sel:[1,0]
	global_store_dwordx4 v[202:203], v[240:243], off
	v_pk_fma_f32 v[152:153], v[208:209], v[152:153], v[48:49]
	v_pk_fma_f32 v[154:155], v[206:207], v[154:155], v[50:51]
	v_add_u32_e32 v202, 0x8090, v194
	v_mov_b32_e32 v203, v159
	v_sub_f32_e32 v149, v149, v216
	v_sub_f32_e32 v148, v148, v216
	v_sub_f32_e32 v151, v151, v216
	v_sub_f32_e32 v150, v150, v216
	v_pk_fma_f32 v[154:155], v[130:131], s[78:79], v[154:155] op_sel_hi:[1,0,1]
	v_pk_fma_f32 v[152:153], v[128:129], s[78:79], v[152:153] op_sel_hi:[1,0,1]
	v_lshl_add_u64 v[202:203], v[202:203], 2, s[90:91]
	v_pk_mul_f32 v[150:151], v[216:217], v[150:151] op_sel:[1,0]
	v_pk_mul_f32 v[148:149], v[216:217], v[148:149] op_sel:[1,0]
	global_store_dwordx4 v[202:203], v[152:155], off
	v_pk_fma_f32 v[148:149], v[214:215], v[148:149], v[44:45]
	v_pk_fma_f32 v[150:151], v[212:213], v[150:151], v[46:47]
	v_add_u32_e32 v152, 0x10080, v194
	v_mov_b32_e32 v153, v159
	v_sub_f32_e32 v145, v145, v216
	v_sub_f32_e32 v144, v144, v216
	v_sub_f32_e32 v147, v147, v216
	v_sub_f32_e32 v146, v146, v216
	v_pk_fma_f32 v[150:151], v[134:135], s[78:79], v[150:151] op_sel_hi:[1,0,1]
	v_pk_fma_f32 v[148:149], v[132:133], s[78:79], v[148:149] op_sel_hi:[1,0,1]
	v_lshl_add_u64 v[152:153], v[152:153], 2, s[90:91]
	v_pk_mul_f32 v[146:147], v[216:217], v[146:147] op_sel:[1,0]
	v_pk_mul_f32 v[144:145], v[216:217], v[144:145] op_sel:[1,0]
	global_store_dwordx4 v[152:153], v[148:151], off
	v_pk_fma_f32 v[144:145], v[208:209], v[144:145], v[40:41]
	v_pk_fma_f32 v[146:147], v[206:207], v[146:147], v[42:43]
;     template <bool LN, int BJ, int LO, int HI> DI void batch(const f32x4 (&acc)[2][2][4][2], unsigned row0, unsigned col0, const f32x4 (&gv)[2], const f32x4 (&bv)[2]) const {
;         f32x4 r[HI - LO]; float mean[(HI - LO) / 2], rstd[(HI - LO) / 2];
; #pragma unroll
;         for (int i = LO; i < HI; ++i) { const int ai = i >> 3, m = (i >> 1) & 3, n = i & 1; const unsigned row = row0 + ai * HALF + m * 16;
;             if (n == 0) { mean[(i - LO) >> 1] = 0.f; rstd[(i - LO) >> 1] = 1.f;
;                 if (LN) { const float2 st = *(const float2*)(stats + row * 2u); mean[(i - LO) >> 1] = st.x; rstd[(i - LO) >> 1] = st.y; } }
;             r[i - LO] = *(const f32x4*)(src + (row * (unsigned)DM + col0 + BJ * HALF + n * 16)); }
; #pragma unroll
;         for (int i = LO; i < HI; ++i) { const int ai = i >> 3, m = (i >> 1) & 3, n = i & 1; const unsigned row = row0 + ai * HALF + m * 16;
;             *(f32x4*)(Y + (row * (unsigned)DM + col0 + BJ * HALF + n * 16)) = acc[ai][BJ][m][n] + ((r[i - LO] - mean[(i - LO) >> 1]) * rstd[(i - LO) >> 1]) * gv[n] + bv[n]; }
	v_add_u32_e32 v148, 0x10090, v194
	v_mov_b32_e32 v149, v159
	v_sub_f32_e32 v141, v141, v200
	v_sub_f32_e32 v140, v140, v200
	v_sub_f32_e32 v143, v143, v200
	v_sub_f32_e32 v142, v142, v200
	v_pk_fma_f32 v[146:147], v[130:131], s[78:79], v[146:147] op_sel_hi:[1,0,1]
	v_pk_fma_f32 v[144:145], v[128:129], s[78:79], v[144:145] op_sel_hi:[1,0,1]
	v_lshl_add_u64 v[148:149], v[148:149], 2, s[90:91]
	v_pk_mul_f32 v[142:143], v[200:201], v[142:143] op_sel:[1,0]
	v_pk_mul_f32 v[140:141], v[200:201], v[140:141] op_sel:[1,0]
	global_store_dwordx4 v[148:149], v[144:147], off
	v_pk_fma_f32 v[140:141], v[214:215], v[140:141], v[36:37]
	v_pk_fma_f32 v[142:143], v[212:213], v[142:143], v[38:39]
	v_add_u32_e32 v144, 0x18080, v194
	v_mov_b32_e32 v145, v159
	v_sub_f32_e32 v137, v137, v200
	v_sub_f32_e32 v136, v136, v200
	v_sub_f32_e32 v139, v139, v200
	v_sub_f32_e32 v138, v138, v200
	v_pk_fma_f32 v[142:143], v[134:135], s[78:79], v[142:143] op_sel_hi:[1,0,1]
	v_pk_fma_f32 v[140:141], v[132:133], s[78:79], v[140:141] op_sel_hi:[1,0,1]
	v_lshl_add_u64 v[144:145], v[144:145], 2, s[90:91]
	v_pk_mul_f32 v[138:139], v[200:201], v[138:139] op_sel:[1,0]
	v_pk_mul_f32 v[136:137], v[200:201], v[136:137] op_sel:[1,0]
	global_store_dwordx4 v[144:145], v[140:143], off
	v_pk_fma_f32 v[136:137], v[208:209], v[136:137], v[32:33]
	v_pk_fma_f32 v[138:139], v[206:207], v[138:139], v[34:35]
	v_add_u32_e32 v140, 0x18090, v194
	v_mov_b32_e32 v141, v159
	v_pk_fma_f32 v[138:139], v[130:131], s[78:79], v[138:139] op_sel_hi:[1,0,1]
	v_pk_fma_f32 v[136:137], v[128:129], s[78:79], v[136:137] op_sel_hi:[1,0,1]
	v_lshl_add_u64 v[140:141], v[140:141], 2, s[90:91]
	global_store_dwordx4 v[140:141], v[136:139], off
	s_nop 1
	v_add_u32_e32 v136, v233, v230
	v_mov_b32_e32 v137, v159
	v_lshl_add_u64 v[136:137], v[136:137], 2, s[88:89]
	global_load_dwordx2 v[220:221], v[196:197], off
	global_load_dwordx4 v[216:219], v[136:137], off
	v_add_u32_e32 v136, v233, v229
	v_mov_b32_e32 v137, v159
	v_lshl_add_u64 v[136:137], v[136:137], 2, s[88:89]
	global_load_dwordx4 v[240:243], v[136:137], off
	global_load_dwordx2 v[200:201], v[198:199], off
	v_add_u32_e32 v136, v234, v230
	v_mov_b32_e32 v137, v159
	v_lshl_add_u64 v[136:137], v[136:137], 2, s[88:89]
	global_load_dwordx4 v[244:247], v[136:137], off
	v_add_u32_e32 v136, v234, v229
	v_mov_b32_e32 v137, v159
	v_lshl_add_u64 v[136:137], v[136:137], 2, s[88:89]
	global_load_dwordx4 v[152:155], v[136:137], off
	global_load_dwordx2 v[198:199], v[204:205], off
	v_add_u32_e32 v136, v237, v230
	v_mov_b32_e32 v137, v159
	v_lshl_add_u64 v[136:137], v[136:137], 2, s[88:89]
	global_load_dwordx4 v[148:151], v[136:137], off
	v_add_u32_e32 v136, v237, v229
	v_mov_b32_e32 v137, v159
	v_lshl_add_u64 v[136:137], v[136:137], 2, s[88:89]
	global_load_dwordx4 v[144:147], v[136:137], off
	global_load_dwordx2 v[196:197], v[210:211], off
	v_add_u32_e32 v136, v238, v230
	v_mov_b32_e32 v137, v159
	v_lshl_add_u64 v[136:137], v[136:137], 2, s[88:89]
	global_load_dwordx4 v[140:143], v[136:137], off
	v_add_u32_e32 v136, v238, v229
	v_mov_b32_e32 v137, v159
	v_lshl_add_u64 v[136:137], v[136:137], 2, s[88:89]
	global_load_dwordx4 v[136:139], v[136:137], off
	v_add_u32_e32 v210, 0x40080, v194
	v_mov_b32_e32 v211, v159
	v_lshl_add_u64 v[210:211], v[210:211], 2, s[90:91]
	s_waitcnt vmcnt(0)
;     template <bool LN, int BJ, int LO, int HI> DI void batch(const f32x4 (&acc)[2][2][4][2], unsigned row0, unsigned col0, const f32x4 (&gv)[2], const f32x4 (&bv)[2]) const {
;         f32x4 r[HI - LO]; float mean[(HI - LO) / 2], rstd[(HI - LO) / 2];
; #pragma unroll
;         for (int i = LO; i < HI; ++i) { const int ai = i >> 3, m = (i >> 1) & 3, n = i & 1; const unsigned row = row0 + ai * HALF + m * 16;
;             if (n == 0) { mean[(i - LO) >> 1] = 0.f; rstd[(i - LO) >> 1] = 1.f;
;                 if (LN) { const float2 st = *(const float2*)(stats + row * 2u); mean[(i - LO) >> 1] = st.x; rstd[(i - LO) >> 1] = st.y; } }
;             r[i - LO] = *(const f32x4*)(src + (row * (unsigned)DM + col0 + BJ * HALF + n * 16)); }
; #pragma unroll
;         for (int i = LO; i < HI; ++i) { const int ai = i >> 3, m = (i >> 1) & 3, n = i & 1; const unsigned row = row0 + ai * HALF + m * 16;
;             *(f32x4*)(Y + (row * (unsigned)DM + col0 + BJ * HALF + n * 16)) = acc[ai][BJ][m][n] + ((r[i - LO] - mean[(i - LO) >> 1]) * rstd[(i - LO) >> 1]) * gv[n] + bv[n]; }
	v_sub_f32_e32 v203, v217, v220
	v_sub_f32_e32 v202, v216, v220
	v_sub_f32_e32 v205, v219, v220
	v_sub_f32_e32 v204, v218, v220
	v_pk_mul_f32 v[204:205], v[220:221], v[204:205] op_sel:[1,0]
	v_pk_mul_f32 v[202:203], v[220:221], v[202:203] op_sel:[1,0]
	v_pk_fma_f32 v[204:205], v[212:213], v[204:205], v[30:31]
	v_pk_fma_f32 v[202:203], v[214:215], v[202:203], v[28:29]
	v_pk_fma_f32 v[204:205], v[134:135], s[78:79], v[204:205] op_sel_hi:[1,0,1]
	v_pk_fma_f32 v[202:203], v[132:133], s[78:79], v[202:203] op_sel_hi:[1,0,1]
	global_store_dwordx4 v[210:211], v[202:205], off
	v_add_u32_e32 v210, 0x40090, v194
	v_mov_b32_e32 v211, v159
	v_sub_f32_e32 v203, v241, v220
	v_sub_f32_e32 v202, v240, v220
	v_sub_f32_e32 v205, v243, v220
	v_sub_f32_e32 v204, v242, v220
	v_pk_mul_f32 v[204:205], v[220:221], v[204:205] op_sel:[1,0]
	v_pk_mul_f32 v[202:203], v[220:221], v[202:203] op_sel:[1,0]
	v_pk_fma_f32 v[204:205], v[206:207], v[204:205], v[26:27]
	v_pk_fma_f32 v[202:203], v[208:209], v[202:203], v[24:25]
	v_pk_fma_f32 v[204:205], v[130:131], s[78:79], v[204:205] op_sel_hi:[1,0,1]
	v_pk_fma_f32 v[202:203], v[128:129], s[78:79], v[202:203] op_sel_hi:[1,0,1]
	v_lshl_add_u64 v[210:211], v[210:211], 2, s[90:91]
	global_store_dwordx4 v[210:211], v[202:205], off
	v_sub_f32_e32 v149, v149, v198
	v_sub_f32_e32 v148, v148, v198
	v_sub_f32_e32 v203, v245, v200
	v_sub_f32_e32 v202, v244, v200
	v_sub_f32_e32 v141, v141, v196
	v_sub_f32_e32 v140, v140, v196
	v_sub_f32_e32 v205, v247, v200
	v_sub_f32_e32 v204, v246, v200
	v_pk_mul_f32 v[202:203], v[200:201], v[202:203] op_sel:[1,0]
	v_sub_f32_e32 v151, v151, v198
	v_sub_f32_e32 v150, v150, v198
	v_pk_mul_f32 v[148:149], v[198:199], v[148:149] op_sel:[1,0]
	v_sub_f32_e32 v143, v143, v196
	v_sub_f32_e32 v142, v142, v196
	v_pk_mul_f32 v[140:141], v[196:197], v[140:141] op_sel:[1,0]
	v_pk_mul_f32 v[204:205], v[200:201], v[204:205] op_sel:[1,0]
	v_pk_fma_f32 v[202:203], v[214:215], v[202:203], v[20:21]
	v_sub_f32_e32 v153, v153, v200
	v_sub_f32_e32 v152, v152, v200
	v_sub_f32_e32 v155, v155, v200
	v_sub_f32_e32 v154, v154, v200
	v_pk_mul_f32 v[150:151], v[198:199], v[150:151] op_sel:[1,0]
	v_pk_fma_f32 v[148:149], v[214:215], v[148:149], v[12:13]
	v_pk_mul_f32 v[142:143], v[196:197], v[142:143] op_sel:[1,0]
	v_pk_fma_f32 v[140:141], v[214:215], v[140:141], v[4:5]
	v_pk_fma_f32 v[204:205], v[212:213], v[204:205], v[22:23]
	v_pk_fma_f32 v[202:203], v[132:133], s[78:79], v[202:203] op_sel_hi:[1,0,1]
	v_pk_mul_f32 v[154:155], v[200:201], v[154:155] op_sel:[1,0]
	v_pk_mul_f32 v[152:153], v[200:201], v[152:153] op_sel:[1,0]
	v_pk_fma_f32 v[150:151], v[212:213], v[150:151], v[14:15]
	v_pk_fma_f32 v[148:149], v[132:133], s[78:79], v[148:149] op_sel_hi:[1,0,1]
	v_pk_fma_f32 v[142:143], v[212:213], v[142:143], v[6:7]
	v_pk_fma_f32 v[132:133], v[132:133], s[78:79], v[140:141] op_sel_hi:[1,0,1]
	v_add_u32_e32 v140, 0x58080, v194
	v_mov_b32_e32 v141, v159
	v_pk_fma_f32 v[204:205], v[134:135], s[78:79], v[204:205] op_sel_hi:[1,0,1]
	v_pk_fma_f32 v[152:153], v[208:209], v[152:153], v[16:17]
	v_pk_fma_f32 v[154:155], v[206:207], v[154:155], v[18:19]
	v_add_u32_e32 v200, 0x48090, v194
	v_mov_b32_e32 v201, v159
	v_pk_fma_f32 v[150:151], v[134:135], s[78:79], v[150:151] op_sel_hi:[1,0,1]
	v_pk_fma_f32 v[134:135], v[134:135], s[78:79], v[142:143] op_sel_hi:[1,0,1]
	v_lshl_add_u64 v[140:141], v[140:141], 2, s[90:91]
	v_pk_fma_f32 v[154:155], v[130:131], s[78:79], v[154:155] op_sel_hi:[1,0,1]
	v_pk_fma_f32 v[152:153], v[128:129], s[78:79], v[152:153] op_sel_hi:[1,0,1]
	v_lshl_add_u64 v[200:201], v[200:201], 2, s[90:91]
	v_sub_f32_e32 v145, v145, v198
	v_sub_f32_e32 v144, v144, v198
	global_store_dwordx4 v[140:141], v[132:135], off
	global_store_dwordx4 v[200:201], v[152:155], off
	v_sub_f32_e32 v147, v147, v198
	v_sub_f32_e32 v133, v137, v196
	v_sub_f32_e32 v132, v136, v196
	v_add_u32_e32 v152, 0x50080, v194
	v_mov_b32_e32 v153, v159
	v_sub_f32_e32 v146, v146, v198
	v_pk_mul_f32 v[144:145], v[198:199], v[144:145] op_sel:[1,0]
	v_sub_f32_e32 v135, v139, v196
	v_sub_f32_e32 v134, v138, v196
	v_pk_mul_f32 v[132:133], v[196:197], v[132:133] op_sel:[1,0]
	v_lshl_add_u64 v[152:153], v[152:153], 2, s[90:91]
	v_pk_mul_f32 v[146:147], v[198:199], v[146:147] op_sel:[1,0]
	v_pk_fma_f32 v[144:145], v[208:209], v[144:145], v[8:9]
	v_pk_mul_f32 v[134:135], v[196:197], v[134:135] op_sel:[1,0]
	v_pk_fma_f32 v[132:133], v[208:209], v[132:133], v[0:1]
	v_add_u32_e32 v210, 0x48080, v194
	v_mov_b32_e32 v211, v159
	global_store_dwordx4 v[152:153], v[148:151], off
	v_pk_fma_f32 v[146:147], v[206:207], v[146:147], v[10:11]
	v_pk_fma_f32 v[144:145], v[128:129], s[78:79], v[144:145] op_sel_hi:[1,0,1]
	v_add_u32_e32 v148, 0x50090, v194
	v_mov_b32_e32 v149, v159
	v_pk_fma_f32 v[134:135], v[206:207], v[134:135], v[2:3]
	v_pk_fma_f32 v[128:129], v[128:129], s[78:79], v[132:133] op_sel_hi:[1,0,1]
	v_add_u32_e32 v132, 0x58090, v194
	v_mov_b32_e32 v133, v159
	v_lshl_add_u64 v[210:211], v[210:211], 2, s[90:91]
	v_pk_fma_f32 v[146:147], v[130:131], s[78:79], v[146:147] op_sel_hi:[1,0,1]
	v_lshl_add_u64 v[148:149], v[148:149], 2, s[90:91]
	v_pk_fma_f32 v[130:131], v[130:131], s[78:79], v[134:135] op_sel_hi:[1,0,1]
	v_lshl_add_u64 v[132:133], v[132:133], 2, s[90:91]
	global_store_dwordx4 v[210:211], v[202:205], off
	global_store_dwordx4 v[148:149], v[144:147], off
	global_store_dwordx4 v[132:133], v[128:131], off
	s_mov_b64 s[24:25], 0
	s_branch .LBB0_324
